# EpiRes: nw table loads (and nscale where address is ready) hoisted before the first wait
# speedup vs baseline: 1.0217x; 1.0022x over previous
.LBB0_59:
	s_or_b64 exec, exec, s[24:25]
	v_lshl_add_u64 v[44:45], v[18:19], 0, v[128:129]
	global_load_dwordx4 v[92:95], v[44:45], off nt
	global_load_dwordx4 v[96:99], v[44:45], off offset:1024 nt
	global_load_dwordx4 v[100:103], v[44:45], off offset:2048 nt
	global_load_dwordx4 v[104:107], v[44:45], off offset:3072 nt
	global_load_dwordx4 v[108:111], v[2:3], off
	global_load_dwordx4 v[112:115], v[2:3], off offset:1024
	global_load_dwordx4 v[116:119], v[2:3], off offset:2048
	global_load_dwordx4 v[120:123], v[2:3], off offset:3072
	v_lshrrev_b32_e32 v9, 10, v16
	s_movk_i32 s16, 0x1800
	v_lshlrev_b64 v[16:17], 12, v[14:15]
	v_mad_u32_u24 v9, v9, s16, s16
	v_lshl_add_u64 v[46:47], v[4:5], 0, v[16:17]
	v_cndmask_b32_e64 v16, v9, 0, s[36:37]
	v_ashrrev_i32_e32 v17, 31, v16
	s_mov_b64 s[24:25], 0x5801000
	v_lshl_add_u64 v[16:17], v[16:17], 2, s[86:87]
	v_lshl_add_u64 v[48:49], v[16:17], 0, s[24:25]
	v_lshl_add_u64 v[32:33], v[48:49], 0, v[128:129]
	v_lshlrev_b64 v[36:37], 11, v[14:15]
	v_lshl_add_u64 v[50:51], v[6:7], 0, v[36:37]
	global_load_dwordx4 v[132:135], v[32:33], off
	global_load_dwordx4 v[136:139], v[32:33], off offset:1024
	global_load_dwordx4 v[140:143], v[32:33], off offset:2048
	global_load_dwordx4 v[144:147], v[32:33], off offset:3072
	s_waitcnt vmcnt(0)
	global_store_dwordx4 v[46:47], v[92:95], off
	v_pk_mul_f32 v[18:19], v[94:95], v[110:111]
	v_pk_mul_f32 v[16:17], v[92:93], v[108:109]
	v_pk_add_f32 v[34:35], v[134:135], 1.0 op_sel_hi:[1,0]
	v_pk_add_f32 v[32:33], v[132:133], 1.0 op_sel_hi:[1,0]
	v_pk_mul_f32 v[18:19], v[18:19], v[34:35]
	v_pk_mul_f32 v[16:17], v[16:17], v[32:33]
	v_and_b32_sdwa v13, v19, v170 dst_sel:DWORD dst_unused:UNUSED_PAD src0_sel:WORD_1 src1_sel:DWORD
	s_waitcnt lgkmcnt(0)
	v_and_b32_sdwa v11, v16, v170 dst_sel:DWORD dst_unused:UNUSED_PAD src0_sel:WORD_1 src1_sel:DWORD
	v_and_b32_sdwa v27, v17, v170 dst_sel:DWORD dst_unused:UNUSED_PAD src0_sel:WORD_1 src1_sel:DWORD
	v_and_b32_sdwa v9, v18, v170 dst_sel:DWORD dst_unused:UNUSED_PAD src0_sel:WORD_1 src1_sel:DWORD
	v_add3_u32 v11, v16, v11, s56
	v_add3_u32 v13, v19, v13, s56
	v_add3_u32 v16, v17, v27, s56
	v_add3_u32 v9, v18, v9, s56
	v_and_b32_e32 v13, 0xffff0000, v13
	v_and_b32_e32 v16, 0xffff0000, v16
	v_or_b32_sdwa v17, v13, v9 dst_sel:DWORD dst_unused:UNUSED_PAD src0_sel:DWORD src1_sel:WORD_1
	v_or_b32_sdwa v16, v16, v11 dst_sel:DWORD dst_unused:UNUSED_PAD src0_sel:DWORD src1_sel:WORD_1
	global_store_dwordx2 v[50:51], v[16:17], off
	v_mov_b32_e32 v9, v129
	v_lshl_add_u64 v[36:37], v[48:49], 0, v[8:9]
	global_store_dwordx4 v[46:47], v[96:99], off offset:1024
	v_pk_mul_f32 v[34:35], v[98:99], v[114:115]
	v_pk_mul_f32 v[32:33], v[96:97], v[112:113]
	v_pk_add_f32 v[38:39], v[138:139], 1.0 op_sel_hi:[1,0]
	v_pk_add_f32 v[36:37], v[136:137], 1.0 op_sel_hi:[1,0]
	v_pk_mul_f32 v[34:35], v[34:35], v[38:39]
	v_pk_mul_f32 v[32:33], v[32:33], v[36:37]
	v_and_b32_sdwa v13, v35, v170 dst_sel:DWORD dst_unused:UNUSED_PAD src0_sel:WORD_1 src1_sel:DWORD
	v_and_b32_sdwa v27, v33, v170 dst_sel:DWORD dst_unused:UNUSED_PAD src0_sel:WORD_1 src1_sel:DWORD
	v_and_b32_sdwa v9, v34, v170 dst_sel:DWORD dst_unused:UNUSED_PAD src0_sel:WORD_1 src1_sel:DWORD
	v_and_b32_sdwa v11, v32, v170 dst_sel:DWORD dst_unused:UNUSED_PAD src0_sel:WORD_1 src1_sel:DWORD
	v_add3_u32 v13, v35, v13, s56
	v_add3_u32 v27, v33, v27, s56
	v_add3_u32 v11, v32, v11, s56
	v_add3_u32 v9, v34, v9, s56
	v_and_b32_e32 v13, 0xffff0000, v13
	v_and_b32_e32 v27, 0xffff0000, v27
	v_or_b32_sdwa v33, v13, v9 dst_sel:DWORD dst_unused:UNUSED_PAD src0_sel:DWORD src1_sel:WORD_1
	v_or_b32_sdwa v32, v27, v11 dst_sel:DWORD dst_unused:UNUSED_PAD src0_sel:DWORD src1_sel:WORD_1
	global_store_dwordx2 v[50:51], v[32:33], off offset:512
	v_mov_b32_e32 v11, v129
	v_lshl_add_u64 v[40:41], v[48:49], 0, v[10:11]
	global_store_dwordx4 v[46:47], v[100:103], off offset:2048
	v_pk_mul_f32 v[38:39], v[102:103], v[118:119]
	v_pk_mul_f32 v[36:37], v[100:101], v[116:117]
	v_pk_add_f32 v[42:43], v[142:143], 1.0 op_sel_hi:[1,0]
	v_pk_add_f32 v[40:41], v[140:141], 1.0 op_sel_hi:[1,0]
	v_pk_mul_f32 v[38:39], v[38:39], v[42:43]
	v_pk_mul_f32 v[36:37], v[36:37], v[40:41]
	v_and_b32_sdwa v13, v39, v170 dst_sel:DWORD dst_unused:UNUSED_PAD src0_sel:WORD_1 src1_sel:DWORD
	v_and_b32_sdwa v27, v37, v170 dst_sel:DWORD dst_unused:UNUSED_PAD src0_sel:WORD_1 src1_sel:DWORD
	v_and_b32_sdwa v9, v38, v170 dst_sel:DWORD dst_unused:UNUSED_PAD src0_sel:WORD_1 src1_sel:DWORD
	v_and_b32_sdwa v11, v36, v170 dst_sel:DWORD dst_unused:UNUSED_PAD src0_sel:WORD_1 src1_sel:DWORD
	v_add3_u32 v13, v39, v13, s56
	v_add3_u32 v27, v37, v27, s56
	v_add3_u32 v11, v36, v11, s56
	v_add3_u32 v9, v38, v9, s56
	v_and_b32_e32 v13, 0xffff0000, v13
	v_and_b32_e32 v27, 0xffff0000, v27
	v_or_b32_sdwa v37, v13, v9 dst_sel:DWORD dst_unused:UNUSED_PAD src0_sel:DWORD src1_sel:WORD_1
	v_or_b32_sdwa v36, v27, v11 dst_sel:DWORD dst_unused:UNUSED_PAD src0_sel:DWORD src1_sel:WORD_1
	global_store_dwordx2 v[50:51], v[36:37], off offset:1024
	v_mov_b32_e32 v13, v129
	v_lshl_add_u64 v[44:45], v[48:49], 0, v[12:13]
	v_mul_f32_e32 v9, v93, v93
	v_mul_f32_e32 v11, v97, v97
	v_fmac_f32_e32 v9, v92, v92
	v_fmac_f32_e32 v11, v96, v96
	v_fmac_f32_e32 v9, v94, v94
	v_fmac_f32_e32 v11, v98, v98
	v_fmac_f32_e32 v9, v95, v95
	v_fmac_f32_e32 v11, v99, v99
	v_add_f32_e32 v9, v9, v11
	v_mul_f32_e32 v11, v101, v101
	v_fmac_f32_e32 v11, v100, v100
	v_fmac_f32_e32 v11, v102, v102
	v_fmac_f32_e32 v11, v103, v103
	v_add_f32_e32 v9, v9, v11
	global_store_dwordx4 v[46:47], v[104:107], off offset:3072
	v_mul_f32_e32 v11, v105, v105
	v_fmac_f32_e32 v11, v104, v104
	v_fmac_f32_e32 v11, v106, v106
	v_fmac_f32_e32 v11, v107, v107
	v_add_f32_e32 v9, v9, v11
	ds_bpermute_b32 v11, v20, v9
	s_waitcnt lgkmcnt(0)
	v_add_f32_e32 v9, v9, v11
	ds_bpermute_b32 v11, v21, v9
	s_waitcnt lgkmcnt(0)
	v_add_f32_e32 v9, v9, v11
	ds_bpermute_b32 v11, v22, v9
	s_waitcnt lgkmcnt(0)
	v_add_f32_e32 v9, v9, v11
	ds_bpermute_b32 v11, v23, v9
	s_waitcnt lgkmcnt(0)
	v_add_f32_e32 v9, v9, v11
	ds_bpermute_b32 v11, v24, v9
	s_waitcnt lgkmcnt(0)
	v_add_f32_e32 v9, v9, v11
	ds_bpermute_b32 v11, v25, v9
	v_pk_mul_f32 v[16:17], v[106:107], v[122:123]
	v_pk_mul_f32 v[18:19], v[104:105], v[120:121]
	v_pk_add_f32 v[28:29], v[146:147], 1.0 op_sel_hi:[1,0]
	v_pk_add_f32 v[30:31], v[144:145], 1.0 op_sel_hi:[1,0]
	v_pk_mul_f32 v[16:17], v[16:17], v[28:29]
	v_pk_mul_f32 v[18:19], v[18:19], v[30:31]
	v_and_b32_sdwa v13, v16, v170 dst_sel:DWORD dst_unused:UNUSED_PAD src0_sel:WORD_1 src1_sel:DWORD
	v_and_b32_sdwa v28, v17, v170 dst_sel:DWORD dst_unused:UNUSED_PAD src0_sel:WORD_1 src1_sel:DWORD
	v_and_b32_sdwa v29, v19, v170 dst_sel:DWORD dst_unused:UNUSED_PAD src0_sel:WORD_1 src1_sel:DWORD
	v_and_b32_sdwa v27, v18, v170 dst_sel:DWORD dst_unused:UNUSED_PAD src0_sel:WORD_1 src1_sel:DWORD
	v_add3_u32 v13, v16, v13, s56
	v_add3_u32 v16, v17, v28, s56
	v_add3_u32 v17, v19, v29, s56
	v_add3_u32 v18, v18, v27, s56
	v_and_b32_e32 v16, 0xffff0000, v16
	v_and_b32_e32 v19, 0xffff0000, v17
	v_or_b32_sdwa v17, v16, v13 dst_sel:DWORD dst_unused:UNUSED_PAD src0_sel:DWORD src1_sel:WORD_1
	v_or_b32_sdwa v16, v19, v18 dst_sel:DWORD dst_unused:UNUSED_PAD src0_sel:DWORD src1_sel:WORD_1
	global_store_dwordx2 v[50:51], v[16:17], off offset:1536
	s_and_saveexec_b64 s[24:25], vcc
	s_cbranch_execz .LBB0_54
	s_waitcnt lgkmcnt(0)
	v_add_f32_e32 v9, v9, v11
	v_cndmask_b32_e64 v9, 0, v9, s[0:1]
	v_lshl_add_u64 v[14:15], v[14:15], 2, v[0:1]
	global_store_dword v[14:15], v9, off
	s_branch .LBB0_54

.LBB0_92:
	s_add_i32 s0, s1, 2
	v_add_u32_e32 v111, v104, v105
	ds_read_b128 v[136:139], v111 offset:16384
	ds_read_b128 v[140:143], v111 offset:18432
	ds_read_b128 v[144:147], v111 offset:20480
	ds_read_b128 v[148:151], v111 offset:22528
	v_add_u32_e32 v110, v103, v105
	ds_read_b128 v[116:119], v110
	s_add_i32 s1, s1, 4
	ds_read_b128 v[120:123], v110 offset:2048
	s_min_u32 s1, s1, 15
	v_add_u32_e32 v113, v104, v114
	s_lshl_b32 s92, s1, 7
	ds_read_b128 v[124:127], v110 offset:4096
	v_add_u32_e32 v112, v103, v114
	ds_read_b128 v[194:197], v113 offset:16384
	ds_read_b128 v[198:201], v113 offset:18432
	ds_read_b128 v[202:205], v113 offset:20480
	ds_read_b128 v[206:209], v113 offset:22528
	v_lshl_add_u64 v[164:165], v[98:99], 0, s[92:93]
	ds_read_b128 v[132:135], v110 offset:6144
	ds_read_b128 v[152:155], v112
	ds_read_b128 v[156:159], v112 offset:2048
	ds_read_b128 v[160:163], v112 offset:4096
	ds_read_b128 v[190:193], v112 offset:6144
	s_waitcnt lgkmcnt(11)
	v_mfma_f32_16x16x32_bf16 v[92:95], v[136:139], v[116:119], v[92:95]
	v_mfma_f32_16x16x32_bf16 v[88:91], v[140:143], v[116:119], v[88:91]
	v_mfma_f32_16x16x32_bf16 v[52:55], v[144:147], v[116:119], v[52:55]
	v_mfma_f32_16x16x32_bf16 v[48:51], v[148:151], v[116:119], v[48:51]
	global_load_dwordx4 v[116:119], v[164:165], off
	s_waitcnt vmcnt(6)
	ds_write_b128 v109, v[56:59] offset:32768
	v_add_co_u32_e32 v56, vcc, s11, v164
	s_waitcnt lgkmcnt(11)
	v_mfma_f32_16x16x32_bf16 v[44:47], v[136:139], v[120:123], v[44:47]
	v_addc_co_u32_e32 v57, vcc, 0, v165, vcc
	v_mfma_f32_16x16x32_bf16 v[40:43], v[140:143], v[120:123], v[40:43]
	v_mfma_f32_16x16x32_bf16 v[36:39], v[144:147], v[120:123], v[36:39]
	v_mfma_f32_16x16x32_bf16 v[32:35], v[148:151], v[120:123], v[32:35]
	global_load_dwordx4 v[120:123], v[56:57], off
	v_add_co_u32_e32 v56, vcc, s33, v164
	ds_write_b128 v109, v[60:63] offset:36864
	s_nop 0
	v_addc_co_u32_e32 v57, vcc, 0, v165, vcc
	s_waitcnt lgkmcnt(11)
	v_mfma_f32_16x16x32_bf16 v[28:31], v[136:139], v[124:127], v[28:31]
	v_mfma_f32_16x16x32_bf16 v[24:27], v[140:143], v[124:127], v[24:27]
	v_mfma_f32_16x16x32_bf16 v[20:23], v[144:147], v[124:127], v[20:23]
	v_mfma_f32_16x16x32_bf16 v[16:19], v[148:151], v[124:127], v[16:19]
	global_load_dwordx4 v[124:127], v[56:57], off
	v_add_co_u32_e32 v56, vcc, s59, v164
	ds_write_b128 v109, v[64:67] offset:40960
	s_nop 0
	v_addc_co_u32_e32 v57, vcc, 0, v165, vcc
	v_lshl_add_u64 v[64:65], v[100:101], 0, s[92:93]
	v_add_co_u32_e32 v66, vcc, s11, v64
	s_waitcnt lgkmcnt(7)
	v_mfma_f32_16x16x32_bf16 v[12:15], v[136:139], v[132:135], v[12:15]
	v_addc_co_u32_e32 v67, vcc, 0, v65, vcc
	v_mfma_f32_16x16x32_bf16 v[8:11], v[140:143], v[132:135], v[8:11]
	v_mfma_f32_16x16x32_bf16 v[4:7], v[144:147], v[132:135], v[4:7]
	v_mfma_f32_16x16x32_bf16 v[0:3], v[148:151], v[132:135], v[0:3]
	global_load_dwordx4 v[132:135], v[56:57], off
	s_waitcnt vmcnt(7)
	ds_write_b128 v109, v[72:75] offset:45056
	s_waitcnt lgkmcnt(7)
	v_mfma_f32_16x16x32_bf16 v[56:59], v[194:197], v[152:155], v[92:95]
	v_mfma_f32_16x16x32_bf16 v[60:63], v[198:201], v[152:155], v[88:91]
	v_mfma_f32_16x16x32_bf16 v[52:55], v[202:205], v[152:155], v[52:55]
	v_mfma_f32_16x16x32_bf16 v[48:51], v[206:209], v[152:155], v[48:51]
	global_load_dwordx4 v[136:139], v[64:65], off
	ds_write_b128 v109, v[68:71] offset:49152
	s_waitcnt lgkmcnt(7)
	v_mfma_f32_16x16x32_bf16 v[44:47], v[194:197], v[156:159], v[44:47]
	v_mfma_f32_16x16x32_bf16 v[40:43], v[198:201], v[156:159], v[40:43]
	v_mfma_f32_16x16x32_bf16 v[36:39], v[202:205], v[156:159], v[36:39]
	v_mfma_f32_16x16x32_bf16 v[32:35], v[206:209], v[156:159], v[32:35]
	global_load_dwordx4 v[140:143], v[66:67], off
	v_add_co_u32_e32 v66, vcc, s33, v64
	s_waitcnt vmcnt(8)
	ds_write_b128 v109, v[76:79] offset:53248
	v_addc_co_u32_e32 v67, vcc, 0, v65, vcc
	v_add_co_u32_e32 v64, vcc, s59, v64
	s_waitcnt lgkmcnt(7)
	v_mfma_f32_16x16x32_bf16 v[28:31], v[194:197], v[160:163], v[28:31]
	v_addc_co_u32_e32 v65, vcc, 0, v65, vcc
	v_mfma_f32_16x16x32_bf16 v[24:27], v[198:201], v[160:163], v[24:27]
	v_mfma_f32_16x16x32_bf16 v[20:23], v[202:205], v[160:163], v[20:23]
	v_mfma_f32_16x16x32_bf16 v[16:19], v[206:209], v[160:163], v[16:19]
	global_load_dwordx4 v[144:147], v[66:67], off
	s_waitcnt vmcnt(8)
	ds_write_b128 v109, v[80:83] offset:57344
	s_waitcnt lgkmcnt(7)
	v_mfma_f32_16x16x32_bf16 v[12:15], v[194:197], v[190:193], v[12:15]
	v_mfma_f32_16x16x32_bf16 v[8:11], v[198:201], v[190:193], v[8:11]
	v_mfma_f32_16x16x32_bf16 v[4:7], v[202:205], v[190:193], v[4:7]
	v_mfma_f32_16x16x32_bf16 v[0:3], v[206:209], v[190:193], v[0:3]
	global_load_dwordx4 v[148:151], v[64:65], off
	s_waitcnt vmcnt(8)
	ds_write_b128 v109, v[84:87] offset:61440
	s_waitcnt lgkmcnt(0)
	s_barrier
	ds_read_b128 v[84:87], v111 offset:51200
	ds_read_b128 v[80:83], v111 offset:49152
	ds_read_b128 v[88:91], v111 offset:53248
	ds_read_b128 v[92:95], v111 offset:55296
	ds_read_b128 v[64:67], v110 offset:32768
	s_min_u32 s1, s0, 12
	s_lshl_b32 s92, s1, 7
	ds_read_b128 v[68:71], v110 offset:34816
	v_lshl_add_u64 v[164:165], v[98:99], 0, s[92:93]
	ds_read_b128 v[72:75], v110 offset:36864
	ds_read_b128 v[76:79], v110 offset:38912
	ds_read_b128 v[152:155], v112 offset:32768
	ds_read_b128 v[156:159], v112 offset:34816
	ds_read_b128 v[160:163], v112 offset:36864
	ds_read_b128 v[190:193], v112 offset:38912
	ds_read_b128 v[194:197], v113 offset:49152
	ds_read_b128 v[198:201], v113 offset:51200
	ds_read_b128 v[202:205], v113 offset:53248
	ds_read_b128 v[206:209], v113 offset:55296
	s_waitcnt lgkmcnt(11)
	v_mfma_f32_16x16x32_bf16 v[214:217], v[84:87], v[64:67], v[60:63]
	v_mfma_f32_16x16x32_bf16 v[210:213], v[80:83], v[64:67], v[56:59]
	s_nop 1
	v_add_co_u32_e32 v60, vcc, s11, v164
	s_nop 1
	v_addc_co_u32_e32 v61, vcc, 0, v165, vcc
	v_mfma_f32_16x16x32_bf16 v[52:55], v[88:91], v[64:67], v[52:55]
	v_mfma_f32_16x16x32_bf16 v[48:51], v[92:95], v[64:67], v[48:51]
	v_add_co_u32_e32 v64, vcc, s33, v164
	global_load_dwordx4 v[56:59], v[164:165], off offset:384
	s_nop 0
	v_addc_co_u32_e32 v65, vcc, 0, v165, vcc
	s_waitcnt vmcnt(8)
	ds_write_b128 v109, v[116:119]
	s_waitcnt lgkmcnt(11)
	v_mfma_f32_16x16x32_bf16 v[44:47], v[80:83], v[68:71], v[44:47]
	v_mfma_f32_16x16x32_bf16 v[40:43], v[84:87], v[68:71], v[40:43]
	v_mfma_f32_16x16x32_bf16 v[36:39], v[88:91], v[68:71], v[36:39]
	v_mfma_f32_16x16x32_bf16 v[32:35], v[92:95], v[68:71], v[32:35]
	v_add_co_u32_e32 v68, vcc, s59, v164
	global_load_dwordx4 v[60:63], v[60:61], off offset:384
	s_waitcnt vmcnt(8)
	ds_write_b128 v109, v[120:123] offset:4096
	s_waitcnt lgkmcnt(11)
	v_mfma_f32_16x16x32_bf16 v[28:31], v[80:83], v[72:75], v[28:31]
	v_addc_co_u32_e32 v69, vcc, 0, v165, vcc
	v_mfma_f32_16x16x32_bf16 v[24:27], v[84:87], v[72:75], v[24:27]
	v_mfma_f32_16x16x32_bf16 v[20:23], v[88:91], v[72:75], v[20:23]
	v_mfma_f32_16x16x32_bf16 v[16:19], v[92:95], v[72:75], v[16:19]
	global_load_dwordx4 v[64:67], v[64:65], off offset:384
	s_waitcnt vmcnt(8)
	ds_write_b128 v109, v[124:127] offset:8192
	s_waitcnt lgkmcnt(11)
	v_mfma_f32_16x16x32_bf16 v[8:11], v[84:87], v[76:79], v[8:11]
	v_lshl_add_u64 v[84:85], v[100:101], 0, s[92:93]
	v_mfma_f32_16x16x32_bf16 v[12:15], v[80:83], v[76:79], v[12:15]
	v_mfma_f32_16x16x32_bf16 v[4:7], v[88:91], v[76:79], v[4:7]
	v_mfma_f32_16x16x32_bf16 v[0:3], v[92:95], v[76:79], v[0:3]
	v_add_co_u32_e32 v76, vcc, s11, v84
	global_load_dwordx4 v[72:75], v[68:69], off offset:384
	s_nop 0
	v_addc_co_u32_e32 v77, vcc, 0, v85, vcc
	v_add_co_u32_e32 v80, vcc, s33, v84
	s_waitcnt vmcnt(8)
	ds_write_b128 v109, v[132:135] offset:12288
	v_addc_co_u32_e32 v81, vcc, 0, v85, vcc
	s_waitcnt lgkmcnt(7)
	v_mfma_f32_16x16x32_bf16 v[92:95], v[194:197], v[152:155], v[210:213]
	s_waitcnt lgkmcnt(6)
	v_mfma_f32_16x16x32_bf16 v[88:91], v[198:201], v[152:155], v[214:217]
	s_waitcnt lgkmcnt(5)
	v_mfma_f32_16x16x32_bf16 v[52:55], v[202:205], v[152:155], v[52:55]
	s_waitcnt lgkmcnt(4)
	v_mfma_f32_16x16x32_bf16 v[48:51], v[206:209], v[152:155], v[48:51]
	global_load_dwordx4 v[68:71], v[84:85], off offset:384
	v_add_co_u32_e32 v84, vcc, s59, v84
	s_waitcnt vmcnt(8)
	ds_write_b128 v109, v[136:139] offset:16384
	v_addc_co_u32_e32 v85, vcc, 0, v85, vcc
	v_mfma_f32_16x16x32_bf16 v[44:47], v[194:197], v[156:159], v[44:47]
	v_mfma_f32_16x16x32_bf16 v[40:43], v[198:201], v[156:159], v[40:43]
	v_mfma_f32_16x16x32_bf16 v[36:39], v[202:205], v[156:159], v[36:39]
	v_mfma_f32_16x16x32_bf16 v[32:35], v[206:209], v[156:159], v[32:35]
	global_load_dwordx4 v[76:79], v[76:77], off offset:384
	s_waitcnt vmcnt(8)
	ds_write_b128 v109, v[140:143] offset:20480
	v_mfma_f32_16x16x32_bf16 v[28:31], v[194:197], v[160:163], v[28:31]
	v_mfma_f32_16x16x32_bf16 v[24:27], v[198:201], v[160:163], v[24:27]
	v_mfma_f32_16x16x32_bf16 v[20:23], v[202:205], v[160:163], v[20:23]
	v_mfma_f32_16x16x32_bf16 v[16:19], v[206:209], v[160:163], v[16:19]
	global_load_dwordx4 v[80:83], v[80:81], off offset:384
	s_waitcnt vmcnt(8)
	ds_write_b128 v109, v[144:147] offset:24576
	v_mfma_f32_16x16x32_bf16 v[12:15], v[194:197], v[190:193], v[12:15]
	v_mfma_f32_16x16x32_bf16 v[8:11], v[198:201], v[190:193], v[8:11]
	v_mfma_f32_16x16x32_bf16 v[4:7], v[202:205], v[190:193], v[4:7]
	v_mfma_f32_16x16x32_bf16 v[0:3], v[206:209], v[190:193], v[0:3]
	global_load_dwordx4 v[84:87], v[84:85], off offset:384
	s_waitcnt vmcnt(8)
	ds_write_b128 v109, v[148:151] offset:28672
	s_cmp_lt_u32 s0, 14
	s_mov_b32 s1, s0
	s_waitcnt lgkmcnt(0)
	s_barrier
	s_cbranch_scc1 .LBB0_92
	s_mul_i32 s0, s69, 0x12000
	v_readlane_b32 s16, v250, 25
	s_add_u32 s24, s16, s0
	v_readlane_b32 s0, v251, 5
	v_lshlrev_b32_e32 v114, 6, v102
	v_readlane_b32 s17, v250, 26
	s_waitcnt vmcnt(5)
	v_add_u32_e32 v64, s0, v108
	v_readlane_b32 s0, v251, 6
	v_add_u32_e32 v56, 0xffffe000, v64
	v_or_b32_e32 v62, v64, v107
	v_or_b32_e32 v65, s0, v114
	v_lshrrev_b32_e32 v56, 10, v56
	s_movk_i32 s0, 0x1800
	v_mad_u32_u24 v56, v56, s0, s0
	v_cmp_lt_i32_e32 vcc, s13, v62
	s_addc_u32 s25, s17, 0
	v_lshlrev_b32_e32 v115, 2, v97
	v_cndmask_b32_e32 v56, 0, v56, vcc
	s_add_u32 s40, s24, 0x2000
	v_or_b32_e32 v58, v65, v115
	v_ashrrev_i32_e32 v57, 31, v56
	s_addc_u32 s41, s25, 0
	s_waitcnt vmcnt(4)
	v_lshlrev_b64 v[74:75], 2, v[56:57]
	v_ashrrev_i32_e32 v59, 31, v58
	v_ashrrev_i32_e32 v63, 31, v62
	v_lshl_add_u64 v[56:57], s[40:41], 0, v[74:75]
	v_lshlrev_b64 v[60:61], 2, v[58:59]
	v_readlane_b32 s0, v250, 15
	s_waitcnt vmcnt(1)
	v_lshl_add_u64 v[82:83], v[56:57], 0, v[60:61]
	v_lshlrev_b64 v[56:57], 12, v[62:63]
	v_readlane_b32 s1, v250, 16
	v_readlane_b32 s16, v250, 21
	v_lshlrev_b64 v[78:79], 11, v[62:63]
	v_lshl_add_u64 v[56:57], s[0:1], 0, v[56:57]
	s_waitcnt vmcnt(0)
	v_lshl_add_u64 v[84:85], v[56:57], 0, v[60:61]
	global_load_dwordx4 v[116:119], v[82:83], off
	global_load_dwordx4 v[120:123], v[82:83], off offset:64
	global_load_dwordx4 v[124:127], v[82:83], off offset:128
	global_load_dwordx4 v[132:135], v[82:83], off offset:192
	global_load_dwordx4 v[190:193], v[84:85], off
	global_load_dwordx4 v[194:197], v[84:85], off offset:64
	global_load_dwordx4 v[198:201], v[84:85], off offset:128
	global_load_dwordx4 v[202:205], v[84:85], off offset:192
	v_add_co_u32_e32 v164, vcc, 0x10000, v84
	s_nop 1
	v_addc_co_u32_e32 v165, vcc, 0, v85, vcc
	v_add_co_u32_e32 v222, vcc, 0x20000, v84
	s_nop 1
	v_addc_co_u32_e32 v223, vcc, 0, v85, vcc
	v_add_co_u32_e32 v224, vcc, 0x30000, v84
	s_nop 1
	v_addc_co_u32_e32 v225, vcc, 0, v85, vcc
	global_load_dwordx4 v[206:209], v[164:165], off
	global_load_dwordx4 v[210:213], v[164:165], off offset:64
	global_load_dwordx4 v[214:217], v[164:165], off offset:128
	global_load_dwordx4 v[218:221], v[164:165], off offset:192
	s_lshl_b32 s0, s69, 12
	v_readlane_b32 s68, v250, 41
	v_readlane_b32 s72, v250, 45
	v_readlane_b32 s73, v250, 46
	s_add_u32 s0, s72, s0
	s_addc_u32 s1, s73, 0
	s_add_u32 s42, s24, 0x4000
	s_addc_u32 s43, s25, 0
	v_lshl_add_u64 v[74:75], s[42:43], 0, v[74:75]
	v_lshl_add_u64 v[56:57], s[0:1], 0, v[60:61]
	v_lshl_add_u64 v[86:87], v[74:75], 0, v[60:61]
	v_readlane_b32 s17, v250, 22
	v_readlane_b32 s69, v250, 42
	v_readlane_b32 s69, v254, 49
	v_lshl_add_u64 v[78:79], s[16:17], 0, v[78:79]
	s_mul_i32 s24, s69, 0x140000
	s_add_u32 s24, s86, s24
	v_lshrrev_b32_e32 v65, 6, v65
	s_mov_b32 s16, 0xa000
	s_addc_u32 s25, s87, 0
	s_add_u32 s26, s24, 0xaf1a000
	s_addc_u32 s27, s25, 0
	v_cmp_eq_u32_e64 s[36:37], 0, v97
	v_readlane_b32 s70, v250, 43
	v_readlane_b32 s71, v250, 44
	v_readlane_b32 s74, v250, 47
	v_readlane_b32 s75, v250, 48
	v_readlane_b32 s76, v250, 49
	v_readlane_b32 s77, v250, 50
	v_readlane_b32 s78, v250, 51
	v_readlane_b32 s79, v250, 52
	v_readlane_b32 s80, v250, 53
	v_readlane_b32 s81, v250, 54
	v_readlane_b32 s82, v250, 55
	v_readlane_b32 s83, v250, 56
	global_load_dwordx4 v[136:139], v[56:57], off
	global_load_dwordx4 v[140:143], v[56:57], off offset:64
	global_load_dwordx4 v[144:147], v[56:57], off offset:128
	global_load_dwordx4 v[148:151], v[56:57], off offset:192
	global_load_dwordx4 v[152:155], v[86:87], off
	global_load_dwordx4 v[156:159], v[86:87], off offset:64
	global_load_dwordx4 v[160:163], v[86:87], off offset:128
	global_load_dwordx4 v[180:183], v[86:87], off offset:192
	s_waitcnt vmcnt(0)
	v_pk_fma_f32 v[68:69], v[94:95], v[118:119], v[192:193]
	v_pk_fma_f32 v[66:67], v[92:93], v[116:117], v[190:191]
	global_store_dwordx4 v[84:85], v[66:69], off
	v_lshl_add_u64 v[92:93], v[58:59], 1, v[78:79]
	s_waitcnt vmcnt(0)
	v_pk_mul_f32 v[72:73], v[68:69], v[138:139]
	v_pk_mul_f32 v[70:71], v[66:67], v[136:137]
	s_waitcnt vmcnt(0)
	v_pk_add_f32 v[76:77], v[154:155], 1.0 op_sel_hi:[1,0]
	v_pk_add_f32 v[74:75], v[152:153], 1.0 op_sel_hi:[1,0]
	v_pk_mul_f32 v[72:73], v[72:73], v[76:77]
	v_pk_mul_f32 v[70:71], v[70:71], v[74:75]
	v_and_b32_sdwa v76, v73, v170 dst_sel:DWORD dst_unused:UNUSED_PAD src0_sel:WORD_1 src1_sel:DWORD
	v_and_b32_sdwa v77, v71, v170 dst_sel:DWORD dst_unused:UNUSED_PAD src0_sel:WORD_1 src1_sel:DWORD
	v_and_b32_sdwa v74, v72, v170 dst_sel:DWORD dst_unused:UNUSED_PAD src0_sel:WORD_1 src1_sel:DWORD
	v_and_b32_sdwa v75, v70, v170 dst_sel:DWORD dst_unused:UNUSED_PAD src0_sel:WORD_1 src1_sel:DWORD
	v_add3_u32 v73, v73, v76, s56
	v_add3_u32 v71, v71, v77, s56
	v_add3_u32 v70, v70, v75, s56
	v_add3_u32 v72, v72, v74, s56
	v_and_b32_e32 v73, 0xffff0000, v73
	v_and_b32_e32 v74, 0xffff0000, v71
	v_or_b32_sdwa v71, v73, v72 dst_sel:DWORD dst_unused:UNUSED_PAD src0_sel:DWORD src1_sel:WORD_1
	v_or_b32_sdwa v70, v74, v70 dst_sel:DWORD dst_unused:UNUSED_PAD src0_sel:DWORD src1_sel:WORD_1
	global_store_dwordx2 v[92:93], v[70:71], off
	s_nop 0
	s_waitcnt vmcnt(0)
	v_pk_fma_f32 v[72:73], v[90:91], v[122:123], v[196:197]
	v_pk_fma_f32 v[70:71], v[88:89], v[120:121], v[194:195]
	global_store_dwordx4 v[84:85], v[70:73], off offset:64
	v_pk_mul_f32 v[76:77], v[72:73], v[142:143]
	v_pk_mul_f32 v[74:75], v[70:71], v[140:141]
	v_pk_add_f32 v[80:81], v[158:159], 1.0 op_sel_hi:[1,0]
	v_pk_add_f32 v[78:79], v[156:157], 1.0 op_sel_hi:[1,0]
	v_pk_mul_f32 v[76:77], v[76:77], v[80:81]
	v_pk_mul_f32 v[74:75], v[74:75], v[78:79]
	v_and_b32_sdwa v80, v77, v170 dst_sel:DWORD dst_unused:UNUSED_PAD src0_sel:WORD_1 src1_sel:DWORD
	v_and_b32_sdwa v81, v75, v170 dst_sel:DWORD dst_unused:UNUSED_PAD src0_sel:WORD_1 src1_sel:DWORD
	v_and_b32_sdwa v78, v76, v170 dst_sel:DWORD dst_unused:UNUSED_PAD src0_sel:WORD_1 src1_sel:DWORD
	v_and_b32_sdwa v79, v74, v170 dst_sel:DWORD dst_unused:UNUSED_PAD src0_sel:WORD_1 src1_sel:DWORD
	v_add3_u32 v77, v77, v80, s56
	v_add3_u32 v75, v75, v81, s56
	v_add3_u32 v74, v74, v79, s56
	v_add3_u32 v76, v76, v78, s56
	v_and_b32_e32 v77, 0xffff0000, v77
	v_and_b32_e32 v78, 0xffff0000, v75
	v_or_b32_sdwa v75, v77, v76 dst_sel:DWORD dst_unused:UNUSED_PAD src0_sel:DWORD src1_sel:WORD_1
	v_or_b32_sdwa v74, v78, v74 dst_sel:DWORD dst_unused:UNUSED_PAD src0_sel:DWORD src1_sel:WORD_1
	global_store_dwordx2 v[92:93], v[74:75], off offset:32
	s_nop 0
	v_pk_fma_f32 v[54:55], v[54:55], v[126:127], v[200:201]
	v_pk_fma_f32 v[52:53], v[52:53], v[124:125], v[198:199]
	global_store_dwordx4 v[84:85], v[52:55], off offset:128
	v_pk_mul_f32 v[76:77], v[54:55], v[146:147]
	v_pk_mul_f32 v[74:75], v[52:53], v[144:145]
	v_pk_add_f32 v[80:81], v[162:163], 1.0 op_sel_hi:[1,0]
	v_pk_add_f32 v[78:79], v[160:161], 1.0 op_sel_hi:[1,0]
	v_pk_mul_f32 v[76:77], v[76:77], v[80:81]
	v_pk_mul_f32 v[74:75], v[74:75], v[78:79]
	v_and_b32_sdwa v80, v77, v170 dst_sel:DWORD dst_unused:UNUSED_PAD src0_sel:WORD_1 src1_sel:DWORD
	v_and_b32_sdwa v81, v75, v170 dst_sel:DWORD dst_unused:UNUSED_PAD src0_sel:WORD_1 src1_sel:DWORD
	v_and_b32_sdwa v78, v76, v170 dst_sel:DWORD dst_unused:UNUSED_PAD src0_sel:WORD_1 src1_sel:DWORD
	v_and_b32_sdwa v79, v74, v170 dst_sel:DWORD dst_unused:UNUSED_PAD src0_sel:WORD_1 src1_sel:DWORD
	v_add3_u32 v77, v77, v80, s56
	v_add3_u32 v75, v75, v81, s56
	v_add3_u32 v74, v74, v79, s56
	v_add3_u32 v76, v76, v78, s56
	v_and_b32_e32 v77, 0xffff0000, v77
	v_and_b32_e32 v78, 0xffff0000, v75
	v_or_b32_sdwa v75, v77, v76 dst_sel:DWORD dst_unused:UNUSED_PAD src0_sel:DWORD src1_sel:WORD_1
	v_or_b32_sdwa v74, v78, v74 dst_sel:DWORD dst_unused:UNUSED_PAD src0_sel:DWORD src1_sel:WORD_1
	global_store_dwordx2 v[92:93], v[74:75], off offset:64
	s_nop 0
	v_pk_fma_f32 v[76:77], v[50:51], v[134:135], v[204:205]
	v_pk_fma_f32 v[74:75], v[48:49], v[132:133], v[202:203]
	global_store_dwordx4 v[84:85], v[74:77], off offset:192
	s_nop 0
	v_mbcnt_lo_u32_b32 v48, -1, 0
	v_mbcnt_hi_u32_b32 v48, -1, v48
	v_and_b32_e32 v50, 64, v48
	v_xor_b32_e32 v49, 16, v48
	v_add_u32_e32 v50, 64, v50
	v_xor_b32_e32 v51, 32, v48
	v_cmp_lt_i32_e32 vcc, v49, v50
	s_nop 1
	v_cndmask_b32_e32 v49, v48, v49, vcc
	v_cmp_lt_i32_e32 vcc, v51, v50
	v_lshlrev_b32_e32 v105, 2, v49
	s_nop 0
	v_cndmask_b32_e32 v50, v48, v51, vcc
	v_lshlrev_b32_e32 v104, 2, v50
	v_mul_f32_e32 v50, v67, v67
	v_mul_f32_e32 v51, v71, v71
	v_fmac_f32_e32 v50, v66, v66
	v_fmac_f32_e32 v51, v70, v70
	v_fmac_f32_e32 v50, v68, v68
	v_fmac_f32_e32 v51, v72, v72
	v_fmac_f32_e32 v50, v69, v69
	v_fmac_f32_e32 v51, v73, v73
	v_add_f32_e32 v50, v50, v51
	v_mul_f32_e32 v51, v53, v53
	v_fmac_f32_e32 v51, v52, v52
	v_fmac_f32_e32 v51, v54, v54
	v_fmac_f32_e32 v51, v55, v55
	v_add_f32_e32 v50, v50, v51
	v_mul_f32_e32 v51, v75, v75
	v_fmac_f32_e32 v51, v74, v74
	v_fmac_f32_e32 v51, v76, v76
	v_fmac_f32_e32 v51, v77, v77
	v_add_f32_e32 v50, v50, v51
	ds_bpermute_b32 v51, v105, v50
	v_mul_lo_u32 v48, v65, s16
	v_ashrrev_i32_e32 v49, 31, v48
	v_lshl_add_u64 v[48:49], s[26:27], 0, v[48:49]
	v_lshl_add_u64 v[48:49], v[62:63], 2, v[48:49]
	s_waitcnt lgkmcnt(0)
	v_add_f32_e32 v50, v50, v51
	ds_bpermute_b32 v51, v104, v50
	v_pk_mul_f32 v[52:53], v[76:77], v[150:151]
	v_pk_mul_f32 v[54:55], v[74:75], v[148:149]
	v_pk_add_f32 v[66:67], v[182:183], 1.0 op_sel_hi:[1,0]
	v_pk_add_f32 v[68:69], v[180:181], 1.0 op_sel_hi:[1,0]
	v_pk_mul_f32 v[52:53], v[52:53], v[66:67]
	v_pk_mul_f32 v[54:55], v[54:55], v[68:69]
	v_and_b32_sdwa v67, v53, v170 dst_sel:DWORD dst_unused:UNUSED_PAD src0_sel:WORD_1 src1_sel:DWORD
	v_and_b32_sdwa v68, v55, v170 dst_sel:DWORD dst_unused:UNUSED_PAD src0_sel:WORD_1 src1_sel:DWORD
	v_and_b32_sdwa v65, v52, v170 dst_sel:DWORD dst_unused:UNUSED_PAD src0_sel:WORD_1 src1_sel:DWORD
	v_and_b32_sdwa v66, v54, v170 dst_sel:DWORD dst_unused:UNUSED_PAD src0_sel:WORD_1 src1_sel:DWORD
	v_add3_u32 v53, v53, v67, s56
	v_add3_u32 v55, v55, v68, s56
	v_add3_u32 v54, v54, v66, s56
	v_add3_u32 v52, v52, v65, s56
	v_and_b32_e32 v53, 0xffff0000, v53
	v_and_b32_e32 v55, 0xffff0000, v55
	v_or_b32_sdwa v53, v53, v52 dst_sel:DWORD dst_unused:UNUSED_PAD src0_sel:DWORD src1_sel:WORD_1
	v_or_b32_sdwa v52, v55, v54 dst_sel:DWORD dst_unused:UNUSED_PAD src0_sel:DWORD src1_sel:WORD_1
	global_store_dwordx2 v[92:93], v[52:53], off offset:96
	s_and_saveexec_b64 s[24:25], s[36:37]
	s_cbranch_execz .LBB0_95
	s_waitcnt lgkmcnt(0)
	v_add_f32_e32 v50, v50, v51
	global_store_dword v[48:49], v50, off

.LBB0_119:
	s_add_i32 s2, s3, 2
	v_add_u32_e32 v127, v89, v90
	ds_read_b128 v[100:103], v127 offset:16384
	ds_read_b128 v[106:109], v127 offset:18432
	ds_read_b128 v[110:113], v127 offset:20480
	ds_read_b128 v[114:117], v127 offset:22528
	v_add_u32_e32 v126, v88, v90
	ds_read_b128 v[92:95], v126
	ds_read_b128 v[96:99], v126 offset:2048
	s_add_i32 s3, s3, 4
	s_min_u32 s3, s3, 15
	v_add_u32_e32 v128, v88, v91
	v_add_u32_e32 v130, v89, v91
	s_lshl_b32 s92, s3, 7
	ds_read_b128 v[118:121], v130 offset:18432
	ds_read_b128 v[122:125], v130 offset:20480
	ds_read_b128 v[132:135], v130 offset:22528
	s_waitcnt lgkmcnt(4)
	v_mfma_f32_16x16x32_bf16 v[76:79], v[100:103], v[92:95], v[76:79]
	v_lshl_add_u64 v[44:45], v[80:81], 0, s[92:93]
	v_add_co_u32_e32 v46, vcc, s11, v44
	v_mfma_f32_16x16x32_bf16 v[68:71], v[106:109], v[92:95], v[68:71]
	s_nop 0
	v_addc_co_u32_e32 v47, vcc, 0, v45, vcc
	v_mfma_f32_16x16x32_bf16 v[52:55], v[110:113], v[92:95], v[52:55]
	v_mfma_f32_16x16x32_bf16 v[40:43], v[114:117], v[92:95], v[40:43]
	s_waitcnt lgkmcnt(3)
	v_mfma_f32_16x16x32_bf16 v[92:95], v[100:103], v[96:99], v[36:39]
	s_nop 2
	ds_read_b128 v[36:39], v128
	v_mfma_f32_16x16x32_bf16 v[100:103], v[106:109], v[96:99], v[8:11]
	v_mfma_f32_16x16x32_bf16 v[106:109], v[110:113], v[96:99], v[4:7]
	ds_read_b128 v[110:113], v128 offset:2048
	v_mfma_f32_16x16x32_bf16 v[96:99], v[114:117], v[96:99], v[0:3]
	ds_read_b128 v[114:117], v130 offset:16384
	global_load_dwordx4 v[72:75], v[44:45], off
	s_waitcnt vmcnt(1)
	ds_write_b128 v87, v[12:15] offset:53248
	global_load_dwordx4 v[64:67], v[46:47], off
	v_add_co_u32_e32 v46, vcc, s33, v44
	ds_write_b128 v87, v[16:19] offset:49152
	s_nop 0
	v_addc_co_u32_e32 v47, vcc, 0, v45, vcc
	v_add_co_u32_e32 v44, vcc, s59, v44
	global_load_dwordx4 v[60:63], v[46:47], off
	s_nop 0
	v_addc_co_u32_e32 v45, vcc, 0, v45, vcc
	ds_write_b128 v87, v[20:23] offset:45056
	global_load_dwordx4 v[56:59], v[44:45], off
	v_lshl_add_u64 v[44:45], v[82:83], 0, s[92:93]
	ds_write_b128 v87, v[28:31] offset:32768
	s_waitcnt lgkmcnt(4)
	v_mfma_f32_16x16x32_bf16 v[0:3], v[114:117], v[36:39], v[76:79]
	v_mfma_f32_16x16x32_bf16 v[4:7], v[118:121], v[36:39], v[68:71]
	global_load_dwordx4 v[48:51], v[44:45], off
	v_add_co_u32_e32 v44, vcc, s11, v44
	ds_write_b128 v87, v[32:35] offset:36864
	s_nop 0
	v_addc_co_u32_e32 v45, vcc, 0, v45, vcc
	v_mfma_f32_16x16x32_bf16 v[8:11], v[122:125], v[36:39], v[52:55]
	v_mfma_f32_16x16x32_bf16 v[36:39], v[132:135], v[36:39], v[40:43]
	global_load_dwordx4 v[44:47], v[44:45], off
	ds_write_b128 v87, v[24:27] offset:40960
	v_mfma_f32_16x16x32_bf16 v[40:43], v[114:117], v[110:113], v[92:95]
	v_mfma_f32_16x16x32_bf16 v[52:55], v[118:121], v[110:113], v[100:103]
	v_mfma_f32_16x16x32_bf16 v[68:71], v[122:125], v[110:113], v[106:109]
	v_mfma_f32_16x16x32_bf16 v[76:79], v[132:135], v[110:113], v[96:99]
	s_waitcnt lgkmcnt(0)
	s_barrier
	ds_read_b128 v[100:103], v127 offset:49152
	ds_read_b128 v[106:109], v127 offset:51200
	ds_read_b128 v[110:113], v127 offset:53248
	ds_read_b128 v[114:117], v127 offset:55296
	ds_read_b128 v[92:95], v126 offset:32768
	ds_read_b128 v[96:99], v126 offset:34816
	s_min_u32 s3, s2, 12
	s_lshl_b32 s92, s3, 7
	ds_read_b128 v[118:121], v130 offset:51200
	ds_read_b128 v[122:125], v130 offset:53248
	ds_read_b128 v[132:135], v130 offset:55296
	s_waitcnt lgkmcnt(4)
	v_mfma_f32_16x16x32_bf16 v[0:3], v[100:103], v[92:95], v[0:3]
	v_lshl_add_u64 v[12:13], v[80:81], 0, s[92:93]
	v_add_co_u32_e32 v14, vcc, s11, v12
	v_mfma_f32_16x16x32_bf16 v[4:7], v[106:109], v[92:95], v[4:7]
	s_nop 0
	v_addc_co_u32_e32 v15, vcc, 0, v13, vcc
	v_mfma_f32_16x16x32_bf16 v[8:11], v[110:113], v[92:95], v[8:11]
	v_mfma_f32_16x16x32_bf16 v[36:39], v[114:117], v[92:95], v[36:39]
	s_waitcnt lgkmcnt(3)
	v_mfma_f32_16x16x32_bf16 v[92:95], v[100:103], v[96:99], v[40:43]
	s_nop 2
	ds_read_b128 v[40:43], v128 offset:32768
	v_mfma_f32_16x16x32_bf16 v[100:103], v[106:109], v[96:99], v[52:55]
	v_mfma_f32_16x16x32_bf16 v[106:109], v[110:113], v[96:99], v[68:71]
	ds_read_b128 v[110:113], v128 offset:34816
	v_mfma_f32_16x16x32_bf16 v[96:99], v[114:117], v[96:99], v[76:79]
	ds_read_b128 v[114:117], v130 offset:49152
	global_load_dwordx4 v[28:31], v[12:13], off offset:384
	s_waitcnt vmcnt(1)
	ds_write_b128 v87, v[44:47] offset:20480
	global_load_dwordx4 v[32:35], v[14:15], off offset:384
	v_add_co_u32_e32 v14, vcc, s33, v12
	ds_write_b128 v87, v[48:51] offset:16384
	s_nop 0
	v_addc_co_u32_e32 v15, vcc, 0, v13, vcc
	v_add_co_u32_e32 v12, vcc, s59, v12
	global_load_dwordx4 v[24:27], v[14:15], off offset:384
	s_nop 0
	v_addc_co_u32_e32 v13, vcc, 0, v13, vcc
	ds_write_b128 v87, v[56:59] offset:12288
	global_load_dwordx4 v[20:23], v[12:13], off offset:384
	v_lshl_add_u64 v[12:13], v[82:83], 0, s[92:93]
	ds_write_b128 v87, v[72:75]
	s_waitcnt lgkmcnt(4)
	v_mfma_f32_16x16x32_bf16 v[76:79], v[114:117], v[40:43], v[0:3]
	v_mfma_f32_16x16x32_bf16 v[68:71], v[118:121], v[40:43], v[4:7]
	global_load_dwordx4 v[16:19], v[12:13], off offset:384
	v_add_co_u32_e32 v12, vcc, s11, v12
	ds_write_b128 v87, v[64:67] offset:4096
	s_nop 0
	v_addc_co_u32_e32 v13, vcc, 0, v13, vcc
	v_mfma_f32_16x16x32_bf16 v[52:55], v[122:125], v[40:43], v[8:11]
	v_mfma_f32_16x16x32_bf16 v[40:43], v[132:135], v[40:43], v[36:39]
	global_load_dwordx4 v[12:15], v[12:13], off offset:384
	ds_write_b128 v87, v[60:63] offset:8192
	v_mfma_f32_16x16x32_bf16 v[36:39], v[114:117], v[110:113], v[92:95]
	v_mfma_f32_16x16x32_bf16 v[8:11], v[118:121], v[110:113], v[100:103]
	v_mfma_f32_16x16x32_bf16 v[4:7], v[122:125], v[110:113], v[106:109]
	v_mfma_f32_16x16x32_bf16 v[0:3], v[132:135], v[110:113], v[96:99]
	s_cmp_lt_u32 s2, 14
	s_mov_b32 s3, s2
	s_waitcnt lgkmcnt(0)
	s_barrier
	s_cbranch_scc1 .LBB0_119
	v_readlane_b32 s2, v251, 18
	s_waitcnt vmcnt(1)
	s_nop 0
	v_add_u32_e32 v18, s2, v86
	v_readlane_b32 s2, v251, 19
	s_waitcnt vmcnt(0)
	v_add_u32_e32 v13, 0xffffe000, v18
	v_or_b32_e32 v12, v18, v85
	v_lshl_or_b32 v19, v84, 2, s2
	v_lshrrev_b32_e32 v13, 10, v13
	s_movk_i32 s2, 0x1800
	v_mad_u32_u24 v13, v13, s2, s2
	v_cmp_lt_i32_e32 vcc, s13, v12
	v_lshlrev_b32_e32 v128, 2, v19
	v_readlane_b32 s2, v250, 15
	v_cndmask_b32_e32 v14, 0, v13, vcc
	v_ashrrev_i32_e32 v15, 31, v14
	v_lshlrev_b64 v[24:25], 2, v[14:15]
	v_ashrrev_i32_e32 v13, 31, v12
	v_lshl_add_u64 v[14:15], s[40:41], 0, v[24:25]
	v_lshl_add_u64 v[48:49], v[14:15], 0, v[128:129]
	v_lshlrev_b64 v[14:15], 12, v[12:13]
	v_readlane_b32 s3, v250, 16
	v_lshl_add_u64 v[28:29], s[42:43], 0, v[24:25]
	v_lshlrev_b64 v[32:33], 11, v[12:13]
	v_lshl_add_u64 v[14:15], s[2:3], 0, v[14:15]
	v_lshl_add_u64 v[50:51], v[14:15], 0, v[128:129]
	global_load_dwordx4 v[72:75], v[48:49], off
	global_load_dwordx4 v[80:83], v[48:49], off offset:64
	global_load_dwordx4 v[88:91], v[48:49], off offset:128
	global_load_dwordx4 v[136:139], v[48:49], off offset:192
	global_load_dwordx4 v[194:197], v[50:51], off
	global_load_dwordx4 v[198:201], v[50:51], off offset:64
	global_load_dwordx4 v[202:205], v[50:51], off offset:128
	global_load_dwordx4 v[206:209], v[50:51], off offset:192
	v_add_co_u32_e32 v58, vcc, 0x10000, v50
	s_nop 1
	v_addc_co_u32_e32 v59, vcc, 0, v51, vcc
	global_load_dwordx4 v[210:213], v[58:59], off
	global_load_dwordx4 v[214:217], v[58:59], off offset:64
	global_load_dwordx4 v[218:221], v[58:59], off offset:128
	global_load_dwordx4 v[222:225], v[58:59], off offset:192
	v_readlane_b32 s2, v250, 21
	v_readlane_b32 s3, v250, 22
	v_cmp_eq_u32_e32 vcc, 0, v84
	global_load_dwordx4 v[140:143], v128, s[0:1]
	global_load_dwordx4 v[144:147], v128, s[0:1] offset:64
	global_load_dwordx4 v[148:151], v128, s[0:1] offset:128
	global_load_dwordx4 v[152:155], v128, s[0:1] offset:192
	s_waitcnt vmcnt(0)
	v_pk_fma_f32 v[22:23], v[78:79], v[74:75], v[196:197]
	v_pk_fma_f32 v[20:21], v[76:77], v[72:73], v[194:195]
	global_store_dwordx4 v[50:51], v[20:23], off
	v_lshl_add_u64 v[14:15], v[28:29], 0, v[128:129]
	global_load_dwordx4 v[156:159], v[14:15], off
	global_load_dwordx4 v[160:163], v[14:15], off offset:64
	global_load_dwordx4 v[180:183], v[14:15], off offset:128
	global_load_dwordx4 v[190:193], v[14:15], off offset:192
	v_lshlrev_b32_e32 v16, 1, v19
	v_mov_b32_e32 v17, v129
	v_lshl_add_u64 v[32:33], s[2:3], 0, v[32:33]
	v_lshl_add_u64 v[56:57], v[32:33], 0, v[16:17]
	s_waitcnt vmcnt(0)
	v_pk_mul_f32 v[26:27], v[22:23], v[142:143]
	v_pk_mul_f32 v[24:25], v[20:21], v[140:141]
	s_waitcnt vmcnt(0)
	v_pk_add_f32 v[30:31], v[158:159], 1.0 op_sel_hi:[1,0]
	v_pk_add_f32 v[28:29], v[156:157], 1.0 op_sel_hi:[1,0]
	v_pk_mul_f32 v[26:27], v[26:27], v[30:31]
	v_pk_mul_f32 v[24:25], v[24:25], v[28:29]
	v_and_b32_sdwa v19, v26, v170 dst_sel:DWORD dst_unused:UNUSED_PAD src0_sel:WORD_1 src1_sel:DWORD
	v_and_b32_sdwa v29, v27, v170 dst_sel:DWORD dst_unused:UNUSED_PAD src0_sel:WORD_1 src1_sel:DWORD
	v_and_b32_sdwa v30, v25, v170 dst_sel:DWORD dst_unused:UNUSED_PAD src0_sel:WORD_1 src1_sel:DWORD
	v_and_b32_sdwa v28, v24, v170 dst_sel:DWORD dst_unused:UNUSED_PAD src0_sel:WORD_1 src1_sel:DWORD
	v_add3_u32 v19, v26, v19, s56
	v_add3_u32 v26, v27, v29, s56
	v_add3_u32 v25, v25, v30, s56
	v_add3_u32 v24, v24, v28, s56
	v_and_b32_e32 v26, 0xffff0000, v26
	v_and_b32_e32 v27, 0xffff0000, v25
	v_or_b32_sdwa v25, v26, v19 dst_sel:DWORD dst_unused:UNUSED_PAD src0_sel:DWORD src1_sel:WORD_1
	v_or_b32_sdwa v24, v27, v24 dst_sel:DWORD dst_unused:UNUSED_PAD src0_sel:DWORD src1_sel:WORD_1
	global_store_dwordx2 v[56:57], v[24:25], off
	s_nop 0
	s_waitcnt vmcnt(0)
	v_pk_fma_f32 v[26:27], v[70:71], v[82:83], v[200:201]
	v_pk_fma_f32 v[24:25], v[68:69], v[80:81], v[198:199]
	global_store_dwordx4 v[50:51], v[24:27], off offset:64
	v_pk_mul_f32 v[30:31], v[26:27], v[146:147]
	v_pk_mul_f32 v[28:29], v[24:25], v[144:145]
	v_pk_add_f32 v[34:35], v[162:163], 1.0 op_sel_hi:[1,0]
	v_pk_add_f32 v[32:33], v[160:161], 1.0 op_sel_hi:[1,0]
	v_pk_mul_f32 v[30:31], v[30:31], v[34:35]
	v_pk_mul_f32 v[28:29], v[28:29], v[32:33]
	v_and_b32_sdwa v19, v30, v170 dst_sel:DWORD dst_unused:UNUSED_PAD src0_sel:WORD_1 src1_sel:DWORD
	v_and_b32_sdwa v33, v31, v170 dst_sel:DWORD dst_unused:UNUSED_PAD src0_sel:WORD_1 src1_sel:DWORD
	v_and_b32_sdwa v34, v29, v170 dst_sel:DWORD dst_unused:UNUSED_PAD src0_sel:WORD_1 src1_sel:DWORD
	v_and_b32_sdwa v32, v28, v170 dst_sel:DWORD dst_unused:UNUSED_PAD src0_sel:WORD_1 src1_sel:DWORD
	v_add3_u32 v19, v30, v19, s56
	v_add3_u32 v30, v31, v33, s56
	v_add3_u32 v29, v29, v34, s56
	v_add3_u32 v28, v28, v32, s56
	v_and_b32_e32 v30, 0xffff0000, v30
	v_and_b32_e32 v31, 0xffff0000, v29
	v_or_b32_sdwa v29, v30, v19 dst_sel:DWORD dst_unused:UNUSED_PAD src0_sel:DWORD src1_sel:WORD_1
	v_or_b32_sdwa v28, v31, v28 dst_sel:DWORD dst_unused:UNUSED_PAD src0_sel:DWORD src1_sel:WORD_1
	global_store_dwordx2 v[56:57], v[28:29], off offset:32
	s_nop 0
	v_pk_fma_f32 v[30:31], v[54:55], v[90:91], v[204:205]
	v_pk_fma_f32 v[28:29], v[52:53], v[88:89], v[202:203]
	global_store_dwordx4 v[50:51], v[28:31], off offset:128
	v_pk_mul_f32 v[34:35], v[30:31], v[150:151]
	v_pk_mul_f32 v[32:33], v[28:29], v[148:149]
	v_pk_add_f32 v[46:47], v[182:183], 1.0 op_sel_hi:[1,0]
	v_pk_add_f32 v[44:45], v[180:181], 1.0 op_sel_hi:[1,0]
	v_pk_mul_f32 v[34:35], v[34:35], v[46:47]
	v_pk_mul_f32 v[32:33], v[32:33], v[44:45]
	v_and_b32_sdwa v19, v34, v170 dst_sel:DWORD dst_unused:UNUSED_PAD src0_sel:WORD_1 src1_sel:DWORD
	v_and_b32_sdwa v45, v35, v170 dst_sel:DWORD dst_unused:UNUSED_PAD src0_sel:WORD_1 src1_sel:DWORD
	v_and_b32_sdwa v46, v33, v170 dst_sel:DWORD dst_unused:UNUSED_PAD src0_sel:WORD_1 src1_sel:DWORD
	v_and_b32_sdwa v44, v32, v170 dst_sel:DWORD dst_unused:UNUSED_PAD src0_sel:WORD_1 src1_sel:DWORD
	v_add3_u32 v19, v34, v19, s56
	v_add3_u32 v34, v35, v45, s56
	v_add3_u32 v33, v33, v46, s56
	v_add3_u32 v32, v32, v44, s56
	v_and_b32_e32 v34, 0xffff0000, v34
	v_and_b32_e32 v35, 0xffff0000, v33
	v_or_b32_sdwa v33, v34, v19 dst_sel:DWORD dst_unused:UNUSED_PAD src0_sel:DWORD src1_sel:WORD_1
	v_or_b32_sdwa v32, v35, v32 dst_sel:DWORD dst_unused:UNUSED_PAD src0_sel:DWORD src1_sel:WORD_1
	global_store_dwordx2 v[56:57], v[32:33], off offset:64
	s_nop 0
	v_pk_fma_f32 v[34:35], v[42:43], v[138:139], v[208:209]
	v_pk_fma_f32 v[32:33], v[40:41], v[136:137], v[206:207]
	global_store_dwordx4 v[50:51], v[32:35], off offset:192
	v_mul_f32_e32 v14, v21, v21
	v_mul_f32_e32 v15, v25, v25
	v_fmac_f32_e32 v14, v20, v20
	v_fmac_f32_e32 v15, v24, v24
	v_fmac_f32_e32 v14, v22, v22
	v_fmac_f32_e32 v15, v26, v26
	v_fmac_f32_e32 v14, v23, v23
	v_fmac_f32_e32 v15, v27, v27
	v_add_f32_e32 v14, v14, v15
	v_mul_f32_e32 v15, v29, v29
	v_fmac_f32_e32 v15, v28, v28
	v_fmac_f32_e32 v15, v30, v30
	v_fmac_f32_e32 v15, v31, v31
	v_add_f32_e32 v14, v14, v15
	v_mul_f32_e32 v15, v33, v33
	v_fmac_f32_e32 v15, v32, v32
	v_fmac_f32_e32 v15, v34, v34
	v_fmac_f32_e32 v15, v35, v35
	v_add_f32_e32 v14, v14, v15
	ds_bpermute_b32 v15, v105, v14
	s_waitcnt lgkmcnt(0)
	v_add_f32_e32 v14, v14, v15
	ds_bpermute_b32 v15, v104, v14
	v_pk_mul_f32 v[20:21], v[34:35], v[154:155]
	v_pk_mul_f32 v[22:23], v[32:33], v[152:153]
	v_pk_add_f32 v[24:25], v[192:193], 1.0 op_sel_hi:[1,0]
	v_pk_add_f32 v[26:27], v[190:191], 1.0 op_sel_hi:[1,0]
	v_pk_mul_f32 v[20:21], v[20:21], v[24:25]
	v_pk_mul_f32 v[22:23], v[22:23], v[26:27]
	v_and_b32_sdwa v19, v20, v170 dst_sel:DWORD dst_unused:UNUSED_PAD src0_sel:WORD_1 src1_sel:DWORD
	v_and_b32_sdwa v25, v21, v170 dst_sel:DWORD dst_unused:UNUSED_PAD src0_sel:WORD_1 src1_sel:DWORD
	v_and_b32_sdwa v26, v23, v170 dst_sel:DWORD dst_unused:UNUSED_PAD src0_sel:WORD_1 src1_sel:DWORD
	v_and_b32_sdwa v24, v22, v170 dst_sel:DWORD dst_unused:UNUSED_PAD src0_sel:WORD_1 src1_sel:DWORD
	v_add3_u32 v19, v20, v19, s56
	v_add3_u32 v20, v21, v25, s56
	v_add3_u32 v21, v23, v26, s56
	v_add3_u32 v22, v22, v24, s56
	v_and_b32_e32 v20, 0xffff0000, v20
	v_and_b32_e32 v23, 0xffff0000, v21
	v_or_b32_sdwa v21, v20, v19 dst_sel:DWORD dst_unused:UNUSED_PAD src0_sel:DWORD src1_sel:WORD_1
	v_or_b32_sdwa v20, v23, v22 dst_sel:DWORD dst_unused:UNUSED_PAD src0_sel:DWORD src1_sel:WORD_1
	global_store_dwordx2 v[56:57], v[20:21], off offset:96
	s_and_saveexec_b64 s[2:3], vcc
	s_cbranch_execz .LBB0_122
	v_readlane_b32 s16, v253, 20
	s_add_u32 s24, s26, s16
	s_addc_u32 s25, s27, 0
	v_lshl_add_u64 v[20:21], v[12:13], 2, s[24:25]
	s_waitcnt lgkmcnt(0)
	v_add_f32_e32 v13, v14, v15
	global_store_dword v[20:21], v13, off

.LBB0_236:
	s_add_i32 s24, s25, 2
	v_add_u32_e32 v111, v104, v105
	ds_read_b128 v[136:139], v111 offset:16384
	ds_read_b128 v[140:143], v111 offset:18432
	ds_read_b128 v[144:147], v111 offset:20480
	ds_read_b128 v[148:151], v111 offset:22528
	v_add_u32_e32 v110, v103, v105
	ds_read_b128 v[116:119], v110
	s_add_i32 s25, s25, 4
	ds_read_b128 v[120:123], v110 offset:2048
	s_min_u32 s25, s25, 63
	v_add_u32_e32 v113, v104, v114
	s_lshl_b32 s92, s25, 7
	ds_read_b128 v[124:127], v110 offset:4096
	v_add_u32_e32 v112, v103, v114
	ds_read_b128 v[194:197], v113 offset:16384
	ds_read_b128 v[198:201], v113 offset:18432
	ds_read_b128 v[202:205], v113 offset:20480
	ds_read_b128 v[206:209], v113 offset:22528
	v_lshl_add_u64 v[164:165], v[98:99], 0, s[92:93]
	ds_read_b128 v[132:135], v110 offset:6144
	ds_read_b128 v[152:155], v112
	ds_read_b128 v[156:159], v112 offset:2048
	ds_read_b128 v[160:163], v112 offset:4096
	ds_read_b128 v[190:193], v112 offset:6144
	s_waitcnt lgkmcnt(11)
	v_mfma_f32_16x16x32_bf16 v[92:95], v[136:139], v[116:119], v[92:95]
	v_mfma_f32_16x16x32_bf16 v[56:59], v[140:143], v[116:119], v[56:59]
	v_mfma_f32_16x16x32_bf16 v[52:55], v[144:147], v[116:119], v[52:55]
	v_mfma_f32_16x16x32_bf16 v[48:51], v[148:151], v[116:119], v[48:51]
	global_load_dwordx4 v[116:119], v[164:165], off
	s_waitcnt vmcnt(6)
	ds_write_b128 v109, v[60:63] offset:32768
	v_add_co_u32_e32 v60, vcc, s7, v164
	s_waitcnt lgkmcnt(11)
	v_mfma_f32_16x16x32_bf16 v[44:47], v[136:139], v[120:123], v[44:47]
	v_addc_co_u32_e32 v61, vcc, 0, v165, vcc
	v_mfma_f32_16x16x32_bf16 v[40:43], v[140:143], v[120:123], v[40:43]
	v_mfma_f32_16x16x32_bf16 v[36:39], v[144:147], v[120:123], v[36:39]
	v_mfma_f32_16x16x32_bf16 v[32:35], v[148:151], v[120:123], v[32:35]
	global_load_dwordx4 v[120:123], v[60:61], off
	v_add_co_u32_e32 v60, vcc, s52, v164
	ds_write_b128 v109, v[64:67] offset:36864
	s_nop 0
	v_addc_co_u32_e32 v61, vcc, 0, v165, vcc
	s_waitcnt lgkmcnt(11)
	v_mfma_f32_16x16x32_bf16 v[28:31], v[136:139], v[124:127], v[28:31]
	v_lshl_add_u64 v[64:65], v[100:101], 0, s[92:93]
	v_mfma_f32_16x16x32_bf16 v[24:27], v[140:143], v[124:127], v[24:27]
	v_mfma_f32_16x16x32_bf16 v[20:23], v[144:147], v[124:127], v[20:23]
	v_mfma_f32_16x16x32_bf16 v[16:19], v[148:151], v[124:127], v[16:19]
	global_load_dwordx4 v[124:127], v[60:61], off
	v_add_co_u32_e32 v60, vcc, s34, v164
	ds_write_b128 v109, v[68:71] offset:40960
	s_nop 0
	v_addc_co_u32_e32 v61, vcc, 0, v165, vcc
	v_add_co_u32_e32 v66, vcc, s7, v64
	s_waitcnt lgkmcnt(7)
	v_mfma_f32_16x16x32_bf16 v[12:15], v[136:139], v[132:135], v[12:15]
	v_addc_co_u32_e32 v67, vcc, 0, v65, vcc
	v_mfma_f32_16x16x32_bf16 v[8:11], v[140:143], v[132:135], v[8:11]
	v_mfma_f32_16x16x32_bf16 v[4:7], v[144:147], v[132:135], v[4:7]
	v_mfma_f32_16x16x32_bf16 v[0:3], v[148:151], v[132:135], v[0:3]
	global_load_dwordx4 v[132:135], v[60:61], off
	s_waitcnt vmcnt(7)
	ds_write_b128 v109, v[76:79] offset:45056
	s_waitcnt lgkmcnt(7)
	v_mfma_f32_16x16x32_bf16 v[60:63], v[194:197], v[152:155], v[92:95]
	v_mfma_f32_16x16x32_bf16 v[56:59], v[198:201], v[152:155], v[56:59]
	v_mfma_f32_16x16x32_bf16 v[52:55], v[202:205], v[152:155], v[52:55]
	v_mfma_f32_16x16x32_bf16 v[48:51], v[206:209], v[152:155], v[48:51]
	global_load_dwordx4 v[136:139], v[64:65], off
	ds_write_b128 v109, v[72:75] offset:49152
	s_waitcnt lgkmcnt(7)
	v_mfma_f32_16x16x32_bf16 v[44:47], v[194:197], v[156:159], v[44:47]
	v_mfma_f32_16x16x32_bf16 v[40:43], v[198:201], v[156:159], v[40:43]
	v_mfma_f32_16x16x32_bf16 v[36:39], v[202:205], v[156:159], v[36:39]
	v_mfma_f32_16x16x32_bf16 v[32:35], v[206:209], v[156:159], v[32:35]
	global_load_dwordx4 v[140:143], v[66:67], off
	v_add_co_u32_e32 v66, vcc, s52, v64
	s_waitcnt vmcnt(8)
	ds_write_b128 v109, v[80:83] offset:53248
	v_addc_co_u32_e32 v67, vcc, 0, v65, vcc
	v_add_co_u32_e32 v64, vcc, s34, v64
	s_waitcnt lgkmcnt(7)
	v_mfma_f32_16x16x32_bf16 v[28:31], v[194:197], v[160:163], v[28:31]
	v_addc_co_u32_e32 v65, vcc, 0, v65, vcc
	v_mfma_f32_16x16x32_bf16 v[24:27], v[198:201], v[160:163], v[24:27]
	v_mfma_f32_16x16x32_bf16 v[20:23], v[202:205], v[160:163], v[20:23]
	v_mfma_f32_16x16x32_bf16 v[16:19], v[206:209], v[160:163], v[16:19]
	global_load_dwordx4 v[144:147], v[66:67], off
	s_waitcnt vmcnt(8)
	ds_write_b128 v109, v[84:87] offset:57344
	s_waitcnt lgkmcnt(7)
	v_mfma_f32_16x16x32_bf16 v[12:15], v[194:197], v[190:193], v[12:15]
	v_mfma_f32_16x16x32_bf16 v[8:11], v[198:201], v[190:193], v[8:11]
	v_mfma_f32_16x16x32_bf16 v[4:7], v[202:205], v[190:193], v[4:7]
	v_mfma_f32_16x16x32_bf16 v[0:3], v[206:209], v[190:193], v[0:3]
	global_load_dwordx4 v[148:151], v[64:65], off
	s_waitcnt vmcnt(8)
	ds_write_b128 v109, v[88:91] offset:61440
	s_waitcnt lgkmcnt(0)
	s_barrier
	ds_read_b128 v[80:83], v111 offset:49152
	ds_read_b128 v[84:87], v111 offset:51200
	ds_read_b128 v[88:91], v111 offset:53248
	ds_read_b128 v[92:95], v111 offset:55296
	ds_read_b128 v[64:67], v110 offset:32768
	ds_read_b128 v[68:71], v110 offset:34816
	s_min_u32 s25, s24, 60
	s_lshl_b32 s92, s25, 7
	ds_read_b128 v[72:75], v110 offset:36864
	v_lshl_add_u64 v[164:165], v[98:99], 0, s[92:93]
	ds_read_b128 v[76:79], v110 offset:38912
	ds_read_b128 v[152:155], v112 offset:32768
	ds_read_b128 v[156:159], v112 offset:34816
	ds_read_b128 v[160:163], v112 offset:36864
	ds_read_b128 v[190:193], v112 offset:38912
	ds_read_b128 v[194:197], v113 offset:49152
	ds_read_b128 v[198:201], v113 offset:51200
	ds_read_b128 v[202:205], v113 offset:53248
	ds_read_b128 v[206:209], v113 offset:55296
	s_waitcnt lgkmcnt(11)
	v_mfma_f32_16x16x32_bf16 v[210:213], v[80:83], v[64:67], v[60:63]
	v_mfma_f32_16x16x32_bf16 v[56:59], v[84:87], v[64:67], v[56:59]
	v_mfma_f32_16x16x32_bf16 v[52:55], v[88:91], v[64:67], v[52:55]
	v_mfma_f32_16x16x32_bf16 v[48:51], v[92:95], v[64:67], v[48:51]
	v_add_co_u32_e32 v64, vcc, s7, v164
	global_load_dwordx4 v[60:63], v[164:165], off offset:384
	s_nop 0
	v_addc_co_u32_e32 v65, vcc, 0, v165, vcc
	s_waitcnt vmcnt(8)
	ds_write_b128 v109, v[116:119]
	s_waitcnt lgkmcnt(11)
	v_mfma_f32_16x16x32_bf16 v[44:47], v[80:83], v[68:71], v[44:47]
	v_mfma_f32_16x16x32_bf16 v[40:43], v[84:87], v[68:71], v[40:43]
	v_mfma_f32_16x16x32_bf16 v[36:39], v[88:91], v[68:71], v[36:39]
	v_mfma_f32_16x16x32_bf16 v[32:35], v[92:95], v[68:71], v[32:35]
	v_add_co_u32_e32 v68, vcc, s52, v164
	global_load_dwordx4 v[64:67], v[64:65], off offset:384
	s_nop 0
	v_addc_co_u32_e32 v69, vcc, 0, v165, vcc
	s_waitcnt vmcnt(8)
	ds_write_b128 v109, v[120:123] offset:4096
	s_waitcnt lgkmcnt(11)
	v_mfma_f32_16x16x32_bf16 v[28:31], v[80:83], v[72:75], v[28:31]
	v_mfma_f32_16x16x32_bf16 v[24:27], v[84:87], v[72:75], v[24:27]
	v_mfma_f32_16x16x32_bf16 v[20:23], v[88:91], v[72:75], v[20:23]
	v_mfma_f32_16x16x32_bf16 v[16:19], v[92:95], v[72:75], v[16:19]
	v_add_co_u32_e32 v72, vcc, s34, v164
	global_load_dwordx4 v[68:71], v[68:69], off offset:384
	s_waitcnt vmcnt(8)
	ds_write_b128 v109, v[124:127] offset:8192
	s_waitcnt lgkmcnt(11)
	v_mfma_f32_16x16x32_bf16 v[4:7], v[88:91], v[76:79], v[4:7]
	v_addc_co_u32_e32 v73, vcc, 0, v165, vcc
	v_lshl_add_u64 v[88:89], v[100:101], 0, s[92:93]
	v_mfma_f32_16x16x32_bf16 v[12:15], v[80:83], v[76:79], v[12:15]
	v_add_co_u32_e32 v80, vcc, s7, v88
	v_mfma_f32_16x16x32_bf16 v[8:11], v[84:87], v[76:79], v[8:11]
	s_nop 0
	v_addc_co_u32_e32 v81, vcc, 0, v89, vcc
	v_add_co_u32_e32 v84, vcc, s52, v88
	v_mfma_f32_16x16x32_bf16 v[0:3], v[92:95], v[76:79], v[0:3]
	s_nop 0
	v_addc_co_u32_e32 v85, vcc, 0, v89, vcc
	global_load_dwordx4 v[76:79], v[72:73], off offset:384
	s_waitcnt vmcnt(8)
	ds_write_b128 v109, v[132:135] offset:12288
	s_waitcnt lgkmcnt(7)
	v_mfma_f32_16x16x32_bf16 v[92:95], v[194:197], v[152:155], v[210:213]
	s_waitcnt lgkmcnt(6)
	v_mfma_f32_16x16x32_bf16 v[56:59], v[198:201], v[152:155], v[56:59]
	s_waitcnt lgkmcnt(5)
	v_mfma_f32_16x16x32_bf16 v[52:55], v[202:205], v[152:155], v[52:55]
	s_waitcnt lgkmcnt(4)
	v_mfma_f32_16x16x32_bf16 v[48:51], v[206:209], v[152:155], v[48:51]
	global_load_dwordx4 v[72:75], v[88:89], off offset:384
	v_add_co_u32_e32 v88, vcc, s34, v88
	s_waitcnt vmcnt(8)
	ds_write_b128 v109, v[136:139] offset:16384
	v_addc_co_u32_e32 v89, vcc, 0, v89, vcc
	v_mfma_f32_16x16x32_bf16 v[44:47], v[194:197], v[156:159], v[44:47]
	v_mfma_f32_16x16x32_bf16 v[40:43], v[198:201], v[156:159], v[40:43]
	v_mfma_f32_16x16x32_bf16 v[36:39], v[202:205], v[156:159], v[36:39]
	v_mfma_f32_16x16x32_bf16 v[32:35], v[206:209], v[156:159], v[32:35]
	global_load_dwordx4 v[80:83], v[80:81], off offset:384
	s_waitcnt vmcnt(8)
	ds_write_b128 v109, v[140:143] offset:20480
	v_mfma_f32_16x16x32_bf16 v[28:31], v[194:197], v[160:163], v[28:31]
	v_mfma_f32_16x16x32_bf16 v[24:27], v[198:201], v[160:163], v[24:27]
	v_mfma_f32_16x16x32_bf16 v[20:23], v[202:205], v[160:163], v[20:23]
	v_mfma_f32_16x16x32_bf16 v[16:19], v[206:209], v[160:163], v[16:19]
	global_load_dwordx4 v[84:87], v[84:85], off offset:384
	s_waitcnt vmcnt(8)
	ds_write_b128 v109, v[144:147] offset:24576
	v_mfma_f32_16x16x32_bf16 v[12:15], v[194:197], v[190:193], v[12:15]
	v_mfma_f32_16x16x32_bf16 v[8:11], v[198:201], v[190:193], v[8:11]
	v_mfma_f32_16x16x32_bf16 v[4:7], v[202:205], v[190:193], v[4:7]
	v_mfma_f32_16x16x32_bf16 v[0:3], v[206:209], v[190:193], v[0:3]
	global_load_dwordx4 v[88:91], v[88:89], off offset:384
	s_waitcnt vmcnt(8)
	ds_write_b128 v109, v[148:151] offset:28672
	s_cmp_lt_u32 s24, 62
	s_mov_b32 s25, s24
	s_waitcnt lgkmcnt(0)
	s_barrier
	s_cbranch_scc1 .LBB0_236
	s_add_i32 s26, s69, 1
	v_readlane_b32 s16, v251, 5
	s_and_b64 s[24:25], s[8:9], exec
	s_mul_i32 s25, s69, 0x12000
	s_waitcnt vmcnt(2)
	v_add_u32_e32 v80, s16, v108
	v_readlane_b32 s28, v250, 25
	v_add_u32_e32 v60, 0xffffe000, v80
	s_cselect_b32 s24, 3, s26
	v_readlane_b32 s29, v250, 26
	s_add_u32 s25, s28, s25
	v_or_b32_e32 v70, v80, v107
	v_lshlrev_b32_e32 v114, 6, v102
	v_readlane_b32 s16, v251, 6
	v_lshrrev_b32_e32 v60, 10, v60
	s_movk_i32 s5, 0x1800
	s_addc_u32 s26, s29, 0
	v_or_b32_e32 v81, s16, v114
	v_lshlrev_b32_e32 v115, 2, v97
	v_mad_u32_u24 v60, v60, s5, s5
	v_cmp_lt_i32_e32 vcc, s13, v70
	s_add_u32 s40, s25, 0x5000
	v_or_b32_e32 v64, v81, v115
	v_cndmask_b32_e32 v76, 0, v60, vcc
	s_addc_u32 s41, s26, 0
	v_ashrrev_i32_e32 v77, 31, v76
	v_ashrrev_i32_e32 v65, 31, v64
	v_ashrrev_i32_e32 v71, 31, v70
	v_lshl_add_u64 v[60:61], v[76:77], 2, s[40:41]
	v_lshlrev_b64 v[66:67], 2, v[64:65]
	v_readlane_b32 s16, v250, 15
	v_lshl_add_u64 v[74:75], v[60:61], 0, v[66:67]
	v_lshlrev_b64 v[60:61], 12, v[70:71]
	v_readlane_b32 s17, v250, 16
	v_readlane_b32 s68, v250, 41
	s_mul_i32 s25, s24, 0x12000
	v_lshl_add_u64 v[60:61], s[16:17], 0, v[60:61]
	v_lshl_add_u64 v[72:73], v[60:61], 0, v[66:67]
	global_load_dwordx4 v[116:119], v[74:75], off
	global_load_dwordx4 v[120:123], v[74:75], off offset:64
	global_load_dwordx4 v[124:127], v[74:75], off offset:128
	global_load_dwordx4 v[132:135], v[74:75], off offset:192
	global_load_dwordx4 v[190:193], v[72:73], off
	global_load_dwordx4 v[194:197], v[72:73], off offset:64
	global_load_dwordx4 v[198:201], v[72:73], off offset:128
	global_load_dwordx4 v[202:205], v[72:73], off offset:192
	v_add_co_u32_e32 v164, vcc, 0x10000, v72
	s_nop 1
	v_addc_co_u32_e32 v165, vcc, 0, v73, vcc
	v_add_co_u32_e32 v222, vcc, 0x20000, v72
	s_nop 1
	v_addc_co_u32_e32 v223, vcc, 0, v73, vcc
	v_add_co_u32_e32 v224, vcc, 0x30000, v72
	s_nop 1
	v_addc_co_u32_e32 v225, vcc, 0, v73, vcc
	global_load_dwordx4 v[206:209], v[164:165], off
	global_load_dwordx4 v[210:213], v[164:165], off offset:64
	global_load_dwordx4 v[214:217], v[164:165], off offset:128
	global_load_dwordx4 v[218:221], v[164:165], off offset:192
	s_lshl_b32 s24, s24, 12
	v_readlane_b32 s70, v250, 43
	v_readlane_b32 s71, v250, 44
	s_add_u32 s26, s70, s24
	s_addc_u32 s27, s71, 0
	s_add_u32 s24, s28, s25
	s_addc_u32 s25, s29, 0
	s_add_u32 s42, s24, 0x1000
	v_cndmask_b32_e64 v68, 0, 1, s[2:3]
	s_addc_u32 s43, s25, 0
	s_andn2_b64 vcc, exec, s[2:3]
	v_readlane_b32 s2, v250, 21
	s_waitcnt vmcnt(3)
	v_lshlrev_b64 v[86:87], 10, v[70:71]
	v_readlane_b32 s3, v250, 22
	v_cmp_ne_u32_e64 s[36:37], 1, v68
	v_lshl_add_u64 v[68:69], s[26:27], 0, v[66:67]
	v_lshl_add_u64 v[78:79], v[76:77], 2, s[42:43]
	v_lshl_add_u64 v[76:77], v[86:87], 1, s[2:3]
	v_readlane_b32 s69, v250, 42
	v_readlane_b32 s72, v250, 45
	v_readlane_b32 s73, v250, 46
	v_readlane_b32 s74, v250, 47
	v_readlane_b32 s75, v250, 48
	v_readlane_b32 s76, v250, 49
	v_readlane_b32 s77, v250, 50
	v_readlane_b32 s78, v250, 51
	v_readlane_b32 s79, v250, 52
	v_readlane_b32 s80, v250, 53
	v_readlane_b32 s81, v250, 54
	v_readlane_b32 s82, v250, 55
	v_readlane_b32 s83, v250, 56
	global_load_dwordx4 v[136:139], v[68:69], off
	global_load_dwordx4 v[140:143], v[68:69], off offset:64
	global_load_dwordx4 v[144:147], v[68:69], off offset:128
	global_load_dwordx4 v[148:151], v[68:69], off offset:192
	s_waitcnt vmcnt(0)
	v_pk_fma_f32 v[62:63], v[94:95], v[118:119], v[192:193]
	v_pk_fma_f32 v[60:61], v[92:93], v[116:117], v[190:191]
	global_store_dwordx4 v[72:73], v[60:63], off
	s_cbranch_vccnz .LBB0_239
	v_lshl_add_u64 v[86:87], v[78:79], 0, v[66:67]
	s_waitcnt vmcnt(0)
	v_pk_mul_f32 v[84:85], v[62:63], v[138:139]
	global_load_dwordx4 v[152:155], v[86:87], off
	global_load_dwordx4 v[156:159], v[86:87], off offset:64
	global_load_dwordx4 v[160:163], v[86:87], off offset:128
	global_load_dwordx4 v[180:183], v[86:87], off offset:192
	v_pk_mul_f32 v[82:83], v[60:61], v[136:137]
	s_waitcnt vmcnt(0)
	v_pk_add_f32 v[88:89], v[154:155], 1.0 op_sel_hi:[1,0]
	v_pk_add_f32 v[86:87], v[152:153], 1.0 op_sel_hi:[1,0]
	v_pk_mul_f32 v[84:85], v[84:85], v[88:89]
	v_pk_mul_f32 v[82:83], v[82:83], v[86:87]
	v_and_b32_sdwa v88, v84, v170 dst_sel:DWORD dst_unused:UNUSED_PAD src0_sel:WORD_1 src1_sel:DWORD
	v_and_b32_sdwa v89, v82, v170 dst_sel:DWORD dst_unused:UNUSED_PAD src0_sel:WORD_1 src1_sel:DWORD
	v_add3_u32 v82, v82, v89, s56
	v_add3_u32 v84, v84, v88, s56
	v_and_b32_sdwa v88, v85, v170 dst_sel:DWORD dst_unused:UNUSED_PAD src0_sel:WORD_1 src1_sel:DWORD
	v_and_b32_sdwa v89, v83, v170 dst_sel:DWORD dst_unused:UNUSED_PAD src0_sel:WORD_1 src1_sel:DWORD
	v_add3_u32 v85, v85, v88, s56
	v_add3_u32 v83, v83, v89, s56
	v_and_b32_e32 v85, 0xffff0000, v85
	v_and_b32_e32 v88, 0xffff0000, v83
	v_lshl_add_u64 v[86:87], v[64:65], 1, v[76:77]
	v_or_b32_sdwa v83, v85, v84 dst_sel:DWORD dst_unused:UNUSED_PAD src0_sel:DWORD src1_sel:WORD_1
	v_or_b32_sdwa v82, v88, v82 dst_sel:DWORD dst_unused:UNUSED_PAD src0_sel:DWORD src1_sel:WORD_1
	global_store_dwordx2 v[86:87], v[82:83], off

.LBB0_247:
	s_or_b64 exec, exec, s[2:3]
	v_add_u32_e32 v50, 0xffffe010, v80
	v_or_b32_e32 v52, 16, v70
	v_lshrrev_b32_e32 v50, 10, v50
	s_movk_i32 s2, 0x1800
	v_mad_u32_u24 v50, v50, s2, s2
	v_cmp_lt_i32_e32 vcc, s13, v52
	v_ashrrev_i32_e32 v53, 31, v52
	v_readlane_b32 s2, v250, 15
	v_cndmask_b32_e32 v56, 0, v50, vcc
	v_ashrrev_i32_e32 v57, 31, v56
	s_waitcnt lgkmcnt(0)
	v_lshl_add_u64 v[50:51], v[56:57], 2, s[40:41]
	v_lshl_add_u64 v[54:55], v[50:51], 0, v[66:67]
	v_lshlrev_b64 v[50:51], 12, v[52:53]
	v_readlane_b32 s3, v250, 16
	v_lshlrev_b64 v[52:53], 10, v[52:53]
	s_and_b64 vcc, exec, s[36:37]
	v_lshl_add_u64 v[50:51], s[2:3], 0, v[50:51]
	v_lshl_add_u64 v[50:51], v[50:51], 0, v[66:67]
	v_readlane_b32 s2, v250, 21
	v_readlane_b32 s3, v250, 22
	v_lshl_add_u64 v[56:57], v[56:57], 2, s[42:43]
	global_load_dwordx4 v[190:193], v[222:223], off
	global_load_dwordx4 v[194:197], v[222:223], off offset:64
	global_load_dwordx4 v[198:201], v[222:223], off offset:128
	global_load_dwordx4 v[202:205], v[222:223], off offset:192
	s_waitcnt vmcnt(12)
	v_pk_fma_f32 v[46:47], v[46:47], v[118:119], v[208:209]
	v_pk_fma_f32 v[44:45], v[44:45], v[116:117], v[206:207]
	v_lshl_add_u64 v[52:53], v[52:53], 1, s[2:3]
	global_store_dwordx4 v[50:51], v[44:47], off
	s_cbranch_vccnz .LBB0_249
	v_lshl_add_u64 v[62:63], v[56:57], 0, v[66:67]
	v_pk_mul_f32 v[60:61], v[46:47], v[138:139]
	v_pk_mul_f32 v[58:59], v[44:45], v[136:137]
	v_pk_add_f32 v[62:63], v[154:155], 1.0 op_sel_hi:[1,0]
	v_pk_add_f32 v[72:73], v[152:153], 1.0 op_sel_hi:[1,0]
	v_pk_mul_f32 v[60:61], v[60:61], v[62:63]
	v_pk_mul_f32 v[58:59], v[58:59], v[72:73]
	v_and_b32_sdwa v71, v60, v170 dst_sel:DWORD dst_unused:UNUSED_PAD src0_sel:WORD_1 src1_sel:DWORD
	v_and_b32_sdwa v72, v58, v170 dst_sel:DWORD dst_unused:UNUSED_PAD src0_sel:WORD_1 src1_sel:DWORD
	v_add3_u32 v58, v58, v72, s56
	v_add3_u32 v60, v60, v71, s56
	v_and_b32_sdwa v71, v61, v170 dst_sel:DWORD dst_unused:UNUSED_PAD src0_sel:WORD_1 src1_sel:DWORD
	v_and_b32_sdwa v72, v59, v170 dst_sel:DWORD dst_unused:UNUSED_PAD src0_sel:WORD_1 src1_sel:DWORD
	v_add3_u32 v61, v61, v71, s56
	v_add3_u32 v59, v59, v72, s56
	v_and_b32_e32 v61, 0xffff0000, v61
	v_and_b32_e32 v71, 0xffff0000, v59
	v_lshl_add_u64 v[62:63], v[64:65], 1, v[52:53]
	v_or_b32_sdwa v59, v61, v60 dst_sel:DWORD dst_unused:UNUSED_PAD src0_sel:DWORD src1_sel:WORD_1
	v_or_b32_sdwa v58, v71, v58 dst_sel:DWORD dst_unused:UNUSED_PAD src0_sel:DWORD src1_sel:WORD_1
	global_store_dwordx2 v[62:63], v[58:59], off

.LBB0_327:
	s_add_i32 s0, s1, 2
	v_add_u32_e32 v127, v89, v90
	ds_read_b128 v[100:103], v127 offset:16384
	ds_read_b128 v[106:109], v127 offset:18432
	ds_read_b128 v[110:113], v127 offset:20480
	ds_read_b128 v[114:117], v127 offset:22528
	v_add_u32_e32 v126, v88, v90
	ds_read_b128 v[92:95], v126
	ds_read_b128 v[96:99], v126 offset:2048
	s_add_i32 s1, s1, 4
	s_min_u32 s1, s1, 63
	v_add_u32_e32 v128, v88, v91
	v_add_u32_e32 v130, v89, v91
	s_lshl_b32 s92, s1, 7
	ds_read_b128 v[118:121], v130 offset:18432
	ds_read_b128 v[122:125], v130 offset:20480
	ds_read_b128 v[132:135], v130 offset:22528
	s_waitcnt lgkmcnt(4)
	v_mfma_f32_16x16x32_bf16 v[76:79], v[100:103], v[92:95], v[76:79]
	v_lshl_add_u64 v[48:49], v[80:81], 0, s[92:93]
	v_add_co_u32_e32 v50, vcc, s7, v48
	v_mfma_f32_16x16x32_bf16 v[56:59], v[106:109], v[92:95], v[56:59]
	s_nop 0
	v_addc_co_u32_e32 v51, vcc, 0, v49, vcc
	v_mfma_f32_16x16x32_bf16 v[44:47], v[110:113], v[92:95], v[44:47]
	v_mfma_f32_16x16x32_bf16 v[24:27], v[114:117], v[92:95], v[24:27]
	s_waitcnt lgkmcnt(3)
	v_mfma_f32_16x16x32_bf16 v[92:95], v[100:103], v[96:99], v[12:15]
	s_nop 2
	ds_read_b128 v[12:15], v128
	v_mfma_f32_16x16x32_bf16 v[100:103], v[106:109], v[96:99], v[8:11]
	v_mfma_f32_16x16x32_bf16 v[106:109], v[110:113], v[96:99], v[4:7]
	ds_read_b128 v[110:113], v128 offset:2048
	v_mfma_f32_16x16x32_bf16 v[96:99], v[114:117], v[96:99], v[0:3]
	ds_read_b128 v[114:117], v130 offset:16384
	global_load_dwordx4 v[72:75], v[48:49], off
	s_waitcnt vmcnt(1)
	ds_write_b128 v87, v[16:19] offset:53248
	global_load_dwordx4 v[68:71], v[50:51], off
	v_add_co_u32_e32 v50, vcc, s52, v48
	ds_write_b128 v87, v[20:23] offset:49152
	s_nop 0
	v_addc_co_u32_e32 v51, vcc, 0, v49, vcc
	v_add_co_u32_e32 v48, vcc, s34, v48
	global_load_dwordx4 v[64:67], v[50:51], off
	s_nop 0
	v_addc_co_u32_e32 v49, vcc, 0, v49, vcc
	ds_write_b128 v87, v[28:31] offset:45056
	global_load_dwordx4 v[60:63], v[48:49], off
	v_lshl_add_u64 v[48:49], v[82:83], 0, s[92:93]
	ds_write_b128 v87, v[36:39] offset:32768
	s_waitcnt lgkmcnt(4)
	v_mfma_f32_16x16x32_bf16 v[0:3], v[114:117], v[12:15], v[76:79]
	v_mfma_f32_16x16x32_bf16 v[4:7], v[118:121], v[12:15], v[56:59]
	global_load_dwordx4 v[52:55], v[48:49], off
	v_add_co_u32_e32 v48, vcc, s7, v48
	ds_write_b128 v87, v[40:43] offset:36864
	s_nop 0
	v_addc_co_u32_e32 v49, vcc, 0, v49, vcc
	v_mfma_f32_16x16x32_bf16 v[8:11], v[122:125], v[12:15], v[44:47]
	v_mfma_f32_16x16x32_bf16 v[12:15], v[132:135], v[12:15], v[24:27]
	global_load_dwordx4 v[48:51], v[48:49], off
	ds_write_b128 v87, v[32:35] offset:40960
	v_mfma_f32_16x16x32_bf16 v[24:27], v[114:117], v[110:113], v[92:95]
	v_mfma_f32_16x16x32_bf16 v[44:47], v[118:121], v[110:113], v[100:103]
	v_mfma_f32_16x16x32_bf16 v[56:59], v[122:125], v[110:113], v[106:109]
	v_mfma_f32_16x16x32_bf16 v[76:79], v[132:135], v[110:113], v[96:99]
	s_waitcnt lgkmcnt(0)
	s_barrier
	ds_read_b128 v[100:103], v127 offset:49152
	ds_read_b128 v[106:109], v127 offset:51200
	ds_read_b128 v[110:113], v127 offset:53248
	ds_read_b128 v[114:117], v127 offset:55296
	ds_read_b128 v[92:95], v126 offset:32768
	ds_read_b128 v[96:99], v126 offset:34816
	s_min_u32 s1, s0, 60
	s_lshl_b32 s92, s1, 7
	ds_read_b128 v[118:121], v130 offset:51200
	ds_read_b128 v[122:125], v130 offset:53248
	ds_read_b128 v[132:135], v130 offset:55296
	s_waitcnt lgkmcnt(4)
	v_mfma_f32_16x16x32_bf16 v[0:3], v[100:103], v[92:95], v[0:3]
	v_lshl_add_u64 v[16:17], v[80:81], 0, s[92:93]
	v_add_co_u32_e32 v18, vcc, s7, v16
	v_mfma_f32_16x16x32_bf16 v[4:7], v[106:109], v[92:95], v[4:7]
	s_nop 0
	v_addc_co_u32_e32 v19, vcc, 0, v17, vcc
	v_mfma_f32_16x16x32_bf16 v[8:11], v[110:113], v[92:95], v[8:11]
	v_mfma_f32_16x16x32_bf16 v[12:15], v[114:117], v[92:95], v[12:15]
	s_waitcnt lgkmcnt(3)
	v_mfma_f32_16x16x32_bf16 v[92:95], v[100:103], v[96:99], v[24:27]
	s_nop 2
	ds_read_b128 v[24:27], v128 offset:32768
	v_mfma_f32_16x16x32_bf16 v[100:103], v[106:109], v[96:99], v[44:47]
	v_mfma_f32_16x16x32_bf16 v[106:109], v[110:113], v[96:99], v[56:59]
	ds_read_b128 v[110:113], v128 offset:34816
	v_mfma_f32_16x16x32_bf16 v[96:99], v[114:117], v[96:99], v[76:79]
	ds_read_b128 v[114:117], v130 offset:49152
	global_load_dwordx4 v[36:39], v[16:17], off offset:384
	s_waitcnt vmcnt(1)
	ds_write_b128 v87, v[48:51] offset:20480
	global_load_dwordx4 v[40:43], v[18:19], off offset:384
	v_add_co_u32_e32 v18, vcc, s52, v16
	ds_write_b128 v87, v[52:55] offset:16384
	s_nop 0
	v_addc_co_u32_e32 v19, vcc, 0, v17, vcc
	v_add_co_u32_e32 v16, vcc, s34, v16
	global_load_dwordx4 v[32:35], v[18:19], off offset:384
	s_nop 0
	v_addc_co_u32_e32 v17, vcc, 0, v17, vcc
	ds_write_b128 v87, v[60:63] offset:12288
	global_load_dwordx4 v[28:31], v[16:17], off offset:384
	v_lshl_add_u64 v[16:17], v[82:83], 0, s[92:93]
	ds_write_b128 v87, v[72:75]
	s_waitcnt lgkmcnt(4)
	v_mfma_f32_16x16x32_bf16 v[76:79], v[114:117], v[24:27], v[0:3]
	v_mfma_f32_16x16x32_bf16 v[56:59], v[118:121], v[24:27], v[4:7]
	global_load_dwordx4 v[20:23], v[16:17], off offset:384
	v_add_co_u32_e32 v16, vcc, s7, v16
	ds_write_b128 v87, v[68:71] offset:4096
	s_nop 0
	v_addc_co_u32_e32 v17, vcc, 0, v17, vcc
	v_mfma_f32_16x16x32_bf16 v[44:47], v[122:125], v[24:27], v[8:11]
	v_mfma_f32_16x16x32_bf16 v[24:27], v[132:135], v[24:27], v[12:15]
	global_load_dwordx4 v[16:19], v[16:17], off offset:384
	ds_write_b128 v87, v[64:67] offset:8192
	v_mfma_f32_16x16x32_bf16 v[12:15], v[114:117], v[110:113], v[92:95]
	v_mfma_f32_16x16x32_bf16 v[8:11], v[118:121], v[110:113], v[100:103]
	v_mfma_f32_16x16x32_bf16 v[4:7], v[122:125], v[110:113], v[106:109]
	v_mfma_f32_16x16x32_bf16 v[0:3], v[132:135], v[110:113], v[96:99]
	s_cmp_lt_u32 s0, 62
	s_mov_b32 s1, s0
	s_waitcnt lgkmcnt(0)
	s_barrier
	s_cbranch_scc1 .LBB0_327
	v_readlane_b32 s0, v251, 18
	s_nop 1
	v_add_u32_e32 v48, s0, v86
	v_readlane_b32 s0, v251, 19
	s_waitcnt vmcnt(0)
	v_add_u32_e32 v16, 0xffffe000, v48
	v_or_b32_e32 v34, v48, v85
	v_lshl_or_b32 v32, v84, 2, s0
	v_lshrrev_b32_e32 v16, 10, v16
	s_movk_i32 s0, 0x1800
	v_mad_u32_u24 v16, v16, s0, s0
	v_cmp_lt_i32_e32 vcc, s13, v34
	v_ashrrev_i32_e32 v35, 31, v34
	v_lshlrev_b32_e32 v128, 2, v32
	v_cndmask_b32_e32 v28, 0, v16, vcc
	v_ashrrev_i32_e32 v29, 31, v28
	v_lshl_add_u64 v[16:17], v[28:29], 2, s[40:41]
	v_readlane_b32 s0, v250, 15
	v_lshl_add_u64 v[40:41], v[16:17], 0, v[128:129]
	v_lshlrev_b64 v[16:17], 12, v[34:35]
	v_readlane_b32 s1, v250, 16
	v_lshlrev_b64 v[30:31], 10, v[34:35]
	s_and_b64 vcc, exec, s[36:37]
	v_lshl_add_u64 v[16:17], s[0:1], 0, v[16:17]
	v_lshl_add_u64 v[38:39], v[16:17], 0, v[128:129]
	global_load_dwordx4 v[60:63], v[40:41], off
	global_load_dwordx4 v[72:75], v[40:41], off offset:64
	global_load_dwordx4 v[80:83], v[40:41], off offset:128
	global_load_dwordx4 v[88:91], v[40:41], off offset:192
	global_load_dwordx4 v[190:193], v[38:39], off
	global_load_dwordx4 v[194:197], v[38:39], off offset:64
	global_load_dwordx4 v[198:201], v[38:39], off offset:128
	global_load_dwordx4 v[202:205], v[38:39], off offset:192
	v_add_co_u32_e32 v54, vcc, 0x10000, v38
	s_nop 1
	v_addc_co_u32_e32 v55, vcc, 0, v39, vcc
	global_load_dwordx4 v[206:209], v[54:55], off
	global_load_dwordx4 v[210:213], v[54:55], off offset:64
	global_load_dwordx4 v[214:217], v[54:55], off offset:128
	global_load_dwordx4 v[218:221], v[54:55], off offset:192
	v_readlane_b32 s0, v250, 21
	v_readlane_b32 s1, v250, 22
	v_lshl_add_u64 v[42:43], v[28:29], 2, s[42:43]
	v_lshlrev_b32_e32 v32, 1, v32
	v_lshl_add_u64 v[36:37], v[30:31], 1, s[0:1]
	global_load_dwordx4 v[136:139], v128, s[26:27]
	global_load_dwordx4 v[140:143], v128, s[26:27] offset:64
	global_load_dwordx4 v[144:147], v128, s[26:27] offset:128
	global_load_dwordx4 v[148:151], v128, s[26:27] offset:192
	s_waitcnt vmcnt(0)
	v_pk_fma_f32 v[18:19], v[78:79], v[62:63], v[192:193]
	v_pk_fma_f32 v[16:17], v[76:77], v[60:61], v[190:191]
	global_store_dwordx4 v[38:39], v[16:19], off
	s_cbranch_vccnz .LBB0_330
	v_lshl_add_u64 v[28:29], v[42:43], 0, v[128:129]
	v_mov_b32_e32 v33, v129
	global_load_dwordx4 v[152:155], v[28:29], off
	global_load_dwordx4 v[156:159], v[28:29], off offset:64
	global_load_dwordx4 v[160:163], v[28:29], off offset:128
	global_load_dwordx4 v[180:183], v[28:29], off offset:192
	s_waitcnt vmcnt(0)
	v_pk_mul_f32 v[22:23], v[18:19], v[138:139]
	v_pk_mul_f32 v[20:21], v[16:17], v[136:137]
	s_waitcnt vmcnt(0)
	v_pk_add_f32 v[30:31], v[154:155], 1.0 op_sel_hi:[1,0]
	v_pk_add_f32 v[28:29], v[152:153], 1.0 op_sel_hi:[1,0]
	v_pk_mul_f32 v[22:23], v[22:23], v[30:31]
	v_pk_mul_f32 v[20:21], v[20:21], v[28:29]
	v_and_b32_sdwa v30, v22, v170 dst_sel:DWORD dst_unused:UNUSED_PAD src0_sel:WORD_1 src1_sel:DWORD
	v_and_b32_sdwa v31, v20, v170 dst_sel:DWORD dst_unused:UNUSED_PAD src0_sel:WORD_1 src1_sel:DWORD
	v_add3_u32 v20, v20, v31, s56
	v_add3_u32 v22, v22, v30, s56
	v_and_b32_sdwa v30, v23, v170 dst_sel:DWORD dst_unused:UNUSED_PAD src0_sel:WORD_1 src1_sel:DWORD
	v_and_b32_sdwa v31, v21, v170 dst_sel:DWORD dst_unused:UNUSED_PAD src0_sel:WORD_1 src1_sel:DWORD
	v_add3_u32 v23, v23, v30, s56
	v_add3_u32 v21, v21, v31, s56
	v_and_b32_e32 v23, 0xffff0000, v23
	v_and_b32_e32 v30, 0xffff0000, v21
	v_lshl_add_u64 v[28:29], v[36:37], 0, v[32:33]
	v_or_b32_sdwa v21, v23, v22 dst_sel:DWORD dst_unused:UNUSED_PAD src0_sel:DWORD src1_sel:WORD_1
	v_or_b32_sdwa v20, v30, v20 dst_sel:DWORD dst_unused:UNUSED_PAD src0_sel:DWORD src1_sel:WORD_1
	global_store_dwordx2 v[28:29], v[20:21], off

.LBB0_338:
	s_or_b64 exec, exec, s[2:3]
	s_waitcnt lgkmcnt(0)
	v_add_u32_e32 v17, 0xffffe010, v48
	v_or_b32_e32 v16, 16, v34
	v_lshrrev_b32_e32 v17, 10, v17
	s_movk_i32 s2, 0x1800
	v_mad_u32_u24 v17, v17, s2, s2
	v_cmp_lt_i32_e32 vcc, s13, v16
	v_readlane_b32 s2, v250, 15
	v_readlane_b32 s3, v250, 16
	v_cndmask_b32_e32 v20, 0, v17, vcc
	v_ashrrev_i32_e32 v21, 31, v20
	v_ashrrev_i32_e32 v17, 31, v16
	v_lshl_add_u64 v[18:19], v[20:21], 2, s[40:41]
	v_lshl_add_u64 v[22:23], v[18:19], 0, v[128:129]
	v_lshlrev_b64 v[18:19], 12, v[16:17]
	v_lshl_add_u64 v[18:19], s[2:3], 0, v[18:19]
	v_lshl_add_u64 v[18:19], v[18:19], 0, v[128:129]
	v_readlane_b32 s2, v250, 21
	v_lshlrev_b64 v[30:31], 10, v[16:17]
	v_readlane_b32 s3, v250, 22
	s_and_b64 vcc, exec, s[36:37]
	v_lshl_add_u64 v[24:25], v[20:21], 2, s[42:43]
	v_lshl_add_u64 v[20:21], v[30:31], 1, s[2:3]
	s_waitcnt vmcnt(8)
	v_pk_fma_f32 v[14:15], v[14:15], v[62:63], v[208:209]
	v_pk_fma_f32 v[12:13], v[12:13], v[60:61], v[206:207]
	global_store_dwordx4 v[18:19], v[12:15], off
	s_cbranch_vccnz .LBB0_340
	v_lshl_add_u64 v[30:31], v[24:25], 0, v[128:129]
	v_mov_b32_e32 v33, v129
	v_pk_mul_f32 v[28:29], v[14:15], v[138:139]
	v_pk_mul_f32 v[26:27], v[12:13], v[136:137]
	v_pk_add_f32 v[30:31], v[154:155], 1.0 op_sel_hi:[1,0]
	v_pk_add_f32 v[34:35], v[152:153], 1.0 op_sel_hi:[1,0]
	v_pk_mul_f32 v[28:29], v[28:29], v[30:31]
	v_pk_mul_f32 v[26:27], v[26:27], v[34:35]
	v_lshl_add_u64 v[30:31], v[20:21], 0, v[32:33]
	v_and_b32_sdwa v33, v28, v170 dst_sel:DWORD dst_unused:UNUSED_PAD src0_sel:WORD_1 src1_sel:DWORD
	v_and_b32_sdwa v34, v26, v170 dst_sel:DWORD dst_unused:UNUSED_PAD src0_sel:WORD_1 src1_sel:DWORD
	v_add3_u32 v26, v26, v34, s56
	v_add3_u32 v28, v28, v33, s56
	v_and_b32_sdwa v33, v29, v170 dst_sel:DWORD dst_unused:UNUSED_PAD src0_sel:WORD_1 src1_sel:DWORD
	v_and_b32_sdwa v34, v27, v170 dst_sel:DWORD dst_unused:UNUSED_PAD src0_sel:WORD_1 src1_sel:DWORD
	v_add3_u32 v29, v29, v33, s56
	v_add3_u32 v27, v27, v34, s56
	v_and_b32_e32 v29, 0xffff0000, v29
	v_and_b32_e32 v33, 0xffff0000, v27
	v_or_b32_sdwa v27, v29, v28 dst_sel:DWORD dst_unused:UNUSED_PAD src0_sel:DWORD src1_sel:WORD_1
	v_or_b32_sdwa v26, v33, v26 dst_sel:DWORD dst_unused:UNUSED_PAD src0_sel:DWORD src1_sel:WORD_1
	global_store_dwordx2 v[30:31], v[26:27], off

.LBB0_359:
	s_add_i32 s27, s28, 2
	v_add_u32_e32 v181, v144, v145
	ds_read_b128 v[80:83], v181 offset:16384
	ds_read_b128 v[84:87], v181 offset:18432
	ds_read_b128 v[88:91], v181 offset:20480
	ds_read_b128 v[92:95], v181 offset:22528
	v_add_u32_e32 v180, v143, v145
	ds_read_b128 v[64:67], v180
	s_add_i32 s28, s28, 4
	ds_read_b128 v[68:71], v180 offset:2048
	s_min_u32 s28, s28, 15
	s_lshl_b32 s92, s28, 7
	ds_read_b128 v[72:75], v180 offset:4096
	ds_read_b128 v[76:79], v180 offset:6144
	v_add_u32_e32 v182, v143, v146
	v_add_u32_e32 v186, v144, v146
	v_lshl_add_u64 v[224:225], v[138:139], 0, s[92:93]
	ds_read_b128 v[192:195], v182
	ds_read_b128 v[196:199], v182 offset:2048
	ds_read_b128 v[200:203], v182 offset:4096
	ds_read_b128 v[204:207], v182 offset:6144
	ds_read_b128 v[208:211], v186 offset:16384
	ds_read_b128 v[212:215], v186 offset:18432
	ds_read_b128 v[216:219], v186 offset:20480
	ds_read_b128 v[220:223], v186 offset:22528
	s_waitcnt lgkmcnt(11)
	v_mfma_f32_16x16x32_bf16 v[60:63], v[80:83], v[64:67], v[60:63]
	v_mfma_f32_16x16x32_bf16 v[56:59], v[84:87], v[64:67], v[56:59]
	v_mfma_f32_16x16x32_bf16 v[52:55], v[88:91], v[64:67], v[52:55]
	v_mfma_f32_16x16x32_bf16 v[48:51], v[92:95], v[64:67], v[48:51]
	global_load_dwordx4 v[64:67], v[224:225], off
	s_waitcnt vmcnt(6)
	ds_write_b128 v156, v[96:99] offset:32768
	v_add_co_u32_e32 v96, vcc, s11, v224
	s_waitcnt lgkmcnt(11)
	v_mfma_f32_16x16x32_bf16 v[44:47], v[80:83], v[68:71], v[44:47]
	v_addc_co_u32_e32 v97, vcc, 0, v225, vcc
	v_mfma_f32_16x16x32_bf16 v[40:43], v[84:87], v[68:71], v[40:43]
	v_mfma_f32_16x16x32_bf16 v[36:39], v[88:91], v[68:71], v[36:39]
	v_mfma_f32_16x16x32_bf16 v[32:35], v[92:95], v[68:71], v[32:35]
	global_load_dwordx4 v[68:71], v[96:97], off
	v_add_co_u32_e32 v96, vcc, s33, v224
	ds_write_b128 v156, v[100:103] offset:36864
	s_nop 0
	v_addc_co_u32_e32 v97, vcc, 0, v225, vcc
	s_waitcnt lgkmcnt(11)
	v_mfma_f32_16x16x32_bf16 v[28:31], v[80:83], v[72:75], v[28:31]
	v_mfma_f32_16x16x32_bf16 v[24:27], v[84:87], v[72:75], v[24:27]
	v_mfma_f32_16x16x32_bf16 v[20:23], v[88:91], v[72:75], v[20:23]
	v_mfma_f32_16x16x32_bf16 v[16:19], v[92:95], v[72:75], v[16:19]
	global_load_dwordx4 v[72:75], v[96:97], off
	ds_write_b128 v156, v[104:107] offset:40960
	s_waitcnt lgkmcnt(11)
	v_mfma_f32_16x16x32_bf16 v[12:15], v[80:83], v[76:79], v[12:15]
	v_add_co_u32_e32 v80, vcc, s59, v224
	v_mfma_f32_16x16x32_bf16 v[0:3], v[92:95], v[76:79], v[0:3]
	s_nop 0
	v_addc_co_u32_e32 v81, vcc, 0, v225, vcc
	v_lshl_add_u64 v[92:93], v[140:141], 0, s[92:93]
	v_mfma_f32_16x16x32_bf16 v[8:11], v[84:87], v[76:79], v[8:11]
	v_add_co_u32_e32 v84, vcc, s11, v92
	s_nop 1
	v_addc_co_u32_e32 v85, vcc, 0, v93, vcc
	v_mfma_f32_16x16x32_bf16 v[4:7], v[88:91], v[76:79], v[4:7]
	v_add_co_u32_e32 v88, vcc, s33, v92
	global_load_dwordx4 v[76:79], v[80:81], off
	s_nop 0
	v_addc_co_u32_e32 v89, vcc, 0, v93, vcc
	s_waitcnt vmcnt(7)
	ds_write_b128 v156, v[112:115] offset:45056
	s_waitcnt lgkmcnt(7)
	v_mfma_f32_16x16x32_bf16 v[60:63], v[208:211], v[192:195], v[60:63]
	s_waitcnt lgkmcnt(6)
	v_mfma_f32_16x16x32_bf16 v[56:59], v[212:215], v[192:195], v[56:59]
	s_waitcnt lgkmcnt(5)
	v_mfma_f32_16x16x32_bf16 v[52:55], v[216:219], v[192:195], v[52:55]
	s_waitcnt lgkmcnt(4)
	v_mfma_f32_16x16x32_bf16 v[48:51], v[220:223], v[192:195], v[48:51]
	global_load_dwordx4 v[80:83], v[92:93], off
	v_add_co_u32_e32 v92, vcc, s59, v92
	ds_write_b128 v156, v[108:111] offset:49152
	s_nop 0
	v_addc_co_u32_e32 v93, vcc, 0, v93, vcc
	v_mfma_f32_16x16x32_bf16 v[44:47], v[208:211], v[196:199], v[44:47]
	v_mfma_f32_16x16x32_bf16 v[40:43], v[212:215], v[196:199], v[40:43]
	v_mfma_f32_16x16x32_bf16 v[36:39], v[216:219], v[196:199], v[36:39]
	v_mfma_f32_16x16x32_bf16 v[32:35], v[220:223], v[196:199], v[32:35]
	global_load_dwordx4 v[84:87], v[84:85], off
	s_waitcnt vmcnt(8)
	ds_write_b128 v156, v[116:119] offset:53248
	v_mfma_f32_16x16x32_bf16 v[28:31], v[208:211], v[200:203], v[28:31]
	v_mfma_f32_16x16x32_bf16 v[24:27], v[212:215], v[200:203], v[24:27]
	v_mfma_f32_16x16x32_bf16 v[20:23], v[216:219], v[200:203], v[20:23]
	v_mfma_f32_16x16x32_bf16 v[16:19], v[220:223], v[200:203], v[16:19]
	global_load_dwordx4 v[88:91], v[88:89], off
	s_waitcnt vmcnt(8)
	ds_write_b128 v156, v[120:123] offset:57344
	v_mfma_f32_16x16x32_bf16 v[12:15], v[208:211], v[204:207], v[12:15]
	v_mfma_f32_16x16x32_bf16 v[8:11], v[212:215], v[204:207], v[8:11]
	v_mfma_f32_16x16x32_bf16 v[4:7], v[216:219], v[204:207], v[4:7]
	v_mfma_f32_16x16x32_bf16 v[0:3], v[220:223], v[204:207], v[0:3]
	global_load_dwordx4 v[92:95], v[92:93], off
	s_waitcnt vmcnt(8)
	ds_write_b128 v156, v[124:127] offset:61440
	s_waitcnt lgkmcnt(0)
	s_barrier
	ds_read_b128 v[112:115], v181 offset:49152
	ds_read_b128 v[116:119], v181 offset:51200
	ds_read_b128 v[120:123], v181 offset:53248
	ds_read_b128 v[124:127], v181 offset:55296
	ds_read_b128 v[96:99], v180 offset:32768
	ds_read_b128 v[100:103], v180 offset:34816
	s_min_u32 s28, s27, 12
	s_lshl_b32 s92, s28, 7
	ds_read_b128 v[104:107], v180 offset:36864
	v_lshl_add_u64 v[224:225], v[138:139], 0, s[92:93]
	ds_read_b128 v[108:111], v180 offset:38912
	ds_read_b128 v[192:195], v182 offset:32768
	ds_read_b128 v[196:199], v182 offset:34816
	ds_read_b128 v[200:203], v182 offset:36864
	ds_read_b128 v[204:207], v182 offset:38912
	ds_read_b128 v[208:211], v186 offset:49152
	ds_read_b128 v[212:215], v186 offset:51200
	ds_read_b128 v[216:219], v186 offset:53248
	ds_read_b128 v[220:223], v186 offset:55296
	s_waitcnt lgkmcnt(11)
	v_mfma_f32_16x16x32_bf16 v[60:63], v[112:115], v[96:99], v[60:63]
	v_mfma_f32_16x16x32_bf16 v[56:59], v[116:119], v[96:99], v[56:59]
	v_mfma_f32_16x16x32_bf16 v[52:55], v[120:123], v[96:99], v[52:55]
	v_mfma_f32_16x16x32_bf16 v[48:51], v[124:127], v[96:99], v[48:51]
	global_load_dwordx4 v[96:99], v[224:225], off offset:384
	s_waitcnt vmcnt(8)
	ds_write_b128 v156, v[64:67]
	v_add_co_u32_e32 v64, vcc, s11, v224
	s_waitcnt lgkmcnt(11)
	v_mfma_f32_16x16x32_bf16 v[44:47], v[112:115], v[100:103], v[44:47]
	v_addc_co_u32_e32 v65, vcc, 0, v225, vcc
	v_mfma_f32_16x16x32_bf16 v[40:43], v[116:119], v[100:103], v[40:43]
	v_mfma_f32_16x16x32_bf16 v[36:39], v[120:123], v[100:103], v[36:39]
	v_mfma_f32_16x16x32_bf16 v[32:35], v[124:127], v[100:103], v[32:35]
	global_load_dwordx4 v[100:103], v[64:65], off offset:384
	v_add_co_u32_e32 v64, vcc, s33, v224
	s_waitcnt vmcnt(8)
	ds_write_b128 v156, v[68:71] offset:4096
	v_addc_co_u32_e32 v65, vcc, 0, v225, vcc
	s_waitcnt lgkmcnt(11)
	v_mfma_f32_16x16x32_bf16 v[28:31], v[112:115], v[104:107], v[28:31]
	v_mfma_f32_16x16x32_bf16 v[24:27], v[116:119], v[104:107], v[24:27]
	v_mfma_f32_16x16x32_bf16 v[20:23], v[120:123], v[104:107], v[20:23]
	v_mfma_f32_16x16x32_bf16 v[16:19], v[124:127], v[104:107], v[16:19]
	global_load_dwordx4 v[104:107], v[64:65], off offset:384
	v_add_co_u32_e32 v64, vcc, s59, v224
	s_waitcnt vmcnt(8)
	ds_write_b128 v156, v[72:75] offset:8192
	v_addc_co_u32_e32 v65, vcc, 0, v225, vcc
	s_waitcnt lgkmcnt(11)
	v_mfma_f32_16x16x32_bf16 v[12:15], v[112:115], v[108:111], v[12:15]
	v_mfma_f32_16x16x32_bf16 v[8:11], v[116:119], v[108:111], v[8:11]
	v_mfma_f32_16x16x32_bf16 v[4:7], v[120:123], v[108:111], v[4:7]
	v_mfma_f32_16x16x32_bf16 v[0:3], v[124:127], v[108:111], v[0:3]
	global_load_dwordx4 v[112:115], v[64:65], off offset:384
	v_lshl_add_u64 v[64:65], v[140:141], 0, s[92:93]
	v_add_co_u32_e32 v66, vcc, s11, v64
	s_waitcnt vmcnt(8)
	ds_write_b128 v156, v[76:79] offset:12288
	v_addc_co_u32_e32 v67, vcc, 0, v65, vcc
	s_waitcnt lgkmcnt(7)
	v_mfma_f32_16x16x32_bf16 v[60:63], v[208:211], v[192:195], v[60:63]
	s_waitcnt lgkmcnt(6)
	v_mfma_f32_16x16x32_bf16 v[56:59], v[212:215], v[192:195], v[56:59]
	s_waitcnt lgkmcnt(5)
	v_mfma_f32_16x16x32_bf16 v[52:55], v[216:219], v[192:195], v[52:55]
	s_waitcnt lgkmcnt(4)
	v_mfma_f32_16x16x32_bf16 v[48:51], v[220:223], v[192:195], v[48:51]
	global_load_dwordx4 v[108:111], v[64:65], off offset:384
	s_waitcnt vmcnt(8)
	ds_write_b128 v156, v[80:83] offset:16384
	v_mfma_f32_16x16x32_bf16 v[44:47], v[208:211], v[196:199], v[44:47]
	v_mfma_f32_16x16x32_bf16 v[40:43], v[212:215], v[196:199], v[40:43]
	v_mfma_f32_16x16x32_bf16 v[36:39], v[216:219], v[196:199], v[36:39]
	v_mfma_f32_16x16x32_bf16 v[32:35], v[220:223], v[196:199], v[32:35]
	global_load_dwordx4 v[116:119], v[66:67], off offset:384
	v_add_co_u32_e32 v66, vcc, s33, v64
	s_waitcnt vmcnt(8)
	ds_write_b128 v156, v[84:87] offset:20480
	v_addc_co_u32_e32 v67, vcc, 0, v65, vcc
	v_add_co_u32_e32 v64, vcc, s59, v64
	v_mfma_f32_16x16x32_bf16 v[28:31], v[208:211], v[200:203], v[28:31]
	s_nop 0
	v_addc_co_u32_e32 v65, vcc, 0, v65, vcc
	v_mfma_f32_16x16x32_bf16 v[24:27], v[212:215], v[200:203], v[24:27]
	v_mfma_f32_16x16x32_bf16 v[20:23], v[216:219], v[200:203], v[20:23]
	v_mfma_f32_16x16x32_bf16 v[16:19], v[220:223], v[200:203], v[16:19]
	global_load_dwordx4 v[120:123], v[66:67], off offset:384
	s_waitcnt vmcnt(8)
	ds_write_b128 v156, v[88:91] offset:24576
	v_mfma_f32_16x16x32_bf16 v[12:15], v[208:211], v[204:207], v[12:15]
	v_mfma_f32_16x16x32_bf16 v[8:11], v[212:215], v[204:207], v[8:11]
	v_mfma_f32_16x16x32_bf16 v[4:7], v[216:219], v[204:207], v[4:7]
	v_mfma_f32_16x16x32_bf16 v[0:3], v[220:223], v[204:207], v[0:3]
	global_load_dwordx4 v[124:127], v[64:65], off offset:384
	s_waitcnt vmcnt(8)
	ds_write_b128 v156, v[92:95] offset:28672
	s_cmp_gt_u32 s27, 13
	s_mov_b32 s28, s27
	s_waitcnt lgkmcnt(0)
	s_barrier
	s_cbranch_scc0 .LBB0_359
	s_and_saveexec_b64 s[28:29], s[36:37]
	s_cbranch_execz .LBB0_353
	v_add_f32_e32 v64, 0, v128
	v_add_f32_e32 v64, v64, v157
	v_add_f32_e32 v64, v64, v158
	v_add_f32_e32 v64, v64, v159
	v_add_f32_e32 v64, v64, v160
	v_add_f32_e32 v64, v64, v161
	v_add_f32_e32 v64, v64, v162
	v_add_f32_e32 v64, v64, v163
	v_add_f32_e32 v64, v64, v164
	v_add_f32_e32 v64, v64, v165
	v_add_f32_e32 v64, v64, v168
	v_add_f32_e32 v64, v64, v175
	v_add_f32_e32 v64, v64, v179
	v_add_f32_e32 v64, v64, v183
	v_add_f32_e32 v64, v64, v190
	v_add_f32_e32 v64, v64, v191
	v_fmamk_f32 v64, v64, 0x3a800000, v167
	s_mov_b32 s16, 0x800000
	v_mul_f32_e32 v65, 0x4b800000, v64
	v_cmp_gt_f32_e32 vcc, s16, v64
	s_nop 1
	v_cndmask_b32_e32 v64, v64, v65, vcc
	v_rsq_f32_e32 v64, v64
	s_nop 0
	v_mul_f32_e32 v65, 0x45800000, v64
	v_cndmask_b32_e32 v64, v64, v65, vcc
	ds_write_b32 v155, v64
	s_branch .LBB0_353

.LBB0_372:
	s_add_i32 s3, s24, 2
	v_add_u32_e32 v180, v142, v144
	ds_read_b128 v[44:47], v180
	ds_read_b128 v[48:51], v180 offset:2048
	v_add_u32_e32 v181, v143, v144
	ds_read_b128 v[52:55], v180 offset:4096
	ds_read_b128 v[56:59], v180 offset:6144
	ds_read_b128 v[60:63], v181 offset:16384
	ds_read_b128 v[68:71], v181 offset:18432
	ds_read_b128 v[72:75], v181 offset:20480
	ds_read_b128 v[76:79], v181 offset:22528
	v_add_u32_e32 v182, v142, v145
	s_add_i32 s24, s24, 4
	ds_read_b128 v[192:195], v182
	s_min_u32 s24, s24, 15
	s_lshl_b32 s92, s24, 7
	v_add_u32_e32 v186, v143, v145
	v_lshl_add_u64 v[224:225], v[138:139], 0, s[92:93]
	ds_read_b128 v[196:199], v182 offset:2048
	ds_read_b128 v[200:203], v182 offset:4096
	ds_read_b128 v[204:207], v182 offset:6144
	ds_read_b128 v[208:211], v186 offset:16384
	ds_read_b128 v[212:215], v186 offset:18432
	ds_read_b128 v[216:219], v186 offset:20480
	ds_read_b128 v[220:223], v186 offset:22528
	s_waitcnt lgkmcnt(11)
	v_mfma_f32_16x16x32_bf16 v[92:95], v[44:47], v[60:63], v[92:95]
	s_waitcnt lgkmcnt(10)
	v_mfma_f32_16x16x32_bf16 v[88:91], v[44:47], v[68:71], v[88:91]
	s_waitcnt lgkmcnt(9)
	v_mfma_f32_16x16x32_bf16 v[84:87], v[44:47], v[72:75], v[84:87]
	s_waitcnt lgkmcnt(8)
	v_mfma_f32_16x16x32_bf16 v[44:47], v[44:47], v[76:79], v[80:83]
	s_nop 2
	global_load_dwordx4 v[80:83], v[224:225], off
	s_waitcnt vmcnt(6)
	ds_write_b128 v156, v[96:99] offset:32768
	v_add_co_u32_e32 v96, vcc, s11, v224
	v_mfma_f32_16x16x32_bf16 v[64:67], v[48:51], v[60:63], v[64:67]
	s_nop 0
	v_addc_co_u32_e32 v97, vcc, 0, v225, vcc
	v_mfma_f32_16x16x32_bf16 v[40:43], v[48:51], v[68:71], v[40:43]
	v_mfma_f32_16x16x32_bf16 v[36:39], v[48:51], v[72:75], v[36:39]
	v_mfma_f32_16x16x32_bf16 v[32:35], v[48:51], v[76:79], v[32:35]
	global_load_dwordx4 v[48:51], v[96:97], off
	v_add_co_u32_e32 v96, vcc, s33, v224
	ds_write_b128 v156, v[100:103] offset:36864
	s_nop 0
	v_addc_co_u32_e32 v97, vcc, 0, v225, vcc
	v_mfma_f32_16x16x32_bf16 v[28:31], v[52:55], v[60:63], v[28:31]
	v_mfma_f32_16x16x32_bf16 v[24:27], v[52:55], v[68:71], v[24:27]
	v_mfma_f32_16x16x32_bf16 v[20:23], v[52:55], v[72:75], v[20:23]
	v_mfma_f32_16x16x32_bf16 v[16:19], v[52:55], v[76:79], v[16:19]
	global_load_dwordx4 v[52:55], v[96:97], off
	ds_write_b128 v156, v[104:107] offset:40960
	v_mfma_f32_16x16x32_bf16 v[12:15], v[56:59], v[60:63], v[12:15]
	v_add_co_u32_e32 v60, vcc, s59, v224
	s_nop 1
	v_addc_co_u32_e32 v61, vcc, 0, v225, vcc
	v_mfma_f32_16x16x32_bf16 v[8:11], v[56:59], v[68:71], v[8:11]
	v_mfma_f32_16x16x32_bf16 v[4:7], v[56:59], v[72:75], v[4:7]
	v_mfma_f32_16x16x32_bf16 v[0:3], v[56:59], v[76:79], v[0:3]
	global_load_dwordx4 v[56:59], v[60:61], off
	s_waitcnt vmcnt(7)
	ds_write_b128 v156, v[112:115] offset:45056
	s_waitcnt lgkmcnt(5)
	v_mfma_f32_16x16x32_bf16 v[72:75], v[192:195], v[216:219], v[84:87]
	s_nop 2
	v_lshl_add_u64 v[84:85], v[140:141], 0, s[92:93]
	v_add_co_u32_e32 v86, vcc, s11, v84
	v_mfma_f32_16x16x32_bf16 v[60:63], v[192:195], v[208:211], v[92:95]
	s_nop 0
	v_addc_co_u32_e32 v87, vcc, 0, v85, vcc
	v_mfma_f32_16x16x32_bf16 v[68:71], v[192:195], v[212:215], v[88:91]
	s_waitcnt lgkmcnt(4)
	v_mfma_f32_16x16x32_bf16 v[44:47], v[192:195], v[220:223], v[44:47]
	global_load_dwordx4 v[76:79], v[84:85], off
	ds_write_b128 v156, v[108:111] offset:49152
	v_mfma_f32_16x16x32_bf16 v[64:67], v[196:199], v[208:211], v[64:67]
	v_mfma_f32_16x16x32_bf16 v[40:43], v[196:199], v[212:215], v[40:43]
	v_mfma_f32_16x16x32_bf16 v[36:39], v[196:199], v[216:219], v[36:39]
	v_mfma_f32_16x16x32_bf16 v[32:35], v[196:199], v[220:223], v[32:35]
	global_load_dwordx4 v[192:195], v[86:87], off
	v_add_co_u32_e32 v86, vcc, s33, v84
	s_waitcnt vmcnt(8)
	ds_write_b128 v156, v[116:119] offset:53248
	v_addc_co_u32_e32 v87, vcc, 0, v85, vcc
	v_add_co_u32_e32 v84, vcc, s59, v84
	v_mfma_f32_16x16x32_bf16 v[28:31], v[200:203], v[208:211], v[28:31]
	s_nop 0
	v_addc_co_u32_e32 v85, vcc, 0, v85, vcc
	v_mfma_f32_16x16x32_bf16 v[24:27], v[200:203], v[212:215], v[24:27]
	v_mfma_f32_16x16x32_bf16 v[20:23], v[200:203], v[216:219], v[20:23]
	v_mfma_f32_16x16x32_bf16 v[16:19], v[200:203], v[220:223], v[16:19]
	global_load_dwordx4 v[196:199], v[86:87], off
	s_waitcnt vmcnt(8)
	ds_write_b128 v156, v[120:123] offset:57344
	v_mfma_f32_16x16x32_bf16 v[12:15], v[204:207], v[208:211], v[12:15]
	v_mfma_f32_16x16x32_bf16 v[8:11], v[204:207], v[212:215], v[8:11]
	v_mfma_f32_16x16x32_bf16 v[4:7], v[204:207], v[216:219], v[4:7]
	v_mfma_f32_16x16x32_bf16 v[0:3], v[204:207], v[220:223], v[0:3]
	global_load_dwordx4 v[200:203], v[84:85], off
	s_waitcnt vmcnt(8)
	ds_write_b128 v156, v[124:127] offset:61440
	s_waitcnt lgkmcnt(0)
	s_barrier
	ds_read_b128 v[84:87], v180 offset:32768
	ds_read_b128 v[88:91], v180 offset:34816
	ds_read_b128 v[112:115], v181 offset:49152
	ds_read_b128 v[116:119], v181 offset:51200
	ds_read_b128 v[120:123], v181 offset:53248
	ds_read_b128 v[124:127], v181 offset:55296
	ds_read_b128 v[92:95], v180 offset:36864
	ds_read_b128 v[108:111], v180 offset:38912
	ds_read_b128 v[204:207], v182 offset:32768
	s_min_u32 s24, s3, 12
	s_lshl_b32 s92, s24, 7
	ds_read_b128 v[208:211], v182 offset:34816
	ds_read_b128 v[212:215], v182 offset:36864
	ds_read_b128 v[216:219], v182 offset:38912
	ds_read_b128 v[220:223], v186 offset:49152
	ds_read_b128 v[224:227], v186 offset:51200
	ds_read_b128 v[228:231], v186 offset:53248
	ds_read_b128 v[232:235], v186 offset:55296
	s_waitcnt lgkmcnt(13)
	v_mfma_f32_16x16x32_bf16 v[60:63], v[84:87], v[112:115], v[60:63]
	s_waitcnt lgkmcnt(12)
	v_mfma_f32_16x16x32_bf16 v[68:71], v[84:87], v[116:119], v[68:71]
	s_waitcnt lgkmcnt(11)
	v_mfma_f32_16x16x32_bf16 v[72:75], v[84:87], v[120:123], v[72:75]
	s_waitcnt lgkmcnt(10)
	v_mfma_f32_16x16x32_bf16 v[44:47], v[84:87], v[124:127], v[44:47]
	v_lshl_add_u64 v[84:85], v[138:139], 0, s[92:93]
	global_load_dwordx4 v[96:99], v[84:85], off offset:384
	s_waitcnt vmcnt(8)
	ds_write_b128 v156, v[80:83]
	v_add_co_u32_e32 v80, vcc, s11, v84
	v_mfma_f32_16x16x32_bf16 v[64:67], v[88:91], v[112:115], v[64:67]
	s_nop 0
	v_addc_co_u32_e32 v81, vcc, 0, v85, vcc
	v_mfma_f32_16x16x32_bf16 v[40:43], v[88:91], v[116:119], v[40:43]
	v_mfma_f32_16x16x32_bf16 v[36:39], v[88:91], v[120:123], v[36:39]
	v_mfma_f32_16x16x32_bf16 v[32:35], v[88:91], v[124:127], v[32:35]
	global_load_dwordx4 v[100:103], v[80:81], off offset:384
	s_waitcnt vmcnt(8)
	ds_write_b128 v156, v[48:51] offset:4096
	v_add_co_u32_e32 v48, vcc, s33, v84
	s_waitcnt lgkmcnt(11)
	v_mfma_f32_16x16x32_bf16 v[28:31], v[92:95], v[112:115], v[28:31]
	v_addc_co_u32_e32 v49, vcc, 0, v85, vcc
	v_mfma_f32_16x16x32_bf16 v[24:27], v[92:95], v[116:119], v[24:27]
	v_mfma_f32_16x16x32_bf16 v[20:23], v[92:95], v[120:123], v[20:23]
	v_mfma_f32_16x16x32_bf16 v[16:19], v[92:95], v[124:127], v[16:19]
	global_load_dwordx4 v[104:107], v[48:49], off offset:384
	v_add_co_u32_e32 v48, vcc, s59, v84
	s_waitcnt vmcnt(8)
	ds_write_b128 v156, v[52:55] offset:8192
	v_addc_co_u32_e32 v49, vcc, 0, v85, vcc
	s_waitcnt lgkmcnt(11)
	v_mfma_f32_16x16x32_bf16 v[12:15], v[108:111], v[112:115], v[12:15]
	v_mfma_f32_16x16x32_bf16 v[8:11], v[108:111], v[116:119], v[8:11]
	v_mfma_f32_16x16x32_bf16 v[4:7], v[108:111], v[120:123], v[4:7]
	v_mfma_f32_16x16x32_bf16 v[0:3], v[108:111], v[124:127], v[0:3]
	global_load_dwordx4 v[112:115], v[48:49], off offset:384
	s_waitcnt vmcnt(8)
	ds_write_b128 v156, v[56:59] offset:12288
	s_waitcnt lgkmcnt(4)
	v_mfma_f32_16x16x32_bf16 v[80:83], v[204:207], v[232:235], v[44:47]
	s_nop 2
	v_lshl_add_u64 v[44:45], v[140:141], 0, s[92:93]
	v_add_co_u32_e32 v46, vcc, s11, v44
	v_mfma_f32_16x16x32_bf16 v[92:95], v[204:207], v[220:223], v[60:63]
	s_nop 0
	v_addc_co_u32_e32 v47, vcc, 0, v45, vcc
	v_mfma_f32_16x16x32_bf16 v[88:91], v[204:207], v[224:227], v[68:71]
	v_mfma_f32_16x16x32_bf16 v[84:87], v[204:207], v[228:231], v[72:75]
	global_load_dwordx4 v[108:111], v[44:45], off offset:384
	s_waitcnt vmcnt(8)
	ds_write_b128 v156, v[76:79] offset:16384
	v_mfma_f32_16x16x32_bf16 v[64:67], v[208:211], v[220:223], v[64:67]
	v_mfma_f32_16x16x32_bf16 v[40:43], v[208:211], v[224:227], v[40:43]
	v_mfma_f32_16x16x32_bf16 v[36:39], v[208:211], v[228:231], v[36:39]
	v_mfma_f32_16x16x32_bf16 v[32:35], v[208:211], v[232:235], v[32:35]
	global_load_dwordx4 v[116:119], v[46:47], off offset:384
	v_add_co_u32_e32 v46, vcc, s33, v44
	s_waitcnt vmcnt(8)
	ds_write_b128 v156, v[192:195] offset:20480
	v_addc_co_u32_e32 v47, vcc, 0, v45, vcc
	v_add_co_u32_e32 v44, vcc, s59, v44
	v_mfma_f32_16x16x32_bf16 v[28:31], v[212:215], v[220:223], v[28:31]
	s_nop 0
	v_addc_co_u32_e32 v45, vcc, 0, v45, vcc
	v_mfma_f32_16x16x32_bf16 v[24:27], v[212:215], v[224:227], v[24:27]
	v_mfma_f32_16x16x32_bf16 v[20:23], v[212:215], v[228:231], v[20:23]
	v_mfma_f32_16x16x32_bf16 v[16:19], v[212:215], v[232:235], v[16:19]
	global_load_dwordx4 v[120:123], v[46:47], off offset:384
	s_waitcnt vmcnt(8)
	ds_write_b128 v156, v[196:199] offset:24576
	v_mfma_f32_16x16x32_bf16 v[12:15], v[216:219], v[220:223], v[12:15]
	v_mfma_f32_16x16x32_bf16 v[8:11], v[216:219], v[224:227], v[8:11]
	v_mfma_f32_16x16x32_bf16 v[4:7], v[216:219], v[228:231], v[4:7]
	v_mfma_f32_16x16x32_bf16 v[0:3], v[216:219], v[232:235], v[0:3]
	global_load_dwordx4 v[124:127], v[44:45], off offset:384
	s_waitcnt vmcnt(8)
	ds_write_b128 v156, v[200:203] offset:28672
	s_cmp_gt_u32 s3, 13
	s_mov_b32 s24, s3
	s_waitcnt lgkmcnt(0)
	s_barrier
	s_cbranch_scc0 .LBB0_372
	s_and_saveexec_b64 s[24:25], s[36:37]
	s_cbranch_execz .LBB0_366
	v_add_f32_e32 v44, 0, v128
	v_add_f32_e32 v44, v44, v157
	v_add_f32_e32 v44, v44, v158
	v_add_f32_e32 v44, v44, v159
	v_add_f32_e32 v44, v44, v160
	v_add_f32_e32 v44, v44, v161
	v_add_f32_e32 v44, v44, v162
	v_add_f32_e32 v44, v44, v163
	v_add_f32_e32 v44, v44, v164
	v_add_f32_e32 v44, v44, v165
	v_add_f32_e32 v44, v44, v168
	v_add_f32_e32 v44, v44, v175
	v_add_f32_e32 v44, v44, v179
	v_add_f32_e32 v44, v44, v183
	v_add_f32_e32 v44, v44, v190
	v_add_f32_e32 v44, v44, v191
	v_fmamk_f32 v44, v44, 0x3a800000, v167
	s_mov_b32 s3, 0x800000
	v_mul_f32_e32 v45, 0x4b800000, v44
	v_cmp_gt_f32_e32 vcc, s3, v44
	s_nop 1
	v_cndmask_b32_e32 v44, v44, v45, vcc
	v_rsq_f32_e32 v44, v44
	s_nop 0
	v_mul_f32_e32 v45, 0x45800000, v44
	v_cndmask_b32_e32 v44, v44, v45, vcc
	ds_write_b32 v155, v44
	s_branch .LBB0_366

.LBB0_392:
	s_add_i32 s0, s1, 2
	v_add_u32_e32 v111, v104, v105
	ds_read_b128 v[136:139], v111 offset:16384
	ds_read_b128 v[140:143], v111 offset:18432
	ds_read_b128 v[144:147], v111 offset:20480
	ds_read_b128 v[148:151], v111 offset:22528
	v_add_u32_e32 v110, v103, v105
	ds_read_b128 v[116:119], v110
	s_add_i32 s1, s1, 4
	ds_read_b128 v[120:123], v110 offset:2048
	s_min_u32 s1, s1, 15
	v_add_u32_e32 v113, v104, v114
	s_lshl_b32 s92, s1, 7
	ds_read_b128 v[124:127], v110 offset:4096
	v_add_u32_e32 v112, v103, v114
	ds_read_b128 v[194:197], v113 offset:16384
	ds_read_b128 v[198:201], v113 offset:18432
	ds_read_b128 v[202:205], v113 offset:20480
	ds_read_b128 v[206:209], v113 offset:22528
	v_lshl_add_u64 v[164:165], v[98:99], 0, s[92:93]
	ds_read_b128 v[132:135], v110 offset:6144
	ds_read_b128 v[152:155], v112
	ds_read_b128 v[156:159], v112 offset:2048
	ds_read_b128 v[160:163], v112 offset:4096
	ds_read_b128 v[190:193], v112 offset:6144
	s_waitcnt lgkmcnt(11)
	v_mfma_f32_16x16x32_bf16 v[92:95], v[136:139], v[116:119], v[92:95]
	v_mfma_f32_16x16x32_bf16 v[88:91], v[140:143], v[116:119], v[88:91]
	v_mfma_f32_16x16x32_bf16 v[52:55], v[144:147], v[116:119], v[52:55]
	v_mfma_f32_16x16x32_bf16 v[48:51], v[148:151], v[116:119], v[48:51]
	global_load_dwordx4 v[116:119], v[164:165], off
	s_waitcnt vmcnt(6)
	ds_write_b128 v109, v[56:59] offset:32768
	v_add_co_u32_e32 v56, vcc, s11, v164
	s_waitcnt lgkmcnt(11)
	v_mfma_f32_16x16x32_bf16 v[44:47], v[136:139], v[120:123], v[44:47]
	v_addc_co_u32_e32 v57, vcc, 0, v165, vcc
	v_mfma_f32_16x16x32_bf16 v[40:43], v[140:143], v[120:123], v[40:43]
	v_mfma_f32_16x16x32_bf16 v[36:39], v[144:147], v[120:123], v[36:39]
	v_mfma_f32_16x16x32_bf16 v[32:35], v[148:151], v[120:123], v[32:35]
	global_load_dwordx4 v[120:123], v[56:57], off
	v_add_co_u32_e32 v56, vcc, s33, v164
	ds_write_b128 v109, v[60:63] offset:36864
	s_nop 0
	v_addc_co_u32_e32 v57, vcc, 0, v165, vcc
	s_waitcnt lgkmcnt(11)
	v_mfma_f32_16x16x32_bf16 v[28:31], v[136:139], v[124:127], v[28:31]
	v_mfma_f32_16x16x32_bf16 v[24:27], v[140:143], v[124:127], v[24:27]
	v_mfma_f32_16x16x32_bf16 v[20:23], v[144:147], v[124:127], v[20:23]
	v_mfma_f32_16x16x32_bf16 v[16:19], v[148:151], v[124:127], v[16:19]
	global_load_dwordx4 v[124:127], v[56:57], off
	v_add_co_u32_e32 v56, vcc, s59, v164
	ds_write_b128 v109, v[64:67] offset:40960
	s_nop 0
	v_addc_co_u32_e32 v57, vcc, 0, v165, vcc
	v_lshl_add_u64 v[64:65], v[100:101], 0, s[92:93]
	v_add_co_u32_e32 v66, vcc, s11, v64
	s_waitcnt lgkmcnt(7)
	v_mfma_f32_16x16x32_bf16 v[12:15], v[136:139], v[132:135], v[12:15]
	v_addc_co_u32_e32 v67, vcc, 0, v65, vcc
	v_mfma_f32_16x16x32_bf16 v[8:11], v[140:143], v[132:135], v[8:11]
	v_mfma_f32_16x16x32_bf16 v[4:7], v[144:147], v[132:135], v[4:7]
	v_mfma_f32_16x16x32_bf16 v[0:3], v[148:151], v[132:135], v[0:3]
	global_load_dwordx4 v[132:135], v[56:57], off
	s_waitcnt vmcnt(7)
	ds_write_b128 v109, v[72:75] offset:45056
	s_waitcnt lgkmcnt(7)
	v_mfma_f32_16x16x32_bf16 v[56:59], v[194:197], v[152:155], v[92:95]
	v_mfma_f32_16x16x32_bf16 v[60:63], v[198:201], v[152:155], v[88:91]
	v_mfma_f32_16x16x32_bf16 v[52:55], v[202:205], v[152:155], v[52:55]
	v_mfma_f32_16x16x32_bf16 v[48:51], v[206:209], v[152:155], v[48:51]
	global_load_dwordx4 v[136:139], v[64:65], off
	ds_write_b128 v109, v[68:71] offset:49152
	s_waitcnt lgkmcnt(7)
	v_mfma_f32_16x16x32_bf16 v[44:47], v[194:197], v[156:159], v[44:47]
	v_mfma_f32_16x16x32_bf16 v[40:43], v[198:201], v[156:159], v[40:43]
	v_mfma_f32_16x16x32_bf16 v[36:39], v[202:205], v[156:159], v[36:39]
	v_mfma_f32_16x16x32_bf16 v[32:35], v[206:209], v[156:159], v[32:35]
	global_load_dwordx4 v[140:143], v[66:67], off
	v_add_co_u32_e32 v66, vcc, s33, v64
	s_waitcnt vmcnt(8)
	ds_write_b128 v109, v[76:79] offset:53248
	v_addc_co_u32_e32 v67, vcc, 0, v65, vcc
	v_add_co_u32_e32 v64, vcc, s59, v64
	s_waitcnt lgkmcnt(7)
	v_mfma_f32_16x16x32_bf16 v[28:31], v[194:197], v[160:163], v[28:31]
	v_addc_co_u32_e32 v65, vcc, 0, v65, vcc
	v_mfma_f32_16x16x32_bf16 v[24:27], v[198:201], v[160:163], v[24:27]
	v_mfma_f32_16x16x32_bf16 v[20:23], v[202:205], v[160:163], v[20:23]
	v_mfma_f32_16x16x32_bf16 v[16:19], v[206:209], v[160:163], v[16:19]
	global_load_dwordx4 v[144:147], v[66:67], off
	s_waitcnt vmcnt(8)
	ds_write_b128 v109, v[80:83] offset:57344
	s_waitcnt lgkmcnt(7)
	v_mfma_f32_16x16x32_bf16 v[12:15], v[194:197], v[190:193], v[12:15]
	v_mfma_f32_16x16x32_bf16 v[8:11], v[198:201], v[190:193], v[8:11]
	v_mfma_f32_16x16x32_bf16 v[4:7], v[202:205], v[190:193], v[4:7]
	v_mfma_f32_16x16x32_bf16 v[0:3], v[206:209], v[190:193], v[0:3]
	global_load_dwordx4 v[148:151], v[64:65], off
	s_waitcnt vmcnt(8)
	ds_write_b128 v109, v[84:87] offset:61440
	s_waitcnt lgkmcnt(0)
	s_barrier
	ds_read_b128 v[84:87], v111 offset:51200
	ds_read_b128 v[80:83], v111 offset:49152
	ds_read_b128 v[88:91], v111 offset:53248
	ds_read_b128 v[92:95], v111 offset:55296
	ds_read_b128 v[64:67], v110 offset:32768
	s_min_u32 s1, s0, 12
	s_lshl_b32 s92, s1, 7
	ds_read_b128 v[68:71], v110 offset:34816
	v_lshl_add_u64 v[164:165], v[98:99], 0, s[92:93]
	ds_read_b128 v[72:75], v110 offset:36864
	ds_read_b128 v[76:79], v110 offset:38912
	ds_read_b128 v[152:155], v112 offset:32768
	ds_read_b128 v[156:159], v112 offset:34816
	ds_read_b128 v[160:163], v112 offset:36864
	ds_read_b128 v[190:193], v112 offset:38912
	ds_read_b128 v[194:197], v113 offset:49152
	ds_read_b128 v[198:201], v113 offset:51200
	ds_read_b128 v[202:205], v113 offset:53248
	ds_read_b128 v[206:209], v113 offset:55296
	s_waitcnt lgkmcnt(11)
	v_mfma_f32_16x16x32_bf16 v[214:217], v[84:87], v[64:67], v[60:63]
	v_mfma_f32_16x16x32_bf16 v[210:213], v[80:83], v[64:67], v[56:59]
	s_nop 1
	v_add_co_u32_e32 v60, vcc, s11, v164
	s_nop 1
	v_addc_co_u32_e32 v61, vcc, 0, v165, vcc
	v_mfma_f32_16x16x32_bf16 v[52:55], v[88:91], v[64:67], v[52:55]
	v_mfma_f32_16x16x32_bf16 v[48:51], v[92:95], v[64:67], v[48:51]
	v_add_co_u32_e32 v64, vcc, s33, v164
	global_load_dwordx4 v[56:59], v[164:165], off offset:384
	s_nop 0
	v_addc_co_u32_e32 v65, vcc, 0, v165, vcc
	s_waitcnt vmcnt(8)
	ds_write_b128 v109, v[116:119]
	s_waitcnt lgkmcnt(11)
	v_mfma_f32_16x16x32_bf16 v[44:47], v[80:83], v[68:71], v[44:47]
	v_mfma_f32_16x16x32_bf16 v[40:43], v[84:87], v[68:71], v[40:43]
	v_mfma_f32_16x16x32_bf16 v[36:39], v[88:91], v[68:71], v[36:39]
	v_mfma_f32_16x16x32_bf16 v[32:35], v[92:95], v[68:71], v[32:35]
	v_add_co_u32_e32 v68, vcc, s59, v164
	global_load_dwordx4 v[60:63], v[60:61], off offset:384
	s_waitcnt vmcnt(8)
	ds_write_b128 v109, v[120:123] offset:4096
	s_waitcnt lgkmcnt(11)
	v_mfma_f32_16x16x32_bf16 v[28:31], v[80:83], v[72:75], v[28:31]
	v_addc_co_u32_e32 v69, vcc, 0, v165, vcc
	v_mfma_f32_16x16x32_bf16 v[24:27], v[84:87], v[72:75], v[24:27]
	v_mfma_f32_16x16x32_bf16 v[20:23], v[88:91], v[72:75], v[20:23]
	v_mfma_f32_16x16x32_bf16 v[16:19], v[92:95], v[72:75], v[16:19]
	global_load_dwordx4 v[64:67], v[64:65], off offset:384
	s_waitcnt vmcnt(8)
	ds_write_b128 v109, v[124:127] offset:8192
	s_waitcnt lgkmcnt(11)
	v_mfma_f32_16x16x32_bf16 v[8:11], v[84:87], v[76:79], v[8:11]
	v_lshl_add_u64 v[84:85], v[100:101], 0, s[92:93]
	v_mfma_f32_16x16x32_bf16 v[12:15], v[80:83], v[76:79], v[12:15]
	v_mfma_f32_16x16x32_bf16 v[4:7], v[88:91], v[76:79], v[4:7]
	v_mfma_f32_16x16x32_bf16 v[0:3], v[92:95], v[76:79], v[0:3]
	v_add_co_u32_e32 v76, vcc, s11, v84
	global_load_dwordx4 v[72:75], v[68:69], off offset:384
	s_nop 0
	v_addc_co_u32_e32 v77, vcc, 0, v85, vcc
	v_add_co_u32_e32 v80, vcc, s33, v84
	s_waitcnt vmcnt(8)
	ds_write_b128 v109, v[132:135] offset:12288
	v_addc_co_u32_e32 v81, vcc, 0, v85, vcc
	s_waitcnt lgkmcnt(7)
	v_mfma_f32_16x16x32_bf16 v[92:95], v[194:197], v[152:155], v[210:213]
	s_waitcnt lgkmcnt(6)
	v_mfma_f32_16x16x32_bf16 v[88:91], v[198:201], v[152:155], v[214:217]
	s_waitcnt lgkmcnt(5)
	v_mfma_f32_16x16x32_bf16 v[52:55], v[202:205], v[152:155], v[52:55]
	s_waitcnt lgkmcnt(4)
	v_mfma_f32_16x16x32_bf16 v[48:51], v[206:209], v[152:155], v[48:51]
	global_load_dwordx4 v[68:71], v[84:85], off offset:384
	v_add_co_u32_e32 v84, vcc, s59, v84
	s_waitcnt vmcnt(8)
	ds_write_b128 v109, v[136:139] offset:16384
	v_addc_co_u32_e32 v85, vcc, 0, v85, vcc
	v_mfma_f32_16x16x32_bf16 v[44:47], v[194:197], v[156:159], v[44:47]
	v_mfma_f32_16x16x32_bf16 v[40:43], v[198:201], v[156:159], v[40:43]
	v_mfma_f32_16x16x32_bf16 v[36:39], v[202:205], v[156:159], v[36:39]
	v_mfma_f32_16x16x32_bf16 v[32:35], v[206:209], v[156:159], v[32:35]
	global_load_dwordx4 v[76:79], v[76:77], off offset:384
	s_waitcnt vmcnt(8)
	ds_write_b128 v109, v[140:143] offset:20480
	v_mfma_f32_16x16x32_bf16 v[28:31], v[194:197], v[160:163], v[28:31]
	v_mfma_f32_16x16x32_bf16 v[24:27], v[198:201], v[160:163], v[24:27]
	v_mfma_f32_16x16x32_bf16 v[20:23], v[202:205], v[160:163], v[20:23]
	v_mfma_f32_16x16x32_bf16 v[16:19], v[206:209], v[160:163], v[16:19]
	global_load_dwordx4 v[80:83], v[80:81], off offset:384
	s_waitcnt vmcnt(8)
	ds_write_b128 v109, v[144:147] offset:24576
	v_mfma_f32_16x16x32_bf16 v[12:15], v[194:197], v[190:193], v[12:15]
	v_mfma_f32_16x16x32_bf16 v[8:11], v[198:201], v[190:193], v[8:11]
	v_mfma_f32_16x16x32_bf16 v[4:7], v[202:205], v[190:193], v[4:7]
	v_mfma_f32_16x16x32_bf16 v[0:3], v[206:209], v[190:193], v[0:3]
	global_load_dwordx4 v[84:87], v[84:85], off offset:384
	s_waitcnt vmcnt(8)
	ds_write_b128 v109, v[148:151] offset:28672
	s_cmp_lt_u32 s0, 14
	s_mov_b32 s1, s0
	s_waitcnt lgkmcnt(0)
	s_barrier
	s_cbranch_scc1 .LBB0_392
	s_mul_i32 s0, s69, 0x12000
	v_readlane_b32 s16, v250, 25
	s_add_u32 s24, s16, s0
	v_readlane_b32 s0, v251, 5
	v_lshlrev_b32_e32 v114, 6, v102
	v_readlane_b32 s17, v250, 26
	s_waitcnt vmcnt(5)
	v_add_u32_e32 v64, s0, v108
	v_readlane_b32 s0, v251, 6
	v_add_u32_e32 v56, 0xffffe000, v64
	v_or_b32_e32 v62, v64, v107
	v_or_b32_e32 v65, s0, v114
	v_lshrrev_b32_e32 v56, 10, v56
	s_movk_i32 s0, 0x1800
	v_mad_u32_u24 v56, v56, s0, s0
	v_cmp_lt_i32_e32 vcc, s13, v62
	s_addc_u32 s25, s17, 0
	v_lshlrev_b32_e32 v115, 2, v97
	v_cndmask_b32_e32 v56, 0, v56, vcc
	s_add_u32 s40, s24, 0x2000
	v_or_b32_e32 v58, v65, v115
	v_ashrrev_i32_e32 v57, 31, v56
	s_addc_u32 s41, s25, 0
	s_waitcnt vmcnt(4)
	v_lshlrev_b64 v[74:75], 2, v[56:57]
	v_ashrrev_i32_e32 v59, 31, v58
	v_ashrrev_i32_e32 v63, 31, v62
	v_lshl_add_u64 v[56:57], s[40:41], 0, v[74:75]
	v_lshlrev_b64 v[60:61], 2, v[58:59]
	v_readlane_b32 s0, v250, 15
	s_waitcnt vmcnt(1)
	v_lshl_add_u64 v[82:83], v[56:57], 0, v[60:61]
	v_lshlrev_b64 v[56:57], 12, v[62:63]
	v_readlane_b32 s1, v250, 16
	v_readlane_b32 s16, v250, 21
	v_lshlrev_b64 v[78:79], 11, v[62:63]
	v_lshl_add_u64 v[56:57], s[0:1], 0, v[56:57]
	s_waitcnt vmcnt(0)
	v_lshl_add_u64 v[84:85], v[56:57], 0, v[60:61]
	global_load_dwordx4 v[116:119], v[82:83], off
	global_load_dwordx4 v[120:123], v[82:83], off offset:64
	global_load_dwordx4 v[124:127], v[82:83], off offset:128
	global_load_dwordx4 v[132:135], v[82:83], off offset:192
	global_load_dwordx4 v[190:193], v[84:85], off
	global_load_dwordx4 v[194:197], v[84:85], off offset:64
	global_load_dwordx4 v[198:201], v[84:85], off offset:128
	global_load_dwordx4 v[202:205], v[84:85], off offset:192
	v_add_co_u32_e32 v164, vcc, 0x10000, v84
	s_nop 1
	v_addc_co_u32_e32 v165, vcc, 0, v85, vcc
	v_add_co_u32_e32 v222, vcc, 0x20000, v84
	s_nop 1
	v_addc_co_u32_e32 v223, vcc, 0, v85, vcc
	v_add_co_u32_e32 v224, vcc, 0x30000, v84
	s_nop 1
	v_addc_co_u32_e32 v225, vcc, 0, v85, vcc
	global_load_dwordx4 v[206:209], v[164:165], off
	global_load_dwordx4 v[210:213], v[164:165], off offset:64
	global_load_dwordx4 v[214:217], v[164:165], off offset:128
	global_load_dwordx4 v[218:221], v[164:165], off offset:192
	s_lshl_b32 s0, s69, 12
	v_readlane_b32 s68, v250, 41
	v_readlane_b32 s72, v250, 45
	v_readlane_b32 s73, v250, 46
	s_add_u32 s0, s72, s0
	s_addc_u32 s1, s73, 0
	s_add_u32 s42, s24, 0x4000
	s_addc_u32 s43, s25, 0
	v_lshl_add_u64 v[74:75], s[42:43], 0, v[74:75]
	v_lshl_add_u64 v[56:57], s[0:1], 0, v[60:61]
	v_lshl_add_u64 v[86:87], v[74:75], 0, v[60:61]
	v_readlane_b32 s17, v250, 22
	v_readlane_b32 s69, v250, 42
	v_readlane_b32 s69, v254, 49
	v_lshl_add_u64 v[78:79], s[16:17], 0, v[78:79]
	s_mul_i32 s24, s69, 0x140000
	s_add_u32 s24, s86, s24
	v_lshrrev_b32_e32 v65, 6, v65
	s_mov_b32 s16, 0xa000
	s_addc_u32 s25, s87, 0
	s_add_u32 s38, s24, 0xaf1a000
	s_addc_u32 s39, s25, 0
	v_cmp_eq_u32_e64 s[36:37], 0, v97
	v_readlane_b32 s70, v250, 43
	v_readlane_b32 s71, v250, 44
	v_readlane_b32 s74, v250, 47
	v_readlane_b32 s75, v250, 48
	v_readlane_b32 s76, v250, 49
	v_readlane_b32 s77, v250, 50
	v_readlane_b32 s78, v250, 51
	v_readlane_b32 s79, v250, 52
	v_readlane_b32 s80, v250, 53
	v_readlane_b32 s81, v250, 54
	v_readlane_b32 s82, v250, 55
	v_readlane_b32 s83, v250, 56
	global_load_dwordx4 v[136:139], v[56:57], off
	global_load_dwordx4 v[140:143], v[56:57], off offset:64
	global_load_dwordx4 v[144:147], v[56:57], off offset:128
	global_load_dwordx4 v[148:151], v[56:57], off offset:192
	global_load_dwordx4 v[152:155], v[86:87], off
	global_load_dwordx4 v[156:159], v[86:87], off offset:64
	global_load_dwordx4 v[160:163], v[86:87], off offset:128
	global_load_dwordx4 v[180:183], v[86:87], off offset:192
	s_waitcnt vmcnt(0)
	v_pk_fma_f32 v[68:69], v[94:95], v[118:119], v[192:193]
	v_pk_fma_f32 v[66:67], v[92:93], v[116:117], v[190:191]
	global_store_dwordx4 v[84:85], v[66:69], off
	v_lshl_add_u64 v[92:93], v[58:59], 1, v[78:79]
	s_waitcnt vmcnt(0)
	v_pk_mul_f32 v[72:73], v[68:69], v[138:139]
	v_pk_mul_f32 v[70:71], v[66:67], v[136:137]
	s_waitcnt vmcnt(0)
	v_pk_add_f32 v[76:77], v[154:155], 1.0 op_sel_hi:[1,0]
	v_pk_add_f32 v[74:75], v[152:153], 1.0 op_sel_hi:[1,0]
	v_pk_mul_f32 v[72:73], v[72:73], v[76:77]
	v_pk_mul_f32 v[70:71], v[70:71], v[74:75]
	v_and_b32_sdwa v76, v73, v170 dst_sel:DWORD dst_unused:UNUSED_PAD src0_sel:WORD_1 src1_sel:DWORD
	v_and_b32_sdwa v77, v71, v170 dst_sel:DWORD dst_unused:UNUSED_PAD src0_sel:WORD_1 src1_sel:DWORD
	v_and_b32_sdwa v74, v72, v170 dst_sel:DWORD dst_unused:UNUSED_PAD src0_sel:WORD_1 src1_sel:DWORD
	v_and_b32_sdwa v75, v70, v170 dst_sel:DWORD dst_unused:UNUSED_PAD src0_sel:WORD_1 src1_sel:DWORD
	v_add3_u32 v73, v73, v76, s56
	v_add3_u32 v71, v71, v77, s56
	v_add3_u32 v70, v70, v75, s56
	v_add3_u32 v72, v72, v74, s56
	v_and_b32_e32 v73, 0xffff0000, v73
	v_and_b32_e32 v74, 0xffff0000, v71
	v_or_b32_sdwa v71, v73, v72 dst_sel:DWORD dst_unused:UNUSED_PAD src0_sel:DWORD src1_sel:WORD_1
	v_or_b32_sdwa v70, v74, v70 dst_sel:DWORD dst_unused:UNUSED_PAD src0_sel:DWORD src1_sel:WORD_1
	global_store_dwordx2 v[92:93], v[70:71], off
	s_nop 0
	s_waitcnt vmcnt(0)
	v_pk_fma_f32 v[72:73], v[90:91], v[122:123], v[196:197]
	v_pk_fma_f32 v[70:71], v[88:89], v[120:121], v[194:195]
	global_store_dwordx4 v[84:85], v[70:73], off offset:64
	v_pk_mul_f32 v[76:77], v[72:73], v[142:143]
	v_pk_mul_f32 v[74:75], v[70:71], v[140:141]
	v_pk_add_f32 v[80:81], v[158:159], 1.0 op_sel_hi:[1,0]
	v_pk_add_f32 v[78:79], v[156:157], 1.0 op_sel_hi:[1,0]
	v_pk_mul_f32 v[76:77], v[76:77], v[80:81]
	v_pk_mul_f32 v[74:75], v[74:75], v[78:79]
	v_and_b32_sdwa v80, v77, v170 dst_sel:DWORD dst_unused:UNUSED_PAD src0_sel:WORD_1 src1_sel:DWORD
	v_and_b32_sdwa v81, v75, v170 dst_sel:DWORD dst_unused:UNUSED_PAD src0_sel:WORD_1 src1_sel:DWORD
	v_and_b32_sdwa v78, v76, v170 dst_sel:DWORD dst_unused:UNUSED_PAD src0_sel:WORD_1 src1_sel:DWORD
	v_and_b32_sdwa v79, v74, v170 dst_sel:DWORD dst_unused:UNUSED_PAD src0_sel:WORD_1 src1_sel:DWORD
	v_add3_u32 v77, v77, v80, s56
	v_add3_u32 v75, v75, v81, s56
	v_add3_u32 v74, v74, v79, s56
	v_add3_u32 v76, v76, v78, s56
	v_and_b32_e32 v77, 0xffff0000, v77
	v_and_b32_e32 v78, 0xffff0000, v75
	v_or_b32_sdwa v75, v77, v76 dst_sel:DWORD dst_unused:UNUSED_PAD src0_sel:DWORD src1_sel:WORD_1
	v_or_b32_sdwa v74, v78, v74 dst_sel:DWORD dst_unused:UNUSED_PAD src0_sel:DWORD src1_sel:WORD_1
	global_store_dwordx2 v[92:93], v[74:75], off offset:32
	s_nop 0
	v_pk_fma_f32 v[54:55], v[54:55], v[126:127], v[200:201]
	v_pk_fma_f32 v[52:53], v[52:53], v[124:125], v[198:199]
	global_store_dwordx4 v[84:85], v[52:55], off offset:128
	v_pk_mul_f32 v[76:77], v[54:55], v[146:147]
	v_pk_mul_f32 v[74:75], v[52:53], v[144:145]
	v_pk_add_f32 v[80:81], v[162:163], 1.0 op_sel_hi:[1,0]
	v_pk_add_f32 v[78:79], v[160:161], 1.0 op_sel_hi:[1,0]
	v_pk_mul_f32 v[76:77], v[76:77], v[80:81]
	v_pk_mul_f32 v[74:75], v[74:75], v[78:79]
	v_and_b32_sdwa v80, v77, v170 dst_sel:DWORD dst_unused:UNUSED_PAD src0_sel:WORD_1 src1_sel:DWORD
	v_and_b32_sdwa v81, v75, v170 dst_sel:DWORD dst_unused:UNUSED_PAD src0_sel:WORD_1 src1_sel:DWORD
	v_and_b32_sdwa v78, v76, v170 dst_sel:DWORD dst_unused:UNUSED_PAD src0_sel:WORD_1 src1_sel:DWORD
	v_and_b32_sdwa v79, v74, v170 dst_sel:DWORD dst_unused:UNUSED_PAD src0_sel:WORD_1 src1_sel:DWORD
	v_add3_u32 v77, v77, v80, s56
	v_add3_u32 v75, v75, v81, s56
	v_add3_u32 v74, v74, v79, s56
	v_add3_u32 v76, v76, v78, s56
	v_and_b32_e32 v77, 0xffff0000, v77
	v_and_b32_e32 v78, 0xffff0000, v75
	v_or_b32_sdwa v75, v77, v76 dst_sel:DWORD dst_unused:UNUSED_PAD src0_sel:DWORD src1_sel:WORD_1
	v_or_b32_sdwa v74, v78, v74 dst_sel:DWORD dst_unused:UNUSED_PAD src0_sel:DWORD src1_sel:WORD_1
	global_store_dwordx2 v[92:93], v[74:75], off offset:64
	s_nop 0
	v_pk_fma_f32 v[76:77], v[50:51], v[134:135], v[204:205]
	v_pk_fma_f32 v[74:75], v[48:49], v[132:133], v[202:203]
	global_store_dwordx4 v[84:85], v[74:77], off offset:192
	s_nop 0
	v_mbcnt_lo_u32_b32 v48, -1, 0
	v_mbcnt_hi_u32_b32 v48, -1, v48
	v_and_b32_e32 v50, 64, v48
	v_xor_b32_e32 v49, 16, v48
	v_add_u32_e32 v50, 64, v50
	v_xor_b32_e32 v51, 32, v48
	v_cmp_lt_i32_e32 vcc, v49, v50
	s_nop 1
	v_cndmask_b32_e32 v49, v48, v49, vcc
	v_cmp_lt_i32_e32 vcc, v51, v50
	v_lshlrev_b32_e32 v105, 2, v49
	s_nop 0
	v_cndmask_b32_e32 v50, v48, v51, vcc
	v_lshlrev_b32_e32 v104, 2, v50
	v_mul_f32_e32 v50, v67, v67
	v_mul_f32_e32 v51, v71, v71
	v_fmac_f32_e32 v50, v66, v66
	v_fmac_f32_e32 v51, v70, v70
	v_fmac_f32_e32 v50, v68, v68
	v_fmac_f32_e32 v51, v72, v72
	v_fmac_f32_e32 v50, v69, v69
	v_fmac_f32_e32 v51, v73, v73
	v_add_f32_e32 v50, v50, v51
	v_mul_f32_e32 v51, v53, v53
	v_fmac_f32_e32 v51, v52, v52
	v_fmac_f32_e32 v51, v54, v54
	v_fmac_f32_e32 v51, v55, v55
	v_add_f32_e32 v50, v50, v51
	v_mul_f32_e32 v51, v75, v75
	v_fmac_f32_e32 v51, v74, v74
	v_fmac_f32_e32 v51, v76, v76
	v_fmac_f32_e32 v51, v77, v77
	v_add_f32_e32 v50, v50, v51
	ds_bpermute_b32 v51, v105, v50
	v_mul_lo_u32 v48, v65, s16
	v_ashrrev_i32_e32 v49, 31, v48
	v_lshl_add_u64 v[48:49], s[38:39], 0, v[48:49]
	v_lshl_add_u64 v[48:49], v[62:63], 2, v[48:49]
	s_waitcnt lgkmcnt(0)
	v_add_f32_e32 v50, v50, v51
	ds_bpermute_b32 v51, v104, v50
	v_pk_mul_f32 v[52:53], v[76:77], v[150:151]
	v_pk_mul_f32 v[54:55], v[74:75], v[148:149]
	v_pk_add_f32 v[66:67], v[182:183], 1.0 op_sel_hi:[1,0]
	v_pk_add_f32 v[68:69], v[180:181], 1.0 op_sel_hi:[1,0]
	v_pk_mul_f32 v[52:53], v[52:53], v[66:67]
	v_pk_mul_f32 v[54:55], v[54:55], v[68:69]
	v_and_b32_sdwa v67, v53, v170 dst_sel:DWORD dst_unused:UNUSED_PAD src0_sel:WORD_1 src1_sel:DWORD
	v_and_b32_sdwa v68, v55, v170 dst_sel:DWORD dst_unused:UNUSED_PAD src0_sel:WORD_1 src1_sel:DWORD
	v_and_b32_sdwa v65, v52, v170 dst_sel:DWORD dst_unused:UNUSED_PAD src0_sel:WORD_1 src1_sel:DWORD
	v_and_b32_sdwa v66, v54, v170 dst_sel:DWORD dst_unused:UNUSED_PAD src0_sel:WORD_1 src1_sel:DWORD
	v_add3_u32 v53, v53, v67, s56
	v_add3_u32 v55, v55, v68, s56
	v_add3_u32 v54, v54, v66, s56
	v_add3_u32 v52, v52, v65, s56
	v_and_b32_e32 v53, 0xffff0000, v53
	v_and_b32_e32 v55, 0xffff0000, v55
	v_or_b32_sdwa v53, v53, v52 dst_sel:DWORD dst_unused:UNUSED_PAD src0_sel:DWORD src1_sel:WORD_1
	v_or_b32_sdwa v52, v55, v54 dst_sel:DWORD dst_unused:UNUSED_PAD src0_sel:DWORD src1_sel:WORD_1
	global_store_dwordx2 v[92:93], v[52:53], off offset:96
	s_and_saveexec_b64 s[24:25], s[36:37]
	s_cbranch_execz .LBB0_395
	s_waitcnt lgkmcnt(0)
	v_add_f32_e32 v50, v50, v51
	global_store_dword v[48:49], v50, off

.LBB0_419:
	s_add_i32 s2, s3, 2
	v_add_u32_e32 v127, v89, v90
	ds_read_b128 v[100:103], v127 offset:16384
	ds_read_b128 v[106:109], v127 offset:18432
	ds_read_b128 v[110:113], v127 offset:20480
	ds_read_b128 v[114:117], v127 offset:22528
	v_add_u32_e32 v126, v88, v90
	ds_read_b128 v[92:95], v126
	ds_read_b128 v[96:99], v126 offset:2048
	s_add_i32 s3, s3, 4
	s_min_u32 s3, s3, 15
	v_add_u32_e32 v128, v88, v91
	v_add_u32_e32 v130, v89, v91
	s_lshl_b32 s92, s3, 7
	ds_read_b128 v[118:121], v130 offset:18432
	ds_read_b128 v[122:125], v130 offset:20480
	ds_read_b128 v[132:135], v130 offset:22528
	s_waitcnt lgkmcnt(4)
	v_mfma_f32_16x16x32_bf16 v[76:79], v[100:103], v[92:95], v[76:79]
	v_lshl_add_u64 v[44:45], v[80:81], 0, s[92:93]
	v_add_co_u32_e32 v46, vcc, s11, v44
	v_mfma_f32_16x16x32_bf16 v[68:71], v[106:109], v[92:95], v[68:71]
	s_nop 0
	v_addc_co_u32_e32 v47, vcc, 0, v45, vcc
	v_mfma_f32_16x16x32_bf16 v[52:55], v[110:113], v[92:95], v[52:55]
	v_mfma_f32_16x16x32_bf16 v[40:43], v[114:117], v[92:95], v[40:43]
	s_waitcnt lgkmcnt(3)
	v_mfma_f32_16x16x32_bf16 v[92:95], v[100:103], v[96:99], v[36:39]
	s_nop 2
	ds_read_b128 v[36:39], v128
	v_mfma_f32_16x16x32_bf16 v[100:103], v[106:109], v[96:99], v[8:11]
	v_mfma_f32_16x16x32_bf16 v[106:109], v[110:113], v[96:99], v[4:7]
	ds_read_b128 v[110:113], v128 offset:2048
	v_mfma_f32_16x16x32_bf16 v[96:99], v[114:117], v[96:99], v[0:3]
	ds_read_b128 v[114:117], v130 offset:16384
	global_load_dwordx4 v[72:75], v[44:45], off
	s_waitcnt vmcnt(1)
	ds_write_b128 v87, v[12:15] offset:53248
	global_load_dwordx4 v[64:67], v[46:47], off
	v_add_co_u32_e32 v46, vcc, s33, v44
	ds_write_b128 v87, v[16:19] offset:49152
	s_nop 0
	v_addc_co_u32_e32 v47, vcc, 0, v45, vcc
	v_add_co_u32_e32 v44, vcc, s59, v44
	global_load_dwordx4 v[60:63], v[46:47], off
	s_nop 0
	v_addc_co_u32_e32 v45, vcc, 0, v45, vcc
	ds_write_b128 v87, v[20:23] offset:45056
	global_load_dwordx4 v[56:59], v[44:45], off
	v_lshl_add_u64 v[44:45], v[82:83], 0, s[92:93]
	ds_write_b128 v87, v[28:31] offset:32768
	s_waitcnt lgkmcnt(4)
	v_mfma_f32_16x16x32_bf16 v[0:3], v[114:117], v[36:39], v[76:79]
	v_mfma_f32_16x16x32_bf16 v[4:7], v[118:121], v[36:39], v[68:71]
	global_load_dwordx4 v[48:51], v[44:45], off
	v_add_co_u32_e32 v44, vcc, s11, v44
	ds_write_b128 v87, v[32:35] offset:36864
	s_nop 0
	v_addc_co_u32_e32 v45, vcc, 0, v45, vcc
	v_mfma_f32_16x16x32_bf16 v[8:11], v[122:125], v[36:39], v[52:55]
	v_mfma_f32_16x16x32_bf16 v[36:39], v[132:135], v[36:39], v[40:43]
	global_load_dwordx4 v[44:47], v[44:45], off
	ds_write_b128 v87, v[24:27] offset:40960
	v_mfma_f32_16x16x32_bf16 v[40:43], v[114:117], v[110:113], v[92:95]
	v_mfma_f32_16x16x32_bf16 v[52:55], v[118:121], v[110:113], v[100:103]
	v_mfma_f32_16x16x32_bf16 v[68:71], v[122:125], v[110:113], v[106:109]
	v_mfma_f32_16x16x32_bf16 v[76:79], v[132:135], v[110:113], v[96:99]
	s_waitcnt lgkmcnt(0)
	s_barrier
	ds_read_b128 v[100:103], v127 offset:49152
	ds_read_b128 v[106:109], v127 offset:51200
	ds_read_b128 v[110:113], v127 offset:53248
	ds_read_b128 v[114:117], v127 offset:55296
	ds_read_b128 v[92:95], v126 offset:32768
	ds_read_b128 v[96:99], v126 offset:34816
	s_min_u32 s3, s2, 12
	s_lshl_b32 s92, s3, 7
	ds_read_b128 v[118:121], v130 offset:51200
	ds_read_b128 v[122:125], v130 offset:53248
	ds_read_b128 v[132:135], v130 offset:55296
	s_waitcnt lgkmcnt(4)
	v_mfma_f32_16x16x32_bf16 v[0:3], v[100:103], v[92:95], v[0:3]
	v_lshl_add_u64 v[12:13], v[80:81], 0, s[92:93]
	v_add_co_u32_e32 v14, vcc, s11, v12
	v_mfma_f32_16x16x32_bf16 v[4:7], v[106:109], v[92:95], v[4:7]
	s_nop 0
	v_addc_co_u32_e32 v15, vcc, 0, v13, vcc
	v_mfma_f32_16x16x32_bf16 v[8:11], v[110:113], v[92:95], v[8:11]
	v_mfma_f32_16x16x32_bf16 v[36:39], v[114:117], v[92:95], v[36:39]
	s_waitcnt lgkmcnt(3)
	v_mfma_f32_16x16x32_bf16 v[92:95], v[100:103], v[96:99], v[40:43]
	s_nop 2
	ds_read_b128 v[40:43], v128 offset:32768
	v_mfma_f32_16x16x32_bf16 v[100:103], v[106:109], v[96:99], v[52:55]
	v_mfma_f32_16x16x32_bf16 v[106:109], v[110:113], v[96:99], v[68:71]
	ds_read_b128 v[110:113], v128 offset:34816
	v_mfma_f32_16x16x32_bf16 v[96:99], v[114:117], v[96:99], v[76:79]
	ds_read_b128 v[114:117], v130 offset:49152
	global_load_dwordx4 v[28:31], v[12:13], off offset:384
	s_waitcnt vmcnt(1)
	ds_write_b128 v87, v[44:47] offset:20480
	global_load_dwordx4 v[32:35], v[14:15], off offset:384
	v_add_co_u32_e32 v14, vcc, s33, v12
	ds_write_b128 v87, v[48:51] offset:16384
	s_nop 0
	v_addc_co_u32_e32 v15, vcc, 0, v13, vcc
	v_add_co_u32_e32 v12, vcc, s59, v12
	global_load_dwordx4 v[24:27], v[14:15], off offset:384
	s_nop 0
	v_addc_co_u32_e32 v13, vcc, 0, v13, vcc
	ds_write_b128 v87, v[56:59] offset:12288
	global_load_dwordx4 v[20:23], v[12:13], off offset:384
	v_lshl_add_u64 v[12:13], v[82:83], 0, s[92:93]
	ds_write_b128 v87, v[72:75]
	s_waitcnt lgkmcnt(4)
	v_mfma_f32_16x16x32_bf16 v[76:79], v[114:117], v[40:43], v[0:3]
	v_mfma_f32_16x16x32_bf16 v[68:71], v[118:121], v[40:43], v[4:7]
	global_load_dwordx4 v[16:19], v[12:13], off offset:384
	v_add_co_u32_e32 v12, vcc, s11, v12
	ds_write_b128 v87, v[64:67] offset:4096
	s_nop 0
	v_addc_co_u32_e32 v13, vcc, 0, v13, vcc
	v_mfma_f32_16x16x32_bf16 v[52:55], v[122:125], v[40:43], v[8:11]
	v_mfma_f32_16x16x32_bf16 v[40:43], v[132:135], v[40:43], v[36:39]
	global_load_dwordx4 v[12:15], v[12:13], off offset:384
	ds_write_b128 v87, v[60:63] offset:8192
	v_mfma_f32_16x16x32_bf16 v[36:39], v[114:117], v[110:113], v[92:95]
	v_mfma_f32_16x16x32_bf16 v[8:11], v[118:121], v[110:113], v[100:103]
	v_mfma_f32_16x16x32_bf16 v[4:7], v[122:125], v[110:113], v[106:109]
	v_mfma_f32_16x16x32_bf16 v[0:3], v[132:135], v[110:113], v[96:99]
	s_cmp_lt_u32 s2, 14
	s_mov_b32 s3, s2
	s_waitcnt lgkmcnt(0)
	s_barrier
	s_cbranch_scc1 .LBB0_419
	v_readlane_b32 s2, v251, 18
	s_waitcnt vmcnt(1)
	s_nop 0
	v_add_u32_e32 v18, s2, v86
	v_readlane_b32 s2, v251, 19
	s_waitcnt vmcnt(0)
	v_add_u32_e32 v13, 0xffffe000, v18
	v_or_b32_e32 v12, v18, v85
	v_lshl_or_b32 v19, v84, 2, s2
	v_lshrrev_b32_e32 v13, 10, v13
	s_movk_i32 s2, 0x1800
	v_mad_u32_u24 v13, v13, s2, s2
	v_cmp_lt_i32_e32 vcc, s13, v12
	v_lshlrev_b32_e32 v128, 2, v19
	v_readlane_b32 s2, v250, 15
	v_cndmask_b32_e32 v14, 0, v13, vcc
	v_ashrrev_i32_e32 v15, 31, v14
	v_lshlrev_b64 v[24:25], 2, v[14:15]
	v_ashrrev_i32_e32 v13, 31, v12
	v_lshl_add_u64 v[14:15], s[40:41], 0, v[24:25]
	v_lshl_add_u64 v[48:49], v[14:15], 0, v[128:129]
	v_lshlrev_b64 v[14:15], 12, v[12:13]
	v_readlane_b32 s3, v250, 16
	v_lshl_add_u64 v[28:29], s[42:43], 0, v[24:25]
	v_lshlrev_b64 v[32:33], 11, v[12:13]
	v_lshl_add_u64 v[14:15], s[2:3], 0, v[14:15]
	v_lshl_add_u64 v[50:51], v[14:15], 0, v[128:129]
	global_load_dwordx4 v[72:75], v[48:49], off
	global_load_dwordx4 v[80:83], v[48:49], off offset:64
	global_load_dwordx4 v[88:91], v[48:49], off offset:128
	global_load_dwordx4 v[136:139], v[48:49], off offset:192
	global_load_dwordx4 v[194:197], v[50:51], off
	global_load_dwordx4 v[198:201], v[50:51], off offset:64
	global_load_dwordx4 v[202:205], v[50:51], off offset:128
	global_load_dwordx4 v[206:209], v[50:51], off offset:192
	v_add_co_u32_e32 v58, vcc, 0x10000, v50
	s_nop 1
	v_addc_co_u32_e32 v59, vcc, 0, v51, vcc
	global_load_dwordx4 v[210:213], v[58:59], off
	global_load_dwordx4 v[214:217], v[58:59], off offset:64
	global_load_dwordx4 v[218:221], v[58:59], off offset:128
	global_load_dwordx4 v[222:225], v[58:59], off offset:192
	v_readlane_b32 s2, v250, 21
	v_readlane_b32 s3, v250, 22
	v_cmp_eq_u32_e32 vcc, 0, v84
	global_load_dwordx4 v[140:143], v128, s[0:1]
	global_load_dwordx4 v[144:147], v128, s[0:1] offset:64
	global_load_dwordx4 v[148:151], v128, s[0:1] offset:128
	global_load_dwordx4 v[152:155], v128, s[0:1] offset:192
	s_waitcnt vmcnt(0)
	v_pk_fma_f32 v[22:23], v[78:79], v[74:75], v[196:197]
	v_pk_fma_f32 v[20:21], v[76:77], v[72:73], v[194:195]
	global_store_dwordx4 v[50:51], v[20:23], off
	v_lshl_add_u64 v[14:15], v[28:29], 0, v[128:129]
	global_load_dwordx4 v[156:159], v[14:15], off
	global_load_dwordx4 v[160:163], v[14:15], off offset:64
	global_load_dwordx4 v[180:183], v[14:15], off offset:128
	global_load_dwordx4 v[190:193], v[14:15], off offset:192
	v_lshlrev_b32_e32 v16, 1, v19
	v_mov_b32_e32 v17, v129
	v_lshl_add_u64 v[32:33], s[2:3], 0, v[32:33]
	v_lshl_add_u64 v[56:57], v[32:33], 0, v[16:17]
	s_waitcnt vmcnt(0)
	v_pk_mul_f32 v[26:27], v[22:23], v[142:143]
	v_pk_mul_f32 v[24:25], v[20:21], v[140:141]
	s_waitcnt vmcnt(0)
	v_pk_add_f32 v[30:31], v[158:159], 1.0 op_sel_hi:[1,0]
	v_pk_add_f32 v[28:29], v[156:157], 1.0 op_sel_hi:[1,0]
	v_pk_mul_f32 v[26:27], v[26:27], v[30:31]
	v_pk_mul_f32 v[24:25], v[24:25], v[28:29]
	v_and_b32_sdwa v19, v26, v170 dst_sel:DWORD dst_unused:UNUSED_PAD src0_sel:WORD_1 src1_sel:DWORD
	v_and_b32_sdwa v29, v27, v170 dst_sel:DWORD dst_unused:UNUSED_PAD src0_sel:WORD_1 src1_sel:DWORD
	v_and_b32_sdwa v30, v25, v170 dst_sel:DWORD dst_unused:UNUSED_PAD src0_sel:WORD_1 src1_sel:DWORD
	v_and_b32_sdwa v28, v24, v170 dst_sel:DWORD dst_unused:UNUSED_PAD src0_sel:WORD_1 src1_sel:DWORD
	v_add3_u32 v19, v26, v19, s56
	v_add3_u32 v26, v27, v29, s56
	v_add3_u32 v25, v25, v30, s56
	v_add3_u32 v24, v24, v28, s56
	v_and_b32_e32 v26, 0xffff0000, v26
	v_and_b32_e32 v27, 0xffff0000, v25
	v_or_b32_sdwa v25, v26, v19 dst_sel:DWORD dst_unused:UNUSED_PAD src0_sel:DWORD src1_sel:WORD_1
	v_or_b32_sdwa v24, v27, v24 dst_sel:DWORD dst_unused:UNUSED_PAD src0_sel:DWORD src1_sel:WORD_1
	global_store_dwordx2 v[56:57], v[24:25], off
	s_nop 0
	s_waitcnt vmcnt(0)
	v_pk_fma_f32 v[26:27], v[70:71], v[82:83], v[200:201]
	v_pk_fma_f32 v[24:25], v[68:69], v[80:81], v[198:199]
	global_store_dwordx4 v[50:51], v[24:27], off offset:64
	v_pk_mul_f32 v[30:31], v[26:27], v[146:147]
	v_pk_mul_f32 v[28:29], v[24:25], v[144:145]
	v_pk_add_f32 v[34:35], v[162:163], 1.0 op_sel_hi:[1,0]
	v_pk_add_f32 v[32:33], v[160:161], 1.0 op_sel_hi:[1,0]
	v_pk_mul_f32 v[30:31], v[30:31], v[34:35]
	v_pk_mul_f32 v[28:29], v[28:29], v[32:33]
	v_and_b32_sdwa v19, v30, v170 dst_sel:DWORD dst_unused:UNUSED_PAD src0_sel:WORD_1 src1_sel:DWORD
	v_and_b32_sdwa v33, v31, v170 dst_sel:DWORD dst_unused:UNUSED_PAD src0_sel:WORD_1 src1_sel:DWORD
	v_and_b32_sdwa v34, v29, v170 dst_sel:DWORD dst_unused:UNUSED_PAD src0_sel:WORD_1 src1_sel:DWORD
	v_and_b32_sdwa v32, v28, v170 dst_sel:DWORD dst_unused:UNUSED_PAD src0_sel:WORD_1 src1_sel:DWORD
	v_add3_u32 v19, v30, v19, s56
	v_add3_u32 v30, v31, v33, s56
	v_add3_u32 v29, v29, v34, s56
	v_add3_u32 v28, v28, v32, s56
	v_and_b32_e32 v30, 0xffff0000, v30
	v_and_b32_e32 v31, 0xffff0000, v29
	v_or_b32_sdwa v29, v30, v19 dst_sel:DWORD dst_unused:UNUSED_PAD src0_sel:DWORD src1_sel:WORD_1
	v_or_b32_sdwa v28, v31, v28 dst_sel:DWORD dst_unused:UNUSED_PAD src0_sel:DWORD src1_sel:WORD_1
	global_store_dwordx2 v[56:57], v[28:29], off offset:32
	s_nop 0
	v_pk_fma_f32 v[30:31], v[54:55], v[90:91], v[204:205]
	v_pk_fma_f32 v[28:29], v[52:53], v[88:89], v[202:203]
	global_store_dwordx4 v[50:51], v[28:31], off offset:128
	v_pk_mul_f32 v[34:35], v[30:31], v[150:151]
	v_pk_mul_f32 v[32:33], v[28:29], v[148:149]
	v_pk_add_f32 v[46:47], v[182:183], 1.0 op_sel_hi:[1,0]
	v_pk_add_f32 v[44:45], v[180:181], 1.0 op_sel_hi:[1,0]
	v_pk_mul_f32 v[34:35], v[34:35], v[46:47]
	v_pk_mul_f32 v[32:33], v[32:33], v[44:45]
	v_and_b32_sdwa v19, v34, v170 dst_sel:DWORD dst_unused:UNUSED_PAD src0_sel:WORD_1 src1_sel:DWORD
	v_and_b32_sdwa v45, v35, v170 dst_sel:DWORD dst_unused:UNUSED_PAD src0_sel:WORD_1 src1_sel:DWORD
	v_and_b32_sdwa v46, v33, v170 dst_sel:DWORD dst_unused:UNUSED_PAD src0_sel:WORD_1 src1_sel:DWORD
	v_and_b32_sdwa v44, v32, v170 dst_sel:DWORD dst_unused:UNUSED_PAD src0_sel:WORD_1 src1_sel:DWORD
	v_add3_u32 v19, v34, v19, s56
	v_add3_u32 v34, v35, v45, s56
	v_add3_u32 v33, v33, v46, s56
	v_add3_u32 v32, v32, v44, s56
	v_and_b32_e32 v34, 0xffff0000, v34
	v_and_b32_e32 v35, 0xffff0000, v33
	v_or_b32_sdwa v33, v34, v19 dst_sel:DWORD dst_unused:UNUSED_PAD src0_sel:DWORD src1_sel:WORD_1
	v_or_b32_sdwa v32, v35, v32 dst_sel:DWORD dst_unused:UNUSED_PAD src0_sel:DWORD src1_sel:WORD_1
	global_store_dwordx2 v[56:57], v[32:33], off offset:64
	s_nop 0
	v_pk_fma_f32 v[34:35], v[42:43], v[138:139], v[208:209]
	v_pk_fma_f32 v[32:33], v[40:41], v[136:137], v[206:207]
	global_store_dwordx4 v[50:51], v[32:35], off offset:192
	v_mul_f32_e32 v14, v21, v21
	v_mul_f32_e32 v15, v25, v25
	v_fmac_f32_e32 v14, v20, v20
	v_fmac_f32_e32 v15, v24, v24
	v_fmac_f32_e32 v14, v22, v22
	v_fmac_f32_e32 v15, v26, v26
	v_fmac_f32_e32 v14, v23, v23
	v_fmac_f32_e32 v15, v27, v27
	v_add_f32_e32 v14, v14, v15
	v_mul_f32_e32 v15, v29, v29
	v_fmac_f32_e32 v15, v28, v28
	v_fmac_f32_e32 v15, v30, v30
	v_fmac_f32_e32 v15, v31, v31
	v_add_f32_e32 v14, v14, v15
	v_mul_f32_e32 v15, v33, v33
	v_fmac_f32_e32 v15, v32, v32
	v_fmac_f32_e32 v15, v34, v34
	v_fmac_f32_e32 v15, v35, v35
	v_add_f32_e32 v14, v14, v15
	ds_bpermute_b32 v15, v105, v14
	s_waitcnt lgkmcnt(0)
	v_add_f32_e32 v14, v14, v15
	ds_bpermute_b32 v15, v104, v14
	v_pk_mul_f32 v[20:21], v[34:35], v[154:155]
	v_pk_mul_f32 v[22:23], v[32:33], v[152:153]
	v_pk_add_f32 v[24:25], v[192:193], 1.0 op_sel_hi:[1,0]
	v_pk_add_f32 v[26:27], v[190:191], 1.0 op_sel_hi:[1,0]
	v_pk_mul_f32 v[20:21], v[20:21], v[24:25]
	v_pk_mul_f32 v[22:23], v[22:23], v[26:27]
	v_and_b32_sdwa v19, v20, v170 dst_sel:DWORD dst_unused:UNUSED_PAD src0_sel:WORD_1 src1_sel:DWORD
	v_and_b32_sdwa v25, v21, v170 dst_sel:DWORD dst_unused:UNUSED_PAD src0_sel:WORD_1 src1_sel:DWORD
	v_and_b32_sdwa v26, v23, v170 dst_sel:DWORD dst_unused:UNUSED_PAD src0_sel:WORD_1 src1_sel:DWORD
	v_and_b32_sdwa v24, v22, v170 dst_sel:DWORD dst_unused:UNUSED_PAD src0_sel:WORD_1 src1_sel:DWORD
	v_add3_u32 v19, v20, v19, s56
	v_add3_u32 v20, v21, v25, s56
	v_add3_u32 v21, v23, v26, s56
	v_add3_u32 v22, v22, v24, s56
	v_and_b32_e32 v20, 0xffff0000, v20
	v_and_b32_e32 v23, 0xffff0000, v21
	v_or_b32_sdwa v21, v20, v19 dst_sel:DWORD dst_unused:UNUSED_PAD src0_sel:DWORD src1_sel:WORD_1
	v_or_b32_sdwa v20, v23, v22 dst_sel:DWORD dst_unused:UNUSED_PAD src0_sel:DWORD src1_sel:WORD_1
	global_store_dwordx2 v[56:57], v[20:21], off offset:96
	s_and_saveexec_b64 s[2:3], vcc
	s_cbranch_execz .LBB0_422
	v_readlane_b32 s16, v253, 20
	s_add_u32 s24, s38, s16
	s_addc_u32 s25, s39, 0
	v_lshl_add_u64 v[20:21], v[12:13], 2, s[24:25]
	s_waitcnt lgkmcnt(0)
	v_add_f32_e32 v13, v14, v15
	global_store_dword v[20:21], v13, off

.LBB0_454:
	v_ashrrev_i32_e32 v7, 31, v4
	v_ashrrev_i32_e32 v8, 31, v5
	v_lshrrev_b32_e32 v7, 26, v7
	v_lshrrev_b32_e32 v8, 26, v8
	v_add_u32_e32 v7, v4, v7
	v_add_u32_e32 v16, v5, v8
	v_and_b32_e32 v9, 0xffffffc0, v16
	v_and_b32_e32 v8, 0xffffffc0, v7
	v_sub_u32_e32 v17, v5, v9
	v_sub_u32_e32 v18, v4, v8
	v_add3_u32 v8, v18, v72, v8
	v_add3_u32 v10, v17, v73, v9
	v_ashrrev_i32_e32 v11, 31, v10
	v_ashrrev_i32_e32 v9, 31, v8
	v_lshlrev_b64 v[8:9], 2, v[8:9]
	v_lshlrev_b64 v[10:11], 2, v[10:11]
	v_lshl_add_u64 v[12:13], v[0:1], 0, v[8:9]
	v_lshl_add_u64 v[14:15], v[0:1], 0, v[10:11]
	v_lshl_add_u64 v[10:11], v[2:3], 0, v[10:11]
	v_lshl_add_u64 v[8:9], v[2:3], 0, v[8:9]
	v_lshl_add_u64 v[8:9], v[8:9], 0, s[16:17]
	v_cmp_gt_i32_e32 vcc, 32, v18
	v_lshl_add_u64 v[10:11], v[10:11], 0, s[16:17]
	v_cmp_gt_i32_e64 s[0:1], 32, v17
	v_cndmask_b32_e32 v8, v8, v12, vcc
	v_cndmask_b32_e32 v9, v9, v13, vcc
	v_cndmask_b32_e64 v11, v11, v15, s[0:1]
	v_cndmask_b32_e64 v10, v10, v14, s[0:1]
	global_load_dword v10, v[10:11], off
	s_nop 0
	global_load_dword v8, v[8:9], off
	v_ashrrev_i32_e32 v7, 6, v7
	v_ashrrev_i32_e32 v9, 6, v16
	v_lshrrev_b32_e32 v16, 1, v18
	v_lshrrev_b32_e32 v12, 3, v7
	v_lshrrev_b32_e32 v15, 1, v17
	v_and_b32_e32 v16, 7, v16
	v_lshrrev_b32_e32 v11, 3, v9
	v_lshlrev_b32_e32 v7, 1, v7
	v_and_b32_e32 v15, 7, v15
	v_xor_b32_e32 v12, v16, v12
	v_add_u32_e32 v6, -2, v6
	v_lshlrev_b32_e32 v9, 1, v9
	v_lshl_add_u32 v13, v18, 7, 0
	v_and_b32_e32 v7, 14, v7
	v_xor_b32_e32 v11, v15, v11
	v_lshlrev_b32_e32 v12, 4, v12
	v_lshl_add_u32 v14, v17, 7, 0
	v_and_b32_e32 v9, 14, v9
	v_lshlrev_b32_e32 v11, 4, v11
	v_add3_u32 v7, v13, v12, v7
	v_add_u32_e32 v5, 0x200, v5
	v_add_u32_e32 v4, 0x200, v4
	v_add3_u32 v9, v14, v11, v9
	v_cmp_eq_u32_e32 vcc, 0, v6
	s_cbranch_vccnz .Llru32_drainP
.Llru32_loop:
	v_ashrrev_i32_e32 v179, 31, v4
	v_ashrrev_i32_e32 v162, 31, v5
	v_lshrrev_b32_e32 v179, 26, v179
	v_lshrrev_b32_e32 v162, 26, v162
	v_add_u32_e32 v179, v4, v179
	v_add_u32_e32 v16, v5, v162
	v_and_b32_e32 v163, 0xffffffc0, v16
	v_and_b32_e32 v162, 0xffffffc0, v179
	v_sub_u32_e32 v17, v5, v163
	v_sub_u32_e32 v18, v4, v162
	v_add3_u32 v162, v18, v72, v162
	v_add3_u32 v164, v17, v73, v163
	v_ashrrev_i32_e32 v165, 31, v164
	v_ashrrev_i32_e32 v163, 31, v162
	v_lshlrev_b64 v[162:163], 2, v[162:163]
	v_lshlrev_b64 v[164:165], 2, v[164:165]
	v_lshl_add_u64 v[12:13], v[0:1], 0, v[162:163]
	v_lshl_add_u64 v[14:15], v[0:1], 0, v[164:165]
	v_lshl_add_u64 v[164:165], v[2:3], 0, v[164:165]
	v_lshl_add_u64 v[162:163], v[2:3], 0, v[162:163]
	v_lshl_add_u64 v[162:163], v[162:163], 0, s[16:17]
	v_cmp_gt_i32_e32 vcc, 32, v18
	v_lshl_add_u64 v[164:165], v[164:165], 0, s[16:17]
	v_cmp_gt_i32_e64 s[0:1], 32, v17
	v_cndmask_b32_e32 v162, v162, v12, vcc
	v_cndmask_b32_e32 v163, v163, v13, vcc
	v_cndmask_b32_e64 v165, v165, v15, s[0:1]
	v_cndmask_b32_e64 v164, v164, v14, s[0:1]
	global_load_dword v164, v[164:165], off
	s_nop 0
	global_load_dword v162, v[162:163], off
	v_ashrrev_i32_e32 v179, 6, v179
	v_ashrrev_i32_e32 v163, 6, v16
	v_lshrrev_b32_e32 v16, 1, v18
	v_lshrrev_b32_e32 v12, 3, v179
	v_lshrrev_b32_e32 v15, 1, v17
	v_and_b32_e32 v16, 7, v16
	v_lshrrev_b32_e32 v165, 3, v163
	v_lshlrev_b32_e32 v179, 1, v179
	v_and_b32_e32 v15, 7, v15
	v_xor_b32_e32 v12, v16, v12
	v_add_u32_e32 v6, -2, v6
	v_lshlrev_b32_e32 v163, 1, v163
	v_lshl_add_u32 v13, v18, 7, 0
	v_and_b32_e32 v179, 14, v179
	v_xor_b32_e32 v165, v15, v165
	v_lshlrev_b32_e32 v12, 4, v12
	v_lshl_add_u32 v14, v17, 7, 0
	v_and_b32_e32 v163, 14, v163
	v_lshlrev_b32_e32 v165, 4, v165
	v_add3_u32 v179, v13, v12, v179
	v_add_u32_e32 v5, 0x200, v5
	v_add_u32_e32 v4, 0x200, v4
	v_add3_u32 v163, v14, v165, v163
	s_waitcnt vmcnt(2)
	v_and_b32_sdwa v11, v10, v170 dst_sel:DWORD dst_unused:UNUSED_PAD src0_sel:WORD_1 src1_sel:DWORD
	v_and_b32_sdwa v12, v8, v170 dst_sel:DWORD dst_unused:UNUSED_PAD src0_sel:WORD_1 src1_sel:DWORD
	v_add3_u32 v8, v8, v12, s56
	v_add3_u32 v10, v10, v11, s56
	ds_write_b16_d16_hi v7, v8 offset:16384
	ds_write_b16_d16_hi v9, v10 offset:16384
	v_cmp_eq_u32_e32 vcc, 0, v6
	s_cbranch_vccnz .Llru32_drainQ
	v_ashrrev_i32_e32 v7, 31, v4
	v_ashrrev_i32_e32 v8, 31, v5
	v_lshrrev_b32_e32 v7, 26, v7
	v_lshrrev_b32_e32 v8, 26, v8
	v_add_u32_e32 v7, v4, v7
	v_add_u32_e32 v16, v5, v8
	v_and_b32_e32 v9, 0xffffffc0, v16
	v_and_b32_e32 v8, 0xffffffc0, v7
	v_sub_u32_e32 v17, v5, v9
	v_sub_u32_e32 v18, v4, v8
	v_add3_u32 v8, v18, v72, v8
	v_add3_u32 v10, v17, v73, v9
	v_ashrrev_i32_e32 v11, 31, v10
	v_ashrrev_i32_e32 v9, 31, v8
	v_lshlrev_b64 v[8:9], 2, v[8:9]
	v_lshlrev_b64 v[10:11], 2, v[10:11]
	v_lshl_add_u64 v[12:13], v[0:1], 0, v[8:9]
	v_lshl_add_u64 v[14:15], v[0:1], 0, v[10:11]
	v_lshl_add_u64 v[10:11], v[2:3], 0, v[10:11]
	v_lshl_add_u64 v[8:9], v[2:3], 0, v[8:9]
	v_lshl_add_u64 v[8:9], v[8:9], 0, s[16:17]
	v_cmp_gt_i32_e32 vcc, 32, v18
	v_lshl_add_u64 v[10:11], v[10:11], 0, s[16:17]
	v_cmp_gt_i32_e64 s[0:1], 32, v17
	v_cndmask_b32_e32 v8, v8, v12, vcc
	v_cndmask_b32_e32 v9, v9, v13, vcc
	v_cndmask_b32_e64 v11, v11, v15, s[0:1]
	v_cndmask_b32_e64 v10, v10, v14, s[0:1]
	global_load_dword v10, v[10:11], off
	s_nop 0
	global_load_dword v8, v[8:9], off
	v_ashrrev_i32_e32 v7, 6, v7
	v_ashrrev_i32_e32 v9, 6, v16
	v_lshrrev_b32_e32 v16, 1, v18
	v_lshrrev_b32_e32 v12, 3, v7
	v_lshrrev_b32_e32 v15, 1, v17
	v_and_b32_e32 v16, 7, v16
	v_lshrrev_b32_e32 v11, 3, v9
	v_lshlrev_b32_e32 v7, 1, v7
	v_and_b32_e32 v15, 7, v15
	v_xor_b32_e32 v12, v16, v12
	v_add_u32_e32 v6, -2, v6
	v_lshlrev_b32_e32 v9, 1, v9
	v_lshl_add_u32 v13, v18, 7, 0
	v_and_b32_e32 v7, 14, v7
	v_xor_b32_e32 v11, v15, v11
	v_lshlrev_b32_e32 v12, 4, v12
	v_lshl_add_u32 v14, v17, 7, 0
	v_and_b32_e32 v9, 14, v9
	v_lshlrev_b32_e32 v11, 4, v11
	v_add3_u32 v7, v13, v12, v7
	v_add_u32_e32 v5, 0x200, v5
	v_add_u32_e32 v4, 0x200, v4
	v_add3_u32 v9, v14, v11, v9
	s_waitcnt vmcnt(2)
	v_and_b32_sdwa v165, v164, v170 dst_sel:DWORD dst_unused:UNUSED_PAD src0_sel:WORD_1 src1_sel:DWORD
	v_and_b32_sdwa v12, v162, v170 dst_sel:DWORD dst_unused:UNUSED_PAD src0_sel:WORD_1 src1_sel:DWORD
	v_add3_u32 v162, v162, v12, s56
	v_add3_u32 v164, v164, v165, s56
	ds_write_b16_d16_hi v179, v162 offset:16384
	ds_write_b16_d16_hi v163, v164 offset:16384
	v_cmp_eq_u32_e32 vcc, 0, v6
	s_cbranch_vccz .Llru32_loop
.Llru32_drainP:
	s_waitcnt vmcnt(0)
	v_and_b32_sdwa v11, v10, v170 dst_sel:DWORD dst_unused:UNUSED_PAD src0_sel:WORD_1 src1_sel:DWORD
	v_and_b32_sdwa v12, v8, v170 dst_sel:DWORD dst_unused:UNUSED_PAD src0_sel:WORD_1 src1_sel:DWORD
	v_add3_u32 v8, v8, v12, s56
	v_add3_u32 v10, v10, v11, s56
	ds_write_b16_d16_hi v7, v8 offset:16384
	ds_write_b16_d16_hi v9, v10 offset:16384
	s_branch .Llru32_done
.Llru32_drainQ:
	s_waitcnt vmcnt(0)
	v_and_b32_sdwa v165, v164, v170 dst_sel:DWORD dst_unused:UNUSED_PAD src0_sel:WORD_1 src1_sel:DWORD
	v_and_b32_sdwa v12, v162, v170 dst_sel:DWORD dst_unused:UNUSED_PAD src0_sel:WORD_1 src1_sel:DWORD
	v_add3_u32 v162, v162, v12, s56
	v_add3_u32 v164, v164, v165, s56
	ds_write_b16_d16_hi v179, v162 offset:16384
	ds_write_b16_d16_hi v163, v164 offset:16384
.Llru32_done:
	s_or_b64 exec, exec, s[40:41]
	v_readlane_b32 s0, v255, 12
	v_readlane_b32 s1, v255, 13
	s_orn2_b64 s[0:1], s[0:1], exec
	v_lshl_add_u32 v4, v227, 8, v74

.LBB0_582:
	s_add_i32 s0, s1, 2
	v_add_u32_e32 v111, v104, v105
	ds_read_b128 v[136:139], v111 offset:16384
	ds_read_b128 v[140:143], v111 offset:18432
	ds_read_b128 v[144:147], v111 offset:20480
	ds_read_b128 v[148:151], v111 offset:22528
	v_add_u32_e32 v110, v103, v105
	ds_read_b128 v[116:119], v110
	s_add_i32 s1, s1, 4
	ds_read_b128 v[120:123], v110 offset:2048
	s_min_u32 s1, s1, 63
	v_add_u32_e32 v113, v104, v114
	s_lshl_b32 s92, s1, 7
	ds_read_b128 v[124:127], v110 offset:4096
	v_add_u32_e32 v112, v103, v114
	ds_read_b128 v[194:197], v113 offset:16384
	ds_read_b128 v[198:201], v113 offset:18432
	ds_read_b128 v[202:205], v113 offset:20480
	ds_read_b128 v[206:209], v113 offset:22528
	v_lshl_add_u64 v[164:165], v[98:99], 0, s[92:93]
	ds_read_b128 v[132:135], v110 offset:6144
	ds_read_b128 v[152:155], v112
	ds_read_b128 v[156:159], v112 offset:2048
	ds_read_b128 v[160:163], v112 offset:4096
	ds_read_b128 v[190:193], v112 offset:6144
	s_waitcnt lgkmcnt(11)
	v_mfma_f32_16x16x32_bf16 v[92:95], v[136:139], v[116:119], v[92:95]
	v_mfma_f32_16x16x32_bf16 v[88:91], v[140:143], v[116:119], v[88:91]
	v_mfma_f32_16x16x32_bf16 v[52:55], v[144:147], v[116:119], v[52:55]
	v_mfma_f32_16x16x32_bf16 v[48:51], v[148:151], v[116:119], v[48:51]
	global_load_dwordx4 v[116:119], v[164:165], off
	s_waitcnt vmcnt(6)
	ds_write_b128 v109, v[56:59] offset:32768
	v_add_co_u32_e32 v56, vcc, s7, v164
	s_waitcnt lgkmcnt(11)
	v_mfma_f32_16x16x32_bf16 v[44:47], v[136:139], v[120:123], v[44:47]
	v_addc_co_u32_e32 v57, vcc, 0, v165, vcc
	v_mfma_f32_16x16x32_bf16 v[40:43], v[140:143], v[120:123], v[40:43]
	v_mfma_f32_16x16x32_bf16 v[36:39], v[144:147], v[120:123], v[36:39]
	v_mfma_f32_16x16x32_bf16 v[32:35], v[148:151], v[120:123], v[32:35]
	global_load_dwordx4 v[120:123], v[56:57], off
	v_add_co_u32_e32 v56, vcc, s52, v164
	ds_write_b128 v109, v[60:63] offset:36864
	s_nop 0
	v_addc_co_u32_e32 v57, vcc, 0, v165, vcc
	s_waitcnt lgkmcnt(11)
	v_mfma_f32_16x16x32_bf16 v[28:31], v[136:139], v[124:127], v[28:31]
	v_mfma_f32_16x16x32_bf16 v[24:27], v[140:143], v[124:127], v[24:27]
	v_mfma_f32_16x16x32_bf16 v[20:23], v[144:147], v[124:127], v[20:23]
	v_mfma_f32_16x16x32_bf16 v[16:19], v[148:151], v[124:127], v[16:19]
	global_load_dwordx4 v[124:127], v[56:57], off
	v_add_co_u32_e32 v56, vcc, s34, v164
	ds_write_b128 v109, v[64:67] offset:40960
	s_nop 0
	v_addc_co_u32_e32 v57, vcc, 0, v165, vcc
	v_lshl_add_u64 v[64:65], v[100:101], 0, s[92:93]
	v_add_co_u32_e32 v66, vcc, s7, v64
	s_waitcnt lgkmcnt(7)
	v_mfma_f32_16x16x32_bf16 v[12:15], v[136:139], v[132:135], v[12:15]
	v_addc_co_u32_e32 v67, vcc, 0, v65, vcc
	v_mfma_f32_16x16x32_bf16 v[8:11], v[140:143], v[132:135], v[8:11]
	v_mfma_f32_16x16x32_bf16 v[4:7], v[144:147], v[132:135], v[4:7]
	v_mfma_f32_16x16x32_bf16 v[0:3], v[148:151], v[132:135], v[0:3]
	global_load_dwordx4 v[132:135], v[56:57], off
	s_waitcnt vmcnt(7)
	ds_write_b128 v109, v[72:75] offset:45056
	s_waitcnt lgkmcnt(7)
	v_mfma_f32_16x16x32_bf16 v[56:59], v[194:197], v[152:155], v[92:95]
	v_mfma_f32_16x16x32_bf16 v[60:63], v[198:201], v[152:155], v[88:91]
	v_mfma_f32_16x16x32_bf16 v[52:55], v[202:205], v[152:155], v[52:55]
	v_mfma_f32_16x16x32_bf16 v[48:51], v[206:209], v[152:155], v[48:51]
	global_load_dwordx4 v[136:139], v[64:65], off
	ds_write_b128 v109, v[68:71] offset:49152
	s_waitcnt lgkmcnt(7)
	v_mfma_f32_16x16x32_bf16 v[44:47], v[194:197], v[156:159], v[44:47]
	v_mfma_f32_16x16x32_bf16 v[40:43], v[198:201], v[156:159], v[40:43]
	v_mfma_f32_16x16x32_bf16 v[36:39], v[202:205], v[156:159], v[36:39]
	v_mfma_f32_16x16x32_bf16 v[32:35], v[206:209], v[156:159], v[32:35]
	global_load_dwordx4 v[140:143], v[66:67], off
	v_add_co_u32_e32 v66, vcc, s52, v64
	s_waitcnt vmcnt(8)
	ds_write_b128 v109, v[76:79] offset:53248
	v_addc_co_u32_e32 v67, vcc, 0, v65, vcc
	v_add_co_u32_e32 v64, vcc, s34, v64
	s_waitcnt lgkmcnt(7)
	v_mfma_f32_16x16x32_bf16 v[28:31], v[194:197], v[160:163], v[28:31]
	v_addc_co_u32_e32 v65, vcc, 0, v65, vcc
	v_mfma_f32_16x16x32_bf16 v[24:27], v[198:201], v[160:163], v[24:27]
	v_mfma_f32_16x16x32_bf16 v[20:23], v[202:205], v[160:163], v[20:23]
	v_mfma_f32_16x16x32_bf16 v[16:19], v[206:209], v[160:163], v[16:19]
	global_load_dwordx4 v[144:147], v[66:67], off
	s_waitcnt vmcnt(8)
	ds_write_b128 v109, v[80:83] offset:57344
	s_waitcnt lgkmcnt(7)
	v_mfma_f32_16x16x32_bf16 v[12:15], v[194:197], v[190:193], v[12:15]
	v_mfma_f32_16x16x32_bf16 v[8:11], v[198:201], v[190:193], v[8:11]
	v_mfma_f32_16x16x32_bf16 v[4:7], v[202:205], v[190:193], v[4:7]
	v_mfma_f32_16x16x32_bf16 v[0:3], v[206:209], v[190:193], v[0:3]
	global_load_dwordx4 v[148:151], v[64:65], off
	s_waitcnt vmcnt(8)
	ds_write_b128 v109, v[84:87] offset:61440
	s_waitcnt lgkmcnt(0)
	s_barrier
	ds_read_b128 v[84:87], v111 offset:51200
	ds_read_b128 v[80:83], v111 offset:49152
	ds_read_b128 v[88:91], v111 offset:53248
	ds_read_b128 v[92:95], v111 offset:55296
	ds_read_b128 v[64:67], v110 offset:32768
	s_min_u32 s1, s0, 60
	s_lshl_b32 s92, s1, 7
	ds_read_b128 v[68:71], v110 offset:34816
	v_lshl_add_u64 v[164:165], v[98:99], 0, s[92:93]
	ds_read_b128 v[72:75], v110 offset:36864
	ds_read_b128 v[76:79], v110 offset:38912
	ds_read_b128 v[152:155], v112 offset:32768
	ds_read_b128 v[156:159], v112 offset:34816
	ds_read_b128 v[160:163], v112 offset:36864
	ds_read_b128 v[190:193], v112 offset:38912
	ds_read_b128 v[194:197], v113 offset:49152
	ds_read_b128 v[198:201], v113 offset:51200
	ds_read_b128 v[202:205], v113 offset:53248
	ds_read_b128 v[206:209], v113 offset:55296
	s_waitcnt lgkmcnt(11)
	v_mfma_f32_16x16x32_bf16 v[214:217], v[84:87], v[64:67], v[60:63]
	v_mfma_f32_16x16x32_bf16 v[210:213], v[80:83], v[64:67], v[56:59]
	s_nop 1
	v_add_co_u32_e32 v60, vcc, s7, v164
	s_nop 1
	v_addc_co_u32_e32 v61, vcc, 0, v165, vcc
	v_mfma_f32_16x16x32_bf16 v[52:55], v[88:91], v[64:67], v[52:55]
	v_mfma_f32_16x16x32_bf16 v[48:51], v[92:95], v[64:67], v[48:51]
	v_add_co_u32_e32 v64, vcc, s52, v164
	global_load_dwordx4 v[56:59], v[164:165], off offset:384
	s_nop 0
	v_addc_co_u32_e32 v65, vcc, 0, v165, vcc
	s_waitcnt vmcnt(8)
	ds_write_b128 v109, v[116:119]
	s_waitcnt lgkmcnt(11)
	v_mfma_f32_16x16x32_bf16 v[44:47], v[80:83], v[68:71], v[44:47]
	v_mfma_f32_16x16x32_bf16 v[40:43], v[84:87], v[68:71], v[40:43]
	v_mfma_f32_16x16x32_bf16 v[36:39], v[88:91], v[68:71], v[36:39]
	v_mfma_f32_16x16x32_bf16 v[32:35], v[92:95], v[68:71], v[32:35]
	v_add_co_u32_e32 v68, vcc, s34, v164
	global_load_dwordx4 v[60:63], v[60:61], off offset:384
	s_waitcnt vmcnt(8)
	ds_write_b128 v109, v[120:123] offset:4096
	s_waitcnt lgkmcnt(11)
	v_mfma_f32_16x16x32_bf16 v[28:31], v[80:83], v[72:75], v[28:31]
	v_addc_co_u32_e32 v69, vcc, 0, v165, vcc
	v_mfma_f32_16x16x32_bf16 v[24:27], v[84:87], v[72:75], v[24:27]
	v_mfma_f32_16x16x32_bf16 v[20:23], v[88:91], v[72:75], v[20:23]
	v_mfma_f32_16x16x32_bf16 v[16:19], v[92:95], v[72:75], v[16:19]
	global_load_dwordx4 v[64:67], v[64:65], off offset:384
	s_waitcnt vmcnt(8)
	ds_write_b128 v109, v[124:127] offset:8192
	s_waitcnt lgkmcnt(11)
	v_mfma_f32_16x16x32_bf16 v[8:11], v[84:87], v[76:79], v[8:11]
	v_lshl_add_u64 v[84:85], v[100:101], 0, s[92:93]
	v_mfma_f32_16x16x32_bf16 v[12:15], v[80:83], v[76:79], v[12:15]
	v_mfma_f32_16x16x32_bf16 v[4:7], v[88:91], v[76:79], v[4:7]
	v_mfma_f32_16x16x32_bf16 v[0:3], v[92:95], v[76:79], v[0:3]
	v_add_co_u32_e32 v76, vcc, s7, v84
	global_load_dwordx4 v[72:75], v[68:69], off offset:384
	s_nop 0
	v_addc_co_u32_e32 v77, vcc, 0, v85, vcc
	v_add_co_u32_e32 v80, vcc, s52, v84
	s_waitcnt vmcnt(8)
	ds_write_b128 v109, v[132:135] offset:12288
	v_addc_co_u32_e32 v81, vcc, 0, v85, vcc
	s_waitcnt lgkmcnt(7)
	v_mfma_f32_16x16x32_bf16 v[92:95], v[194:197], v[152:155], v[210:213]
	s_waitcnt lgkmcnt(6)
	v_mfma_f32_16x16x32_bf16 v[88:91], v[198:201], v[152:155], v[214:217]
	s_waitcnt lgkmcnt(5)
	v_mfma_f32_16x16x32_bf16 v[52:55], v[202:205], v[152:155], v[52:55]
	s_waitcnt lgkmcnt(4)
	v_mfma_f32_16x16x32_bf16 v[48:51], v[206:209], v[152:155], v[48:51]
	global_load_dwordx4 v[68:71], v[84:85], off offset:384
	v_add_co_u32_e32 v84, vcc, s34, v84
	s_waitcnt vmcnt(8)
	ds_write_b128 v109, v[136:139] offset:16384
	v_addc_co_u32_e32 v85, vcc, 0, v85, vcc
	v_mfma_f32_16x16x32_bf16 v[44:47], v[194:197], v[156:159], v[44:47]
	v_mfma_f32_16x16x32_bf16 v[40:43], v[198:201], v[156:159], v[40:43]
	v_mfma_f32_16x16x32_bf16 v[36:39], v[202:205], v[156:159], v[36:39]
	v_mfma_f32_16x16x32_bf16 v[32:35], v[206:209], v[156:159], v[32:35]
	global_load_dwordx4 v[76:79], v[76:77], off offset:384
	s_waitcnt vmcnt(8)
	ds_write_b128 v109, v[140:143] offset:20480
	v_mfma_f32_16x16x32_bf16 v[28:31], v[194:197], v[160:163], v[28:31]
	v_mfma_f32_16x16x32_bf16 v[24:27], v[198:201], v[160:163], v[24:27]
	v_mfma_f32_16x16x32_bf16 v[20:23], v[202:205], v[160:163], v[20:23]
	v_mfma_f32_16x16x32_bf16 v[16:19], v[206:209], v[160:163], v[16:19]
	global_load_dwordx4 v[80:83], v[80:81], off offset:384
	s_waitcnt vmcnt(8)
	ds_write_b128 v109, v[144:147] offset:24576
	v_mfma_f32_16x16x32_bf16 v[12:15], v[194:197], v[190:193], v[12:15]
	v_mfma_f32_16x16x32_bf16 v[8:11], v[198:201], v[190:193], v[8:11]
	v_mfma_f32_16x16x32_bf16 v[4:7], v[202:205], v[190:193], v[4:7]
	v_mfma_f32_16x16x32_bf16 v[0:3], v[206:209], v[190:193], v[0:3]
	global_load_dwordx4 v[84:87], v[84:85], off offset:384
	s_waitcnt vmcnt(8)
	ds_write_b128 v109, v[148:151] offset:28672
	s_cmp_lt_u32 s0, 62
	s_mov_b32 s1, s0
	s_waitcnt lgkmcnt(0)
	s_barrier
	s_cbranch_scc1 .LBB0_582
	s_or_b32 s0, s69, 1
	s_mul_i32 s1, s69, 0x12000
	v_readlane_b32 s26, v250, 25
	v_readlane_b32 s27, v250, 26
	s_add_u32 s1, s26, s1
	s_addc_u32 s24, s27, 0
	s_add_u32 s38, s1, 0x5000
	v_readlane_b32 s1, v251, 5
	v_lshlrev_b32_e32 v114, 6, v102
	v_lshlrev_b32_e32 v115, 2, v97
	s_waitcnt vmcnt(5)
	v_add_u32_e32 v64, s1, v108
	v_readlane_b32 s1, v251, 6
	v_add_u32_e32 v56, 0xffffe000, v64
	v_or_b32_e32 v62, v64, v107
	v_or_b32_e32 v65, s1, v114
	v_lshrrev_b32_e32 v56, 10, v56
	s_movk_i32 s1, 0x1800
	v_mad_u32_u24 v56, v56, s1, s1
	v_cmp_lt_i32_e32 vcc, s13, v62
	v_or_b32_e32 v58, v65, v115
	s_addc_u32 s39, s24, 0
	v_cndmask_b32_e32 v56, 0, v56, vcc
	v_ashrrev_i32_e32 v57, 31, v56
	s_waitcnt vmcnt(4)
	v_lshlrev_b64 v[74:75], 2, v[56:57]
	v_ashrrev_i32_e32 v59, 31, v58
	v_ashrrev_i32_e32 v63, 31, v62
	v_lshl_add_u64 v[56:57], s[38:39], 0, v[74:75]
	v_lshlrev_b64 v[60:61], 2, v[58:59]
	v_readlane_b32 s16, v250, 15
	s_waitcnt vmcnt(1)
	v_lshl_add_u64 v[82:83], v[56:57], 0, v[60:61]
	v_lshlrev_b64 v[56:57], 12, v[62:63]
	v_readlane_b32 s17, v250, 16
	v_readlane_b32 s68, v250, 41
	s_mul_i32 s24, s0, 0x12000
	v_lshl_add_u64 v[56:57], s[16:17], 0, v[56:57]
	s_waitcnt vmcnt(0)
	v_lshl_add_u64 v[84:85], v[56:57], 0, v[60:61]
	global_load_dwordx4 v[116:119], v[82:83], off
	global_load_dwordx4 v[120:123], v[82:83], off offset:64
	global_load_dwordx4 v[124:127], v[82:83], off offset:128
	global_load_dwordx4 v[132:135], v[82:83], off offset:192
	global_load_dwordx4 v[190:193], v[84:85], off
	global_load_dwordx4 v[194:197], v[84:85], off offset:64
	global_load_dwordx4 v[198:201], v[84:85], off offset:128
	global_load_dwordx4 v[202:205], v[84:85], off offset:192
	v_add_co_u32_e32 v164, vcc, 0x10000, v84
	s_nop 1
	v_addc_co_u32_e32 v165, vcc, 0, v85, vcc
	v_add_co_u32_e32 v222, vcc, 0x20000, v84
	s_nop 1
	v_addc_co_u32_e32 v223, vcc, 0, v85, vcc
	v_add_co_u32_e32 v224, vcc, 0x30000, v84
	s_nop 1
	v_addc_co_u32_e32 v225, vcc, 0, v85, vcc
	global_load_dwordx4 v[206:209], v[164:165], off
	global_load_dwordx4 v[210:213], v[164:165], off offset:64
	global_load_dwordx4 v[214:217], v[164:165], off offset:128
	global_load_dwordx4 v[218:221], v[164:165], off offset:192
	s_lshl_b32 s0, s0, 12
	v_readlane_b32 s70, v250, 43
	v_readlane_b32 s71, v250, 44
	s_add_u32 s0, s70, s0
	s_addc_u32 s1, s71, 0
	s_add_u32 s24, s26, s24
	s_addc_u32 s25, s27, 0
	s_add_u32 s40, s24, 0x1000
	s_addc_u32 s41, s25, 0
	v_lshl_add_u64 v[74:75], s[40:41], 0, v[74:75]
	v_lshl_add_u64 v[56:57], s[0:1], 0, v[60:61]
	v_lshl_add_u64 v[86:87], v[74:75], 0, v[60:61]
	v_readlane_b32 s16, v250, 21
	v_lshlrev_b64 v[78:79], 11, v[62:63]
	v_readlane_b32 s17, v250, 22
	v_readlane_b32 s69, v250, 42
	v_readlane_b32 s69, v254, 49
	v_lshl_add_u64 v[78:79], s[16:17], 0, v[78:79]
	s_mul_i32 s24, s69, 0x140000
	s_add_u32 s24, s86, s24
	s_mov_b32 s16, 0xa000
	s_addc_u32 s25, s87, 0
	s_add_u32 s26, s24, 0xafba000
	s_addc_u32 s27, s25, 0
	v_cmp_eq_u32_e64 s[36:37], 0, v97
	v_readlane_b32 s72, v250, 45
	v_readlane_b32 s73, v250, 46
	v_readlane_b32 s74, v250, 47
	v_readlane_b32 s75, v250, 48
	v_readlane_b32 s76, v250, 49
	v_readlane_b32 s77, v250, 50
	v_readlane_b32 s78, v250, 51
	v_readlane_b32 s79, v250, 52
	v_readlane_b32 s80, v250, 53
	v_readlane_b32 s81, v250, 54
	v_readlane_b32 s82, v250, 55
	v_readlane_b32 s83, v250, 56
	global_load_dwordx4 v[136:139], v[56:57], off
	global_load_dwordx4 v[140:143], v[56:57], off offset:64
	global_load_dwordx4 v[144:147], v[56:57], off offset:128
	global_load_dwordx4 v[148:151], v[56:57], off offset:192
	global_load_dwordx4 v[152:155], v[86:87], off
	global_load_dwordx4 v[156:159], v[86:87], off offset:64
	global_load_dwordx4 v[160:163], v[86:87], off offset:128
	global_load_dwordx4 v[180:183], v[86:87], off offset:192
	s_waitcnt vmcnt(0)
	v_pk_fma_f32 v[68:69], v[94:95], v[118:119], v[192:193]
	v_pk_fma_f32 v[66:67], v[92:93], v[116:117], v[190:191]
	global_store_dwordx4 v[84:85], v[66:69], off
	v_lshl_add_u64 v[92:93], v[58:59], 1, v[78:79]
	s_waitcnt vmcnt(0)
	v_pk_mul_f32 v[72:73], v[68:69], v[138:139]
	v_pk_mul_f32 v[70:71], v[66:67], v[136:137]
	s_waitcnt vmcnt(0)
	v_pk_add_f32 v[76:77], v[154:155], 1.0 op_sel_hi:[1,0]
	v_pk_add_f32 v[74:75], v[152:153], 1.0 op_sel_hi:[1,0]
	v_pk_mul_f32 v[72:73], v[72:73], v[76:77]
	v_pk_mul_f32 v[70:71], v[70:71], v[74:75]
	v_and_b32_sdwa v76, v73, v170 dst_sel:DWORD dst_unused:UNUSED_PAD src0_sel:WORD_1 src1_sel:DWORD
	v_and_b32_sdwa v77, v71, v170 dst_sel:DWORD dst_unused:UNUSED_PAD src0_sel:WORD_1 src1_sel:DWORD
	v_and_b32_sdwa v74, v72, v170 dst_sel:DWORD dst_unused:UNUSED_PAD src0_sel:WORD_1 src1_sel:DWORD
	v_and_b32_sdwa v75, v70, v170 dst_sel:DWORD dst_unused:UNUSED_PAD src0_sel:WORD_1 src1_sel:DWORD
	v_add3_u32 v73, v73, v76, s56
	v_add3_u32 v71, v71, v77, s56
	v_add3_u32 v70, v70, v75, s56
	v_add3_u32 v72, v72, v74, s56
	v_and_b32_e32 v73, 0xffff0000, v73
	v_and_b32_e32 v74, 0xffff0000, v71
	v_or_b32_sdwa v71, v73, v72 dst_sel:DWORD dst_unused:UNUSED_PAD src0_sel:DWORD src1_sel:WORD_1
	v_or_b32_sdwa v70, v74, v70 dst_sel:DWORD dst_unused:UNUSED_PAD src0_sel:DWORD src1_sel:WORD_1
	global_store_dwordx2 v[92:93], v[70:71], off
	s_nop 0
	s_waitcnt vmcnt(0)
	v_pk_fma_f32 v[72:73], v[90:91], v[122:123], v[196:197]
	v_pk_fma_f32 v[70:71], v[88:89], v[120:121], v[194:195]
	global_store_dwordx4 v[84:85], v[70:73], off offset:64
	v_pk_mul_f32 v[76:77], v[72:73], v[142:143]
	v_pk_mul_f32 v[74:75], v[70:71], v[140:141]
	v_pk_add_f32 v[80:81], v[158:159], 1.0 op_sel_hi:[1,0]
	v_pk_add_f32 v[78:79], v[156:157], 1.0 op_sel_hi:[1,0]
	v_pk_mul_f32 v[76:77], v[76:77], v[80:81]
	v_pk_mul_f32 v[74:75], v[74:75], v[78:79]
	v_and_b32_sdwa v80, v77, v170 dst_sel:DWORD dst_unused:UNUSED_PAD src0_sel:WORD_1 src1_sel:DWORD
	v_and_b32_sdwa v81, v75, v170 dst_sel:DWORD dst_unused:UNUSED_PAD src0_sel:WORD_1 src1_sel:DWORD
	v_and_b32_sdwa v78, v76, v170 dst_sel:DWORD dst_unused:UNUSED_PAD src0_sel:WORD_1 src1_sel:DWORD
	v_and_b32_sdwa v79, v74, v170 dst_sel:DWORD dst_unused:UNUSED_PAD src0_sel:WORD_1 src1_sel:DWORD
	v_add3_u32 v77, v77, v80, s56
	v_add3_u32 v75, v75, v81, s56
	v_add3_u32 v74, v74, v79, s56
	v_add3_u32 v76, v76, v78, s56
	v_and_b32_e32 v77, 0xffff0000, v77
	v_and_b32_e32 v78, 0xffff0000, v75
	v_or_b32_sdwa v75, v77, v76 dst_sel:DWORD dst_unused:UNUSED_PAD src0_sel:DWORD src1_sel:WORD_1
	v_or_b32_sdwa v74, v78, v74 dst_sel:DWORD dst_unused:UNUSED_PAD src0_sel:DWORD src1_sel:WORD_1
	global_store_dwordx2 v[92:93], v[74:75], off offset:32
	s_nop 0
	v_pk_fma_f32 v[54:55], v[54:55], v[126:127], v[200:201]
	v_pk_fma_f32 v[52:53], v[52:53], v[124:125], v[198:199]
	global_store_dwordx4 v[84:85], v[52:55], off offset:128
	v_pk_mul_f32 v[76:77], v[54:55], v[146:147]
	v_pk_mul_f32 v[74:75], v[52:53], v[144:145]
	v_pk_add_f32 v[80:81], v[162:163], 1.0 op_sel_hi:[1,0]
	v_pk_add_f32 v[78:79], v[160:161], 1.0 op_sel_hi:[1,0]
	v_pk_mul_f32 v[76:77], v[76:77], v[80:81]
	v_pk_mul_f32 v[74:75], v[74:75], v[78:79]
	v_and_b32_sdwa v80, v77, v170 dst_sel:DWORD dst_unused:UNUSED_PAD src0_sel:WORD_1 src1_sel:DWORD
	v_and_b32_sdwa v81, v75, v170 dst_sel:DWORD dst_unused:UNUSED_PAD src0_sel:WORD_1 src1_sel:DWORD
	v_and_b32_sdwa v78, v76, v170 dst_sel:DWORD dst_unused:UNUSED_PAD src0_sel:WORD_1 src1_sel:DWORD
	v_and_b32_sdwa v79, v74, v170 dst_sel:DWORD dst_unused:UNUSED_PAD src0_sel:WORD_1 src1_sel:DWORD
	v_add3_u32 v77, v77, v80, s56
	v_add3_u32 v75, v75, v81, s56
	v_add3_u32 v74, v74, v79, s56
	v_add3_u32 v76, v76, v78, s56
	v_and_b32_e32 v77, 0xffff0000, v77
	v_and_b32_e32 v78, 0xffff0000, v75
	v_or_b32_sdwa v75, v77, v76 dst_sel:DWORD dst_unused:UNUSED_PAD src0_sel:DWORD src1_sel:WORD_1
	v_or_b32_sdwa v74, v78, v74 dst_sel:DWORD dst_unused:UNUSED_PAD src0_sel:DWORD src1_sel:WORD_1
	global_store_dwordx2 v[92:93], v[74:75], off offset:64
	s_nop 0
	v_pk_fma_f32 v[76:77], v[50:51], v[134:135], v[204:205]
	v_pk_fma_f32 v[74:75], v[48:49], v[132:133], v[202:203]
	global_store_dwordx4 v[84:85], v[74:77], off offset:192
	s_nop 0
	v_mul_f32_e32 v50, v67, v67
	v_mul_f32_e32 v51, v71, v71
	v_fmac_f32_e32 v50, v66, v66
	v_fmac_f32_e32 v51, v70, v70
	v_fmac_f32_e32 v50, v68, v68
	v_fmac_f32_e32 v51, v72, v72
	v_fmac_f32_e32 v50, v69, v69
	v_fmac_f32_e32 v51, v73, v73
	v_add_f32_e32 v50, v50, v51
	v_mul_f32_e32 v51, v53, v53
	v_fmac_f32_e32 v51, v52, v52
	v_fmac_f32_e32 v51, v54, v54
	v_fmac_f32_e32 v51, v55, v55
	v_add_f32_e32 v50, v50, v51
	v_mul_f32_e32 v51, v75, v75
	v_xor_b32_e32 v48, 16, v176
	v_fmac_f32_e32 v51, v74, v74
	v_cmp_lt_i32_e32 vcc, v48, v177
	v_fmac_f32_e32 v51, v76, v76
	v_fmac_f32_e32 v51, v77, v77
	v_cndmask_b32_e32 v48, v176, v48, vcc
	v_lshlrev_b32_e32 v105, 2, v48
	v_add_f32_e32 v50, v50, v51
	ds_bpermute_b32 v51, v105, v50
	v_xor_b32_e32 v49, 32, v176
	v_cmp_lt_i32_e32 vcc, v49, v177
	v_lshrrev_b32_e32 v48, 6, v65
	v_mul_lo_u32 v48, v48, s16
	v_cndmask_b32_e32 v49, v176, v49, vcc
	v_lshlrev_b32_e32 v104, 2, v49
	s_waitcnt lgkmcnt(0)
	v_add_f32_e32 v50, v50, v51
	ds_bpermute_b32 v51, v104, v50
	v_ashrrev_i32_e32 v49, 31, v48
	v_lshl_add_u64 v[48:49], s[26:27], 0, v[48:49]
	v_lshl_add_u64 v[48:49], v[62:63], 2, v[48:49]
	v_pk_mul_f32 v[52:53], v[76:77], v[150:151]
	v_pk_mul_f32 v[54:55], v[74:75], v[148:149]
	v_pk_add_f32 v[66:67], v[182:183], 1.0 op_sel_hi:[1,0]
	v_pk_add_f32 v[68:69], v[180:181], 1.0 op_sel_hi:[1,0]
	v_pk_mul_f32 v[52:53], v[52:53], v[66:67]
	v_pk_mul_f32 v[54:55], v[54:55], v[68:69]
	v_and_b32_sdwa v67, v53, v170 dst_sel:DWORD dst_unused:UNUSED_PAD src0_sel:WORD_1 src1_sel:DWORD
	v_and_b32_sdwa v68, v55, v170 dst_sel:DWORD dst_unused:UNUSED_PAD src0_sel:WORD_1 src1_sel:DWORD
	v_and_b32_sdwa v65, v52, v170 dst_sel:DWORD dst_unused:UNUSED_PAD src0_sel:WORD_1 src1_sel:DWORD
	v_and_b32_sdwa v66, v54, v170 dst_sel:DWORD dst_unused:UNUSED_PAD src0_sel:WORD_1 src1_sel:DWORD
	v_add3_u32 v53, v53, v67, s56
	v_add3_u32 v55, v55, v68, s56
	v_add3_u32 v54, v54, v66, s56
	v_add3_u32 v52, v52, v65, s56
	v_and_b32_e32 v53, 0xffff0000, v53
	v_and_b32_e32 v55, 0xffff0000, v55
	v_or_b32_sdwa v53, v53, v52 dst_sel:DWORD dst_unused:UNUSED_PAD src0_sel:DWORD src1_sel:WORD_1
	v_or_b32_sdwa v52, v55, v54 dst_sel:DWORD dst_unused:UNUSED_PAD src0_sel:DWORD src1_sel:WORD_1
	global_store_dwordx2 v[92:93], v[52:53], off offset:96
	s_and_saveexec_b64 s[24:25], s[36:37]
	s_cbranch_execz .LBB0_585
	s_waitcnt lgkmcnt(0)
	v_add_f32_e32 v50, v50, v51
	global_store_dword v[48:49], v50, off

.LBB0_609:
	s_add_i32 s2, s3, 2
	v_add_u32_e32 v127, v89, v90
	ds_read_b128 v[100:103], v127 offset:16384
	ds_read_b128 v[106:109], v127 offset:18432
	ds_read_b128 v[110:113], v127 offset:20480
	ds_read_b128 v[114:117], v127 offset:22528
	v_add_u32_e32 v126, v88, v90
	ds_read_b128 v[92:95], v126
	ds_read_b128 v[96:99], v126 offset:2048
	s_add_i32 s3, s3, 4
	s_min_u32 s3, s3, 63
	v_add_u32_e32 v128, v88, v91
	v_add_u32_e32 v130, v89, v91
	s_lshl_b32 s92, s3, 7
	ds_read_b128 v[118:121], v130 offset:18432
	ds_read_b128 v[122:125], v130 offset:20480
	ds_read_b128 v[132:135], v130 offset:22528
	s_waitcnt lgkmcnt(4)
	v_mfma_f32_16x16x32_bf16 v[76:79], v[100:103], v[92:95], v[76:79]
	v_lshl_add_u64 v[44:45], v[80:81], 0, s[92:93]
	v_add_co_u32_e32 v46, vcc, s7, v44
	v_mfma_f32_16x16x32_bf16 v[68:71], v[106:109], v[92:95], v[68:71]
	s_nop 0
	v_addc_co_u32_e32 v47, vcc, 0, v45, vcc
	v_mfma_f32_16x16x32_bf16 v[52:55], v[110:113], v[92:95], v[52:55]
	v_mfma_f32_16x16x32_bf16 v[40:43], v[114:117], v[92:95], v[40:43]
	s_waitcnt lgkmcnt(3)
	v_mfma_f32_16x16x32_bf16 v[92:95], v[100:103], v[96:99], v[36:39]
	s_nop 2
	ds_read_b128 v[36:39], v128
	v_mfma_f32_16x16x32_bf16 v[100:103], v[106:109], v[96:99], v[8:11]
	v_mfma_f32_16x16x32_bf16 v[106:109], v[110:113], v[96:99], v[4:7]
	ds_read_b128 v[110:113], v128 offset:2048
	v_mfma_f32_16x16x32_bf16 v[96:99], v[114:117], v[96:99], v[0:3]
	ds_read_b128 v[114:117], v130 offset:16384
	global_load_dwordx4 v[72:75], v[44:45], off
	s_waitcnt vmcnt(1)
	ds_write_b128 v87, v[12:15] offset:53248
	global_load_dwordx4 v[64:67], v[46:47], off
	v_add_co_u32_e32 v46, vcc, s52, v44
	ds_write_b128 v87, v[16:19] offset:49152
	s_nop 0
	v_addc_co_u32_e32 v47, vcc, 0, v45, vcc
	v_add_co_u32_e32 v44, vcc, s34, v44
	global_load_dwordx4 v[60:63], v[46:47], off
	s_nop 0
	v_addc_co_u32_e32 v45, vcc, 0, v45, vcc
	ds_write_b128 v87, v[20:23] offset:45056
	global_load_dwordx4 v[56:59], v[44:45], off
	v_lshl_add_u64 v[44:45], v[82:83], 0, s[92:93]
	ds_write_b128 v87, v[28:31] offset:32768
	s_waitcnt lgkmcnt(4)
	v_mfma_f32_16x16x32_bf16 v[0:3], v[114:117], v[36:39], v[76:79]
	v_mfma_f32_16x16x32_bf16 v[4:7], v[118:121], v[36:39], v[68:71]
	global_load_dwordx4 v[48:51], v[44:45], off
	v_add_co_u32_e32 v44, vcc, s7, v44
	ds_write_b128 v87, v[32:35] offset:36864
	s_nop 0
	v_addc_co_u32_e32 v45, vcc, 0, v45, vcc
	v_mfma_f32_16x16x32_bf16 v[8:11], v[122:125], v[36:39], v[52:55]
	v_mfma_f32_16x16x32_bf16 v[36:39], v[132:135], v[36:39], v[40:43]
	global_load_dwordx4 v[44:47], v[44:45], off
	ds_write_b128 v87, v[24:27] offset:40960
	v_mfma_f32_16x16x32_bf16 v[40:43], v[114:117], v[110:113], v[92:95]
	v_mfma_f32_16x16x32_bf16 v[52:55], v[118:121], v[110:113], v[100:103]
	v_mfma_f32_16x16x32_bf16 v[68:71], v[122:125], v[110:113], v[106:109]
	v_mfma_f32_16x16x32_bf16 v[76:79], v[132:135], v[110:113], v[96:99]
	s_waitcnt lgkmcnt(0)
	s_barrier
	ds_read_b128 v[100:103], v127 offset:49152
	ds_read_b128 v[106:109], v127 offset:51200
	ds_read_b128 v[110:113], v127 offset:53248
	ds_read_b128 v[114:117], v127 offset:55296
	ds_read_b128 v[92:95], v126 offset:32768
	ds_read_b128 v[96:99], v126 offset:34816
	s_min_u32 s3, s2, 60
	s_lshl_b32 s92, s3, 7
	ds_read_b128 v[118:121], v130 offset:51200
	ds_read_b128 v[122:125], v130 offset:53248
	ds_read_b128 v[132:135], v130 offset:55296
	s_waitcnt lgkmcnt(4)
	v_mfma_f32_16x16x32_bf16 v[0:3], v[100:103], v[92:95], v[0:3]
	v_lshl_add_u64 v[12:13], v[80:81], 0, s[92:93]
	v_add_co_u32_e32 v14, vcc, s7, v12
	v_mfma_f32_16x16x32_bf16 v[4:7], v[106:109], v[92:95], v[4:7]
	s_nop 0
	v_addc_co_u32_e32 v15, vcc, 0, v13, vcc
	v_mfma_f32_16x16x32_bf16 v[8:11], v[110:113], v[92:95], v[8:11]
	v_mfma_f32_16x16x32_bf16 v[36:39], v[114:117], v[92:95], v[36:39]
	s_waitcnt lgkmcnt(3)
	v_mfma_f32_16x16x32_bf16 v[92:95], v[100:103], v[96:99], v[40:43]
	s_nop 2
	ds_read_b128 v[40:43], v128 offset:32768
	v_mfma_f32_16x16x32_bf16 v[100:103], v[106:109], v[96:99], v[52:55]
	v_mfma_f32_16x16x32_bf16 v[106:109], v[110:113], v[96:99], v[68:71]
	ds_read_b128 v[110:113], v128 offset:34816
	v_mfma_f32_16x16x32_bf16 v[96:99], v[114:117], v[96:99], v[76:79]
	ds_read_b128 v[114:117], v130 offset:49152
	global_load_dwordx4 v[28:31], v[12:13], off offset:384
	s_waitcnt vmcnt(1)
	ds_write_b128 v87, v[44:47] offset:20480
	global_load_dwordx4 v[32:35], v[14:15], off offset:384
	v_add_co_u32_e32 v14, vcc, s52, v12
	ds_write_b128 v87, v[48:51] offset:16384
	s_nop 0
	v_addc_co_u32_e32 v15, vcc, 0, v13, vcc
	v_add_co_u32_e32 v12, vcc, s34, v12
	global_load_dwordx4 v[24:27], v[14:15], off offset:384
	s_nop 0
	v_addc_co_u32_e32 v13, vcc, 0, v13, vcc
	ds_write_b128 v87, v[56:59] offset:12288
	global_load_dwordx4 v[20:23], v[12:13], off offset:384
	v_lshl_add_u64 v[12:13], v[82:83], 0, s[92:93]
	ds_write_b128 v87, v[72:75]
	s_waitcnt lgkmcnt(4)
	v_mfma_f32_16x16x32_bf16 v[76:79], v[114:117], v[40:43], v[0:3]
	v_mfma_f32_16x16x32_bf16 v[68:71], v[118:121], v[40:43], v[4:7]
	global_load_dwordx4 v[16:19], v[12:13], off offset:384
	v_add_co_u32_e32 v12, vcc, s7, v12
	ds_write_b128 v87, v[64:67] offset:4096
	s_nop 0
	v_addc_co_u32_e32 v13, vcc, 0, v13, vcc
	v_mfma_f32_16x16x32_bf16 v[52:55], v[122:125], v[40:43], v[8:11]
	v_mfma_f32_16x16x32_bf16 v[40:43], v[132:135], v[40:43], v[36:39]
	global_load_dwordx4 v[12:15], v[12:13], off offset:384
	ds_write_b128 v87, v[60:63] offset:8192
	v_mfma_f32_16x16x32_bf16 v[36:39], v[114:117], v[110:113], v[92:95]
	v_mfma_f32_16x16x32_bf16 v[8:11], v[118:121], v[110:113], v[100:103]
	v_mfma_f32_16x16x32_bf16 v[4:7], v[122:125], v[110:113], v[106:109]
	v_mfma_f32_16x16x32_bf16 v[0:3], v[132:135], v[110:113], v[96:99]
	s_cmp_lt_u32 s2, 62
	s_mov_b32 s3, s2
	s_waitcnt lgkmcnt(0)
	s_barrier
	s_cbranch_scc1 .LBB0_609
	v_readlane_b32 s2, v251, 18
	s_waitcnt vmcnt(1)
	s_nop 0
	v_add_u32_e32 v18, s2, v86
	v_readlane_b32 s2, v251, 19
	s_waitcnt vmcnt(0)
	v_add_u32_e32 v13, 0xffffe000, v18
	v_or_b32_e32 v12, v18, v85
	v_lshl_or_b32 v19, v84, 2, s2
	v_lshrrev_b32_e32 v13, 10, v13
	s_movk_i32 s2, 0x1800
	v_mad_u32_u24 v13, v13, s2, s2
	v_cmp_lt_i32_e32 vcc, s13, v12
	v_lshlrev_b32_e32 v128, 2, v19
	v_readlane_b32 s2, v250, 15
	v_cndmask_b32_e32 v14, 0, v13, vcc
	v_ashrrev_i32_e32 v15, 31, v14
	v_lshlrev_b64 v[24:25], 2, v[14:15]
	v_ashrrev_i32_e32 v13, 31, v12
	v_lshl_add_u64 v[14:15], s[38:39], 0, v[24:25]
	v_lshl_add_u64 v[48:49], v[14:15], 0, v[128:129]
	v_lshlrev_b64 v[14:15], 12, v[12:13]
	v_readlane_b32 s3, v250, 16
	v_lshl_add_u64 v[28:29], s[40:41], 0, v[24:25]
	v_lshlrev_b64 v[32:33], 11, v[12:13]
	v_lshl_add_u64 v[14:15], s[2:3], 0, v[14:15]
	v_lshl_add_u64 v[50:51], v[14:15], 0, v[128:129]
	global_load_dwordx4 v[72:75], v[48:49], off
	global_load_dwordx4 v[80:83], v[48:49], off offset:64
	global_load_dwordx4 v[88:91], v[48:49], off offset:128
	global_load_dwordx4 v[136:139], v[48:49], off offset:192
	global_load_dwordx4 v[194:197], v[50:51], off
	global_load_dwordx4 v[198:201], v[50:51], off offset:64
	global_load_dwordx4 v[202:205], v[50:51], off offset:128
	global_load_dwordx4 v[206:209], v[50:51], off offset:192
	v_add_co_u32_e32 v58, vcc, 0x10000, v50
	s_nop 1
	v_addc_co_u32_e32 v59, vcc, 0, v51, vcc
	global_load_dwordx4 v[210:213], v[58:59], off
	global_load_dwordx4 v[214:217], v[58:59], off offset:64
	global_load_dwordx4 v[218:221], v[58:59], off offset:128
	global_load_dwordx4 v[222:225], v[58:59], off offset:192
	v_readlane_b32 s2, v250, 21
	v_readlane_b32 s3, v250, 22
	v_cmp_eq_u32_e32 vcc, 0, v84
	global_load_dwordx4 v[140:143], v128, s[0:1]
	global_load_dwordx4 v[144:147], v128, s[0:1] offset:64
	global_load_dwordx4 v[148:151], v128, s[0:1] offset:128
	global_load_dwordx4 v[152:155], v128, s[0:1] offset:192
	s_waitcnt vmcnt(0)
	v_pk_fma_f32 v[22:23], v[78:79], v[74:75], v[196:197]
	v_pk_fma_f32 v[20:21], v[76:77], v[72:73], v[194:195]
	global_store_dwordx4 v[50:51], v[20:23], off
	v_lshl_add_u64 v[14:15], v[28:29], 0, v[128:129]
	global_load_dwordx4 v[156:159], v[14:15], off
	global_load_dwordx4 v[160:163], v[14:15], off offset:64
	global_load_dwordx4 v[180:183], v[14:15], off offset:128
	global_load_dwordx4 v[190:193], v[14:15], off offset:192
	v_lshlrev_b32_e32 v16, 1, v19
	v_mov_b32_e32 v17, v129
	v_lshl_add_u64 v[32:33], s[2:3], 0, v[32:33]
	v_lshl_add_u64 v[56:57], v[32:33], 0, v[16:17]
	s_waitcnt vmcnt(0)
	v_pk_mul_f32 v[26:27], v[22:23], v[142:143]
	v_pk_mul_f32 v[24:25], v[20:21], v[140:141]
	s_waitcnt vmcnt(0)
	v_pk_add_f32 v[30:31], v[158:159], 1.0 op_sel_hi:[1,0]
	v_pk_add_f32 v[28:29], v[156:157], 1.0 op_sel_hi:[1,0]
	v_pk_mul_f32 v[26:27], v[26:27], v[30:31]
	v_pk_mul_f32 v[24:25], v[24:25], v[28:29]
	v_and_b32_sdwa v19, v26, v170 dst_sel:DWORD dst_unused:UNUSED_PAD src0_sel:WORD_1 src1_sel:DWORD
	v_and_b32_sdwa v29, v27, v170 dst_sel:DWORD dst_unused:UNUSED_PAD src0_sel:WORD_1 src1_sel:DWORD
	v_and_b32_sdwa v30, v25, v170 dst_sel:DWORD dst_unused:UNUSED_PAD src0_sel:WORD_1 src1_sel:DWORD
	v_and_b32_sdwa v28, v24, v170 dst_sel:DWORD dst_unused:UNUSED_PAD src0_sel:WORD_1 src1_sel:DWORD
	v_add3_u32 v19, v26, v19, s56
	v_add3_u32 v26, v27, v29, s56
	v_add3_u32 v25, v25, v30, s56
	v_add3_u32 v24, v24, v28, s56
	v_and_b32_e32 v26, 0xffff0000, v26
	v_and_b32_e32 v27, 0xffff0000, v25
	v_or_b32_sdwa v25, v26, v19 dst_sel:DWORD dst_unused:UNUSED_PAD src0_sel:DWORD src1_sel:WORD_1
	v_or_b32_sdwa v24, v27, v24 dst_sel:DWORD dst_unused:UNUSED_PAD src0_sel:DWORD src1_sel:WORD_1
	global_store_dwordx2 v[56:57], v[24:25], off
	s_nop 0
	s_waitcnt vmcnt(0)
	v_pk_fma_f32 v[26:27], v[70:71], v[82:83], v[200:201]
	v_pk_fma_f32 v[24:25], v[68:69], v[80:81], v[198:199]
	global_store_dwordx4 v[50:51], v[24:27], off offset:64
	v_pk_mul_f32 v[30:31], v[26:27], v[146:147]
	v_pk_mul_f32 v[28:29], v[24:25], v[144:145]
	v_pk_add_f32 v[34:35], v[162:163], 1.0 op_sel_hi:[1,0]
	v_pk_add_f32 v[32:33], v[160:161], 1.0 op_sel_hi:[1,0]
	v_pk_mul_f32 v[30:31], v[30:31], v[34:35]
	v_pk_mul_f32 v[28:29], v[28:29], v[32:33]
	v_and_b32_sdwa v19, v30, v170 dst_sel:DWORD dst_unused:UNUSED_PAD src0_sel:WORD_1 src1_sel:DWORD
	v_and_b32_sdwa v33, v31, v170 dst_sel:DWORD dst_unused:UNUSED_PAD src0_sel:WORD_1 src1_sel:DWORD
	v_and_b32_sdwa v34, v29, v170 dst_sel:DWORD dst_unused:UNUSED_PAD src0_sel:WORD_1 src1_sel:DWORD
	v_and_b32_sdwa v32, v28, v170 dst_sel:DWORD dst_unused:UNUSED_PAD src0_sel:WORD_1 src1_sel:DWORD
	v_add3_u32 v19, v30, v19, s56
	v_add3_u32 v30, v31, v33, s56
	v_add3_u32 v29, v29, v34, s56
	v_add3_u32 v28, v28, v32, s56
	v_and_b32_e32 v30, 0xffff0000, v30
	v_and_b32_e32 v31, 0xffff0000, v29
	v_or_b32_sdwa v29, v30, v19 dst_sel:DWORD dst_unused:UNUSED_PAD src0_sel:DWORD src1_sel:WORD_1
	v_or_b32_sdwa v28, v31, v28 dst_sel:DWORD dst_unused:UNUSED_PAD src0_sel:DWORD src1_sel:WORD_1
	global_store_dwordx2 v[56:57], v[28:29], off offset:32
	s_nop 0
	v_pk_fma_f32 v[30:31], v[54:55], v[90:91], v[204:205]
	v_pk_fma_f32 v[28:29], v[52:53], v[88:89], v[202:203]
	global_store_dwordx4 v[50:51], v[28:31], off offset:128
	v_pk_mul_f32 v[34:35], v[30:31], v[150:151]
	v_pk_mul_f32 v[32:33], v[28:29], v[148:149]
	v_pk_add_f32 v[46:47], v[182:183], 1.0 op_sel_hi:[1,0]
	v_pk_add_f32 v[44:45], v[180:181], 1.0 op_sel_hi:[1,0]
	v_pk_mul_f32 v[34:35], v[34:35], v[46:47]
	v_pk_mul_f32 v[32:33], v[32:33], v[44:45]
	v_and_b32_sdwa v19, v34, v170 dst_sel:DWORD dst_unused:UNUSED_PAD src0_sel:WORD_1 src1_sel:DWORD
	v_and_b32_sdwa v45, v35, v170 dst_sel:DWORD dst_unused:UNUSED_PAD src0_sel:WORD_1 src1_sel:DWORD
	v_and_b32_sdwa v46, v33, v170 dst_sel:DWORD dst_unused:UNUSED_PAD src0_sel:WORD_1 src1_sel:DWORD
	v_and_b32_sdwa v44, v32, v170 dst_sel:DWORD dst_unused:UNUSED_PAD src0_sel:WORD_1 src1_sel:DWORD
	v_add3_u32 v19, v34, v19, s56
	v_add3_u32 v34, v35, v45, s56
	v_add3_u32 v33, v33, v46, s56
	v_add3_u32 v32, v32, v44, s56
	v_and_b32_e32 v34, 0xffff0000, v34
	v_and_b32_e32 v35, 0xffff0000, v33
	v_or_b32_sdwa v33, v34, v19 dst_sel:DWORD dst_unused:UNUSED_PAD src0_sel:DWORD src1_sel:WORD_1
	v_or_b32_sdwa v32, v35, v32 dst_sel:DWORD dst_unused:UNUSED_PAD src0_sel:DWORD src1_sel:WORD_1
	global_store_dwordx2 v[56:57], v[32:33], off offset:64
	s_nop 0
	v_pk_fma_f32 v[34:35], v[42:43], v[138:139], v[208:209]
	v_pk_fma_f32 v[32:33], v[40:41], v[136:137], v[206:207]
	global_store_dwordx4 v[50:51], v[32:35], off offset:192
	v_mul_f32_e32 v14, v21, v21
	v_mul_f32_e32 v15, v25, v25
	v_fmac_f32_e32 v14, v20, v20
	v_fmac_f32_e32 v15, v24, v24
	v_fmac_f32_e32 v14, v22, v22
	v_fmac_f32_e32 v15, v26, v26
	v_fmac_f32_e32 v14, v23, v23
	v_fmac_f32_e32 v15, v27, v27
	v_add_f32_e32 v14, v14, v15
	v_mul_f32_e32 v15, v29, v29
	v_fmac_f32_e32 v15, v28, v28
	v_fmac_f32_e32 v15, v30, v30
	v_fmac_f32_e32 v15, v31, v31
	v_add_f32_e32 v14, v14, v15
	v_mul_f32_e32 v15, v33, v33
	v_fmac_f32_e32 v15, v32, v32
	v_fmac_f32_e32 v15, v34, v34
	v_fmac_f32_e32 v15, v35, v35
	v_add_f32_e32 v14, v14, v15
	ds_bpermute_b32 v15, v105, v14
	s_waitcnt lgkmcnt(0)
	v_add_f32_e32 v14, v14, v15
	ds_bpermute_b32 v15, v104, v14
	v_pk_mul_f32 v[20:21], v[34:35], v[154:155]
	v_pk_mul_f32 v[22:23], v[32:33], v[152:153]
	v_pk_add_f32 v[24:25], v[192:193], 1.0 op_sel_hi:[1,0]
	v_pk_add_f32 v[26:27], v[190:191], 1.0 op_sel_hi:[1,0]
	v_pk_mul_f32 v[20:21], v[20:21], v[24:25]
	v_pk_mul_f32 v[22:23], v[22:23], v[26:27]
	v_and_b32_sdwa v19, v20, v170 dst_sel:DWORD dst_unused:UNUSED_PAD src0_sel:WORD_1 src1_sel:DWORD
	v_and_b32_sdwa v25, v21, v170 dst_sel:DWORD dst_unused:UNUSED_PAD src0_sel:WORD_1 src1_sel:DWORD
	v_and_b32_sdwa v26, v23, v170 dst_sel:DWORD dst_unused:UNUSED_PAD src0_sel:WORD_1 src1_sel:DWORD
	v_and_b32_sdwa v24, v22, v170 dst_sel:DWORD dst_unused:UNUSED_PAD src0_sel:WORD_1 src1_sel:DWORD
	v_add3_u32 v19, v20, v19, s56
	v_add3_u32 v20, v21, v25, s56
	v_add3_u32 v21, v23, v26, s56
	v_add3_u32 v22, v22, v24, s56
	v_and_b32_e32 v20, 0xffff0000, v20
	v_and_b32_e32 v23, 0xffff0000, v21
	v_or_b32_sdwa v21, v20, v19 dst_sel:DWORD dst_unused:UNUSED_PAD src0_sel:DWORD src1_sel:WORD_1
	v_or_b32_sdwa v20, v23, v22 dst_sel:DWORD dst_unused:UNUSED_PAD src0_sel:DWORD src1_sel:WORD_1
	global_store_dwordx2 v[56:57], v[20:21], off offset:96
	s_and_saveexec_b64 s[2:3], vcc
	s_cbranch_execz .LBB0_612
	v_readlane_b32 s16, v253, 20
	s_add_u32 s24, s26, s16
	s_addc_u32 s25, s27, 0
	v_lshl_add_u64 v[20:21], v[12:13], 2, s[24:25]
	s_waitcnt lgkmcnt(0)
	v_add_f32_e32 v13, v14, v15
	global_store_dword v[20:21], v13, off

.LBB0_628:
	s_add_i32 s3, s24, 2
	v_add_u32_e32 v227, v144, v145
	ds_read_b128 v[36:39], v227 offset:16384
	ds_read_b128 v[40:43], v227 offset:18432
	ds_read_b128 v[44:47], v227 offset:20480
	ds_read_b128 v[48:51], v227 offset:22528
	v_add_u32_e32 v226, v143, v145
	ds_read_b128 v[16:19], v226
	v_add_u32_e32 v232, v144, v146
	s_add_i32 s24, s24, 4
	ds_read_b128 v[20:23], v226 offset:2048
	ds_read_b128 v[216:219], v232 offset:20480
	s_min_u32 s24, s24, 15
	s_lshl_b32 s92, s24, 7
	ds_read_b128 v[28:31], v226 offset:4096
	ds_read_b128 v[32:35], v226 offset:6144
	v_add_u32_e32 v228, v143, v146
	v_lshl_add_u64 v[224:225], v[138:139], 0, s[92:93]
	ds_read_b128 v[192:195], v228
	ds_read_b128 v[196:199], v228 offset:2048
	ds_read_b128 v[200:203], v228 offset:4096
	ds_read_b128 v[204:207], v228 offset:6144
	ds_read_b128 v[208:211], v232 offset:16384
	ds_read_b128 v[212:215], v232 offset:18432
	ds_read_b128 v[220:223], v232 offset:22528
	s_waitcnt lgkmcnt(11)
	v_mfma_f32_16x16x32_bf16 v[92:95], v[36:39], v[16:19], v[92:95]
	v_mfma_f32_16x16x32_bf16 v[88:91], v[40:43], v[16:19], v[88:91]
	v_mfma_f32_16x16x32_bf16 v[84:87], v[44:47], v[16:19], v[84:87]
	v_mfma_f32_16x16x32_bf16 v[16:19], v[48:51], v[16:19], v[80:83]
	s_nop 2
	global_load_dwordx4 v[80:83], v[224:225], off
	s_waitcnt vmcnt(6)
	ds_write_b128 v156, v[96:99] offset:32768
	v_add_co_u32_e32 v96, vcc, s11, v224
	s_waitcnt lgkmcnt(11)
	v_mfma_f32_16x16x32_bf16 v[76:79], v[36:39], v[20:23], v[76:79]
	v_addc_co_u32_e32 v97, vcc, 0, v225, vcc
	v_mfma_f32_16x16x32_bf16 v[72:75], v[40:43], v[20:23], v[72:75]
	v_mfma_f32_16x16x32_bf16 v[68:71], v[44:47], v[20:23], v[68:71]
	v_mfma_f32_16x16x32_bf16 v[20:23], v[48:51], v[20:23], v[64:67]
	s_nop 2
	global_load_dwordx4 v[64:67], v[96:97], off
	v_add_co_u32_e32 v96, vcc, s33, v224
	ds_write_b128 v156, v[100:103] offset:36864
	s_nop 0
	v_addc_co_u32_e32 v97, vcc, 0, v225, vcc
	s_waitcnt lgkmcnt(10)
	v_mfma_f32_16x16x32_bf16 v[60:63], v[36:39], v[28:31], v[60:63]
	v_mfma_f32_16x16x32_bf16 v[56:59], v[40:43], v[28:31], v[56:59]
	v_mfma_f32_16x16x32_bf16 v[52:55], v[44:47], v[28:31], v[52:55]
	v_mfma_f32_16x16x32_bf16 v[24:27], v[48:51], v[28:31], v[24:27]
	global_load_dwordx4 v[28:31], v[96:97], off
	ds_write_b128 v156, v[104:107] offset:40960
	s_waitcnt lgkmcnt(10)
	v_mfma_f32_16x16x32_bf16 v[12:15], v[36:39], v[32:35], v[12:15]
	v_add_co_u32_e32 v36, vcc, s59, v224
	s_nop 1
	v_addc_co_u32_e32 v37, vcc, 0, v225, vcc
	v_mfma_f32_16x16x32_bf16 v[8:11], v[40:43], v[32:35], v[8:11]
	v_mfma_f32_16x16x32_bf16 v[4:7], v[44:47], v[32:35], v[4:7]
	v_mfma_f32_16x16x32_bf16 v[0:3], v[48:51], v[32:35], v[0:3]
	global_load_dwordx4 v[32:35], v[36:37], off
	s_waitcnt vmcnt(7)
	ds_write_b128 v156, v[112:115] offset:45056
	s_waitcnt lgkmcnt(10)
	v_mfma_f32_16x16x32_bf16 v[44:47], v[216:219], v[192:195], v[84:87]
	s_nop 2
	v_lshl_add_u64 v[84:85], v[140:141], 0, s[92:93]
	v_add_co_u32_e32 v86, vcc, s11, v84
	s_waitcnt lgkmcnt(6)
	v_mfma_f32_16x16x32_bf16 v[36:39], v[208:211], v[192:195], v[92:95]
	v_addc_co_u32_e32 v87, vcc, 0, v85, vcc
	s_waitcnt lgkmcnt(5)
	v_mfma_f32_16x16x32_bf16 v[40:43], v[212:215], v[192:195], v[88:91]
	s_waitcnt lgkmcnt(4)
	v_mfma_f32_16x16x32_bf16 v[16:19], v[220:223], v[192:195], v[16:19]
	global_load_dwordx4 v[48:51], v[84:85], off
	ds_write_b128 v156, v[108:111] offset:49152
	v_mfma_f32_16x16x32_bf16 v[76:79], v[208:211], v[196:199], v[76:79]
	v_mfma_f32_16x16x32_bf16 v[72:75], v[212:215], v[196:199], v[72:75]
	v_mfma_f32_16x16x32_bf16 v[68:71], v[216:219], v[196:199], v[68:71]
	v_mfma_f32_16x16x32_bf16 v[20:23], v[220:223], v[196:199], v[20:23]
	global_load_dwordx4 v[192:195], v[86:87], off
	v_add_co_u32_e32 v86, vcc, s33, v84
	s_waitcnt vmcnt(8)
	ds_write_b128 v156, v[116:119] offset:53248
	v_addc_co_u32_e32 v87, vcc, 0, v85, vcc
	v_add_co_u32_e32 v84, vcc, s59, v84
	v_mfma_f32_16x16x32_bf16 v[60:63], v[208:211], v[200:203], v[60:63]
	s_nop 0
	v_addc_co_u32_e32 v85, vcc, 0, v85, vcc
	v_mfma_f32_16x16x32_bf16 v[56:59], v[212:215], v[200:203], v[56:59]
	v_mfma_f32_16x16x32_bf16 v[52:55], v[216:219], v[200:203], v[52:55]
	v_mfma_f32_16x16x32_bf16 v[24:27], v[220:223], v[200:203], v[24:27]
	global_load_dwordx4 v[196:199], v[86:87], off
	s_waitcnt vmcnt(8)
	ds_write_b128 v156, v[120:123] offset:57344
	v_mfma_f32_16x16x32_bf16 v[12:15], v[208:211], v[204:207], v[12:15]
	v_mfma_f32_16x16x32_bf16 v[8:11], v[212:215], v[204:207], v[8:11]
	v_mfma_f32_16x16x32_bf16 v[4:7], v[216:219], v[204:207], v[4:7]
	v_mfma_f32_16x16x32_bf16 v[0:3], v[220:223], v[204:207], v[0:3]
	global_load_dwordx4 v[200:203], v[84:85], off
	s_waitcnt vmcnt(8)
	ds_write_b128 v156, v[124:127] offset:61440
	s_waitcnt lgkmcnt(0)
	s_barrier
	ds_read_b128 v[112:115], v227 offset:49152
	ds_read_b128 v[116:119], v227 offset:51200
	ds_read_b128 v[120:123], v227 offset:53248
	ds_read_b128 v[124:127], v227 offset:55296
	ds_read_b128 v[84:87], v226 offset:32768
	ds_read_b128 v[88:91], v226 offset:34816
	ds_read_b128 v[92:95], v226 offset:36864
	ds_read_b128 v[108:111], v226 offset:38912
	ds_read_b128 v[204:207], v228 offset:32768
	ds_read_b128 v[208:211], v228 offset:34816
	ds_read_b128 v[212:215], v228 offset:36864
	ds_read_b128 v[216:219], v228 offset:38912
	ds_read_b128 v[220:223], v232 offset:49152
	ds_read_b128 v[224:227], v232 offset:51200
	ds_read_b128 v[228:231], v232 offset:53248
	ds_read_b128 v[232:235], v232 offset:55296
	s_min_u32 s24, s3, 12
	s_lshl_b32 s92, s24, 7
	s_waitcnt lgkmcnt(11)
	v_mfma_f32_16x16x32_bf16 v[36:39], v[112:115], v[84:87], v[36:39]
	v_mfma_f32_16x16x32_bf16 v[40:43], v[116:119], v[84:87], v[40:43]
	v_mfma_f32_16x16x32_bf16 v[44:47], v[120:123], v[84:87], v[44:47]
	v_mfma_f32_16x16x32_bf16 v[16:19], v[124:127], v[84:87], v[16:19]
	v_lshl_add_u64 v[84:85], v[138:139], 0, s[92:93]
	global_load_dwordx4 v[96:99], v[84:85], off offset:384
	s_waitcnt vmcnt(8)
	ds_write_b128 v156, v[80:83]
	v_add_co_u32_e32 v80, vcc, s11, v84
	s_waitcnt lgkmcnt(11)
	v_mfma_f32_16x16x32_bf16 v[76:79], v[112:115], v[88:91], v[76:79]
	v_addc_co_u32_e32 v81, vcc, 0, v85, vcc
	v_mfma_f32_16x16x32_bf16 v[72:75], v[116:119], v[88:91], v[72:75]
	v_mfma_f32_16x16x32_bf16 v[68:71], v[120:123], v[88:91], v[68:71]
	v_mfma_f32_16x16x32_bf16 v[20:23], v[124:127], v[88:91], v[20:23]
	global_load_dwordx4 v[100:103], v[80:81], off offset:384
	s_waitcnt vmcnt(8)
	ds_write_b128 v156, v[64:67] offset:4096
	v_add_co_u32_e32 v64, vcc, s33, v84
	s_waitcnt lgkmcnt(11)
	v_mfma_f32_16x16x32_bf16 v[60:63], v[112:115], v[92:95], v[60:63]
	v_addc_co_u32_e32 v65, vcc, 0, v85, vcc
	v_mfma_f32_16x16x32_bf16 v[56:59], v[116:119], v[92:95], v[56:59]
	v_mfma_f32_16x16x32_bf16 v[52:55], v[120:123], v[92:95], v[52:55]
	v_mfma_f32_16x16x32_bf16 v[24:27], v[124:127], v[92:95], v[24:27]
	global_load_dwordx4 v[104:107], v[64:65], off offset:384
	s_waitcnt vmcnt(8)
	ds_write_b128 v156, v[28:31] offset:8192
	v_add_co_u32_e32 v28, vcc, s59, v84
	s_waitcnt lgkmcnt(11)
	v_mfma_f32_16x16x32_bf16 v[12:15], v[112:115], v[108:111], v[12:15]
	v_addc_co_u32_e32 v29, vcc, 0, v85, vcc
	v_mfma_f32_16x16x32_bf16 v[8:11], v[116:119], v[108:111], v[8:11]
	v_mfma_f32_16x16x32_bf16 v[4:7], v[120:123], v[108:111], v[4:7]
	v_mfma_f32_16x16x32_bf16 v[0:3], v[124:127], v[108:111], v[0:3]
	global_load_dwordx4 v[112:115], v[28:29], off offset:384
	s_waitcnt vmcnt(8)
	ds_write_b128 v156, v[32:35] offset:12288
	s_waitcnt lgkmcnt(4)
	v_mfma_f32_16x16x32_bf16 v[80:83], v[232:235], v[204:207], v[16:19]
	s_nop 2
	v_lshl_add_u64 v[16:17], v[140:141], 0, s[92:93]
	v_add_co_u32_e32 v18, vcc, s11, v16
	v_mfma_f32_16x16x32_bf16 v[92:95], v[220:223], v[204:207], v[36:39]
	s_nop 0
	v_addc_co_u32_e32 v19, vcc, 0, v17, vcc
	v_mfma_f32_16x16x32_bf16 v[88:91], v[224:227], v[204:207], v[40:43]
	v_mfma_f32_16x16x32_bf16 v[84:87], v[228:231], v[204:207], v[44:47]
	global_load_dwordx4 v[108:111], v[16:17], off offset:384
	s_waitcnt vmcnt(8)
	ds_write_b128 v156, v[48:51] offset:16384
	v_mfma_f32_16x16x32_bf16 v[76:79], v[220:223], v[208:211], v[76:79]
	v_mfma_f32_16x16x32_bf16 v[72:75], v[224:227], v[208:211], v[72:75]
	v_mfma_f32_16x16x32_bf16 v[68:71], v[228:231], v[208:211], v[68:71]
	v_mfma_f32_16x16x32_bf16 v[64:67], v[232:235], v[208:211], v[20:23]
	global_load_dwordx4 v[116:119], v[18:19], off offset:384
	v_add_co_u32_e32 v18, vcc, s33, v16
	s_waitcnt vmcnt(8)
	ds_write_b128 v156, v[192:195] offset:20480
	v_addc_co_u32_e32 v19, vcc, 0, v17, vcc
	v_add_co_u32_e32 v16, vcc, s59, v16
	v_mfma_f32_16x16x32_bf16 v[60:63], v[220:223], v[212:215], v[60:63]
	s_nop 0
	v_addc_co_u32_e32 v17, vcc, 0, v17, vcc
	v_mfma_f32_16x16x32_bf16 v[56:59], v[224:227], v[212:215], v[56:59]
	v_mfma_f32_16x16x32_bf16 v[52:55], v[228:231], v[212:215], v[52:55]
	v_mfma_f32_16x16x32_bf16 v[24:27], v[232:235], v[212:215], v[24:27]
	global_load_dwordx4 v[120:123], v[18:19], off offset:384
	s_waitcnt vmcnt(8)
	ds_write_b128 v156, v[196:199] offset:24576
	v_mfma_f32_16x16x32_bf16 v[12:15], v[220:223], v[216:219], v[12:15]
	v_mfma_f32_16x16x32_bf16 v[8:11], v[224:227], v[216:219], v[8:11]
	v_mfma_f32_16x16x32_bf16 v[4:7], v[228:231], v[216:219], v[4:7]
	v_mfma_f32_16x16x32_bf16 v[0:3], v[232:235], v[216:219], v[0:3]
	global_load_dwordx4 v[124:127], v[16:17], off offset:384
	s_waitcnt vmcnt(8)
	ds_write_b128 v156, v[200:203] offset:28672
	s_cmp_gt_u32 s3, 13
	s_mov_b32 s24, s3
	s_waitcnt lgkmcnt(0)
	s_barrier
	s_cbranch_scc0 .LBB0_628
	s_and_saveexec_b64 s[24:25], s[36:37]
	s_cbranch_execz .LBB0_631
	v_add_f32_e32 v16, 0, v128
	v_add_f32_e32 v16, v16, v157
	v_add_f32_e32 v16, v16, v158
	v_add_f32_e32 v16, v16, v159
	v_add_f32_e32 v16, v16, v160
	v_add_f32_e32 v16, v16, v161
	v_add_f32_e32 v16, v16, v162
	v_add_f32_e32 v16, v16, v163
	v_add_f32_e32 v16, v16, v164
	v_add_f32_e32 v16, v16, v165
	v_add_f32_e32 v16, v16, v168
	v_add_f32_e32 v16, v16, v175
	v_add_f32_e32 v16, v16, v179
	v_add_f32_e32 v16, v16, v183
	v_add_f32_e32 v16, v16, v190
	v_add_f32_e32 v16, v16, v191
	v_fmamk_f32 v16, v16, 0x3a800000, v167
	s_mov_b32 s3, 0x800000
	v_mul_f32_e32 v17, 0x4b800000, v16
	v_cmp_gt_f32_e32 vcc, s3, v16
	s_nop 1
	v_cndmask_b32_e32 v16, v16, v17, vcc
	v_rsq_f32_e32 v16, v16
	s_nop 0
	v_mul_f32_e32 v17, 0x45800000, v16
	v_cndmask_b32_e32 v16, v16, v17, vcc
	ds_write_b32 v155, v16

.LBB0_666:
	s_add_i32 s2, s3, 2
	v_add_u32_e32 v123, v111, v126
	ds_read_b128 v[154:157], v123 offset:16384
	ds_read_b128 v[158:161], v123 offset:18432
	ds_read_b128 v[162:165], v123 offset:20480
	ds_read_b128 v[190:193], v123 offset:22528
	v_add_u32_e32 v122, v110, v126
	ds_read_b128 v[138:141], v122
	ds_read_b128 v[142:145], v122 offset:2048
	v_add_u32_e32 v125, v111, v137
	s_add_i32 s3, s3, 4
	ds_read_b128 v[146:149], v122 offset:4096
	ds_read_b128 v[214:217], v125 offset:18432
	s_min_u32 s3, s3, 15
	ds_read_b128 v[210:213], v125 offset:16384
	ds_read_b128 v[218:221], v125 offset:20480
	ds_read_b128 v[222:225], v125 offset:22528
	s_lshl_b32 s92, s3, 7
	v_add_u32_e32 v124, v110, v137
	v_lshl_add_u64 v[226:227], v[102:103], 0, s[92:93]
	ds_read_b128 v[150:153], v122 offset:6144
	ds_read_b128 v[194:197], v124
	ds_read_b128 v[198:201], v124 offset:2048
	ds_read_b128 v[202:205], v124 offset:4096
	ds_read_b128 v[206:209], v124 offset:6144
	s_waitcnt lgkmcnt(11)
	v_mfma_f32_16x16x32_bf16 v[92:95], v[154:157], v[138:141], v[92:95]
	v_mfma_f32_16x16x32_bf16 v[88:91], v[158:161], v[138:141], v[88:91]
	v_mfma_f32_16x16x32_bf16 v[84:87], v[162:165], v[138:141], v[84:87]
	v_mfma_f32_16x16x32_bf16 v[80:83], v[190:193], v[138:141], v[80:83]
	global_load_dwordx4 v[138:141], v[226:227], off
	s_waitcnt vmcnt(6)
	ds_write_b128 v121, v[28:31] offset:32768
	s_waitcnt lgkmcnt(11)
	v_mfma_f32_16x16x32_bf16 v[28:31], v[154:157], v[142:145], v[76:79]
	s_nop 2
	v_add_co_u32_e32 v76, vcc, s11, v226
	v_mfma_f32_16x16x32_bf16 v[72:75], v[158:161], v[142:145], v[72:75]
	s_nop 0
	v_addc_co_u32_e32 v77, vcc, 0, v227, vcc
	v_mfma_f32_16x16x32_bf16 v[68:71], v[162:165], v[142:145], v[68:71]
	v_mfma_f32_16x16x32_bf16 v[64:67], v[190:193], v[142:145], v[64:67]
	global_load_dwordx4 v[76:79], v[76:77], off
	ds_write_b128 v121, v[32:35] offset:36864
	s_waitcnt lgkmcnt(11)
	v_mfma_f32_16x16x32_bf16 v[32:35], v[154:157], v[146:149], v[48:51]
	s_nop 2
	v_add_co_u32_e32 v48, vcc, s33, v226
	v_mfma_f32_16x16x32_bf16 v[24:27], v[158:161], v[146:149], v[24:27]
	s_nop 0
	v_addc_co_u32_e32 v49, vcc, 0, v227, vcc
	v_mfma_f32_16x16x32_bf16 v[20:23], v[162:165], v[146:149], v[20:23]
	v_mfma_f32_16x16x32_bf16 v[16:19], v[190:193], v[146:149], v[16:19]
	global_load_dwordx4 v[48:51], v[48:49], off
	ds_write_b128 v121, v[36:39] offset:40960
	v_add_co_u32_e32 v36, vcc, s59, v226
	s_waitcnt lgkmcnt(7)
	v_mfma_f32_16x16x32_bf16 v[12:15], v[154:157], v[150:153], v[12:15]
	v_addc_co_u32_e32 v37, vcc, 0, v227, vcc
	v_mfma_f32_16x16x32_bf16 v[8:11], v[158:161], v[150:153], v[8:11]
	v_mfma_f32_16x16x32_bf16 v[4:7], v[162:165], v[150:153], v[4:7]
	v_mfma_f32_16x16x32_bf16 v[0:3], v[190:193], v[150:153], v[0:3]
	global_load_dwordx4 v[142:145], v[36:37], off
	s_waitcnt vmcnt(7)
	ds_write_b128 v121, v[44:47] offset:45056
	s_waitcnt lgkmcnt(7)
	v_mfma_f32_16x16x32_bf16 v[44:47], v[214:217], v[194:197], v[88:91]
	s_nop 2
	v_lshl_add_u64 v[88:89], v[104:105], 0, s[92:93]
	v_mfma_f32_16x16x32_bf16 v[36:39], v[210:213], v[194:197], v[92:95]
	v_mfma_f32_16x16x32_bf16 v[84:87], v[218:221], v[194:197], v[84:87]
	v_mfma_f32_16x16x32_bf16 v[80:83], v[222:225], v[194:197], v[80:83]
	global_load_dwordx4 v[146:149], v[88:89], off
	ds_write_b128 v121, v[40:43] offset:49152
	s_waitcnt lgkmcnt(7)
	v_mfma_f32_16x16x32_bf16 v[40:43], v[210:213], v[198:201], v[28:31]
	s_nop 2
	v_add_co_u32_e32 v28, vcc, s11, v88
	v_mfma_f32_16x16x32_bf16 v[72:75], v[214:217], v[198:201], v[72:75]
	s_nop 0
	v_addc_co_u32_e32 v29, vcc, 0, v89, vcc
	v_mfma_f32_16x16x32_bf16 v[68:71], v[218:221], v[198:201], v[68:71]
	v_mfma_f32_16x16x32_bf16 v[64:67], v[222:225], v[198:201], v[64:67]
	global_load_dwordx4 v[150:153], v[28:29], off
	v_add_co_u32_e32 v28, vcc, s33, v88
	s_waitcnt vmcnt(8)
	ds_write_b128 v121, v[52:55] offset:53248
	v_addc_co_u32_e32 v29, vcc, 0, v89, vcc
	s_waitcnt lgkmcnt(7)
	v_mfma_f32_16x16x32_bf16 v[52:55], v[210:213], v[202:205], v[32:35]
	v_mfma_f32_16x16x32_bf16 v[24:27], v[214:217], v[202:205], v[24:27]
	v_mfma_f32_16x16x32_bf16 v[20:23], v[218:221], v[202:205], v[20:23]
	v_mfma_f32_16x16x32_bf16 v[16:19], v[222:225], v[202:205], v[16:19]
	global_load_dwordx4 v[154:157], v[28:29], off
	v_add_co_u32_e32 v28, vcc, s59, v88
	s_waitcnt vmcnt(8)
	ds_write_b128 v121, v[56:59] offset:57344
	v_addc_co_u32_e32 v29, vcc, 0, v89, vcc
	s_waitcnt lgkmcnt(7)
	v_mfma_f32_16x16x32_bf16 v[12:15], v[210:213], v[206:209], v[12:15]
	v_mfma_f32_16x16x32_bf16 v[8:11], v[214:217], v[206:209], v[8:11]
	v_mfma_f32_16x16x32_bf16 v[4:7], v[218:221], v[206:209], v[4:7]
	v_mfma_f32_16x16x32_bf16 v[0:3], v[222:225], v[206:209], v[0:3]
	global_load_dwordx4 v[158:161], v[28:29], off
	s_waitcnt vmcnt(8)
	ds_write_b128 v121, v[60:63] offset:61440
	s_waitcnt lgkmcnt(0)
	s_barrier
	ds_read_b128 v[92:95], v123 offset:51200
	ds_read_b128 v[88:91], v123 offset:49152
	ds_read_b128 v[162:165], v123 offset:53248
	ds_read_b128 v[190:193], v123 offset:55296
	ds_read_b128 v[28:31], v122 offset:32768
	ds_read_b128 v[32:35], v122 offset:34816
	s_min_u32 s3, s2, 12
	s_lshl_b32 s92, s3, 7
	ds_read_b128 v[56:59], v122 offset:36864
	ds_read_b128 v[60:63], v122 offset:38912
	ds_read_b128 v[194:197], v124 offset:32768
	ds_read_b128 v[198:201], v124 offset:34816
	ds_read_b128 v[202:205], v124 offset:36864
	ds_read_b128 v[206:209], v124 offset:38912
	ds_read_b128 v[210:213], v125 offset:49152
	ds_read_b128 v[214:217], v125 offset:51200
	ds_read_b128 v[218:221], v125 offset:53248
	ds_read_b128 v[222:225], v125 offset:55296
	s_waitcnt lgkmcnt(11)
	v_mfma_f32_16x16x32_bf16 v[230:233], v[92:95], v[28:31], v[44:47]
	v_mfma_f32_16x16x32_bf16 v[226:229], v[88:91], v[28:31], v[36:39]
	s_nop 1
	v_lshl_add_u64 v[44:45], v[102:103], 0, s[92:93]
	v_add_co_u32_e32 v36, vcc, s11, v44
	v_mfma_f32_16x16x32_bf16 v[84:87], v[162:165], v[28:31], v[84:87]
	s_nop 0
	v_addc_co_u32_e32 v37, vcc, 0, v45, vcc
	v_mfma_f32_16x16x32_bf16 v[80:83], v[190:193], v[28:31], v[80:83]
	global_load_dwordx4 v[28:31], v[44:45], off offset:384
	s_waitcnt vmcnt(8)
	ds_write_b128 v121, v[138:141]
	s_waitcnt lgkmcnt(11)
	v_mfma_f32_16x16x32_bf16 v[138:141], v[88:91], v[32:35], v[40:43]
	v_mfma_f32_16x16x32_bf16 v[72:75], v[92:95], v[32:35], v[72:75]
	v_mfma_f32_16x16x32_bf16 v[68:71], v[162:165], v[32:35], v[68:71]
	v_mfma_f32_16x16x32_bf16 v[64:67], v[190:193], v[32:35], v[64:67]
	global_load_dwordx4 v[32:35], v[36:37], off offset:384
	v_add_co_u32_e32 v36, vcc, s33, v44
	s_waitcnt vmcnt(8)
	ds_write_b128 v121, v[76:79] offset:4096
	v_addc_co_u32_e32 v37, vcc, 0, v45, vcc
	v_add_co_u32_e32 v40, vcc, s59, v44
	s_waitcnt lgkmcnt(11)
	v_mfma_f32_16x16x32_bf16 v[234:237], v[88:91], v[56:59], v[52:55]
	v_addc_co_u32_e32 v41, vcc, 0, v45, vcc
	v_mfma_f32_16x16x32_bf16 v[24:27], v[92:95], v[56:59], v[24:27]
	v_mfma_f32_16x16x32_bf16 v[20:23], v[162:165], v[56:59], v[20:23]
	v_mfma_f32_16x16x32_bf16 v[16:19], v[190:193], v[56:59], v[16:19]
	global_load_dwordx4 v[36:39], v[36:37], off offset:384
	s_waitcnt vmcnt(8)
	ds_write_b128 v121, v[48:51] offset:8192
	s_waitcnt lgkmcnt(11)
	v_mfma_f32_16x16x32_bf16 v[12:15], v[88:91], v[60:63], v[12:15]
	v_mfma_f32_16x16x32_bf16 v[8:11], v[92:95], v[60:63], v[8:11]
	v_mfma_f32_16x16x32_bf16 v[4:7], v[162:165], v[60:63], v[4:7]
	v_mfma_f32_16x16x32_bf16 v[0:3], v[190:193], v[60:63], v[0:3]
	v_lshl_add_u64 v[60:61], v[104:105], 0, s[92:93]
	v_add_co_u32_e32 v48, vcc, s11, v60
	global_load_dwordx4 v[44:47], v[40:41], off offset:384
	s_nop 0
	v_addc_co_u32_e32 v49, vcc, 0, v61, vcc
	v_add_co_u32_e32 v56, vcc, s33, v60
	s_waitcnt vmcnt(8)
	ds_write_b128 v121, v[142:145] offset:12288
	v_addc_co_u32_e32 v57, vcc, 0, v61, vcc
	s_waitcnt lgkmcnt(7)
	v_mfma_f32_16x16x32_bf16 v[92:95], v[210:213], v[194:197], v[226:229]
	s_waitcnt lgkmcnt(6)
	v_mfma_f32_16x16x32_bf16 v[88:91], v[214:217], v[194:197], v[230:233]
	s_waitcnt lgkmcnt(5)
	v_mfma_f32_16x16x32_bf16 v[84:87], v[218:221], v[194:197], v[84:87]
	s_waitcnt lgkmcnt(4)
	v_mfma_f32_16x16x32_bf16 v[80:83], v[222:225], v[194:197], v[80:83]
	global_load_dwordx4 v[40:43], v[60:61], off offset:384
	v_add_co_u32_e32 v60, vcc, s59, v60
	s_waitcnt vmcnt(8)
	ds_write_b128 v121, v[146:149] offset:16384
	v_addc_co_u32_e32 v61, vcc, 0, v61, vcc
	v_mfma_f32_16x16x32_bf16 v[76:79], v[210:213], v[198:201], v[138:141]
	v_mfma_f32_16x16x32_bf16 v[72:75], v[214:217], v[198:201], v[72:75]
	v_mfma_f32_16x16x32_bf16 v[68:71], v[218:221], v[198:201], v[68:71]
	v_mfma_f32_16x16x32_bf16 v[64:67], v[222:225], v[198:201], v[64:67]
	global_load_dwordx4 v[52:55], v[48:49], off offset:384
	s_waitcnt vmcnt(8)
	ds_write_b128 v121, v[150:153] offset:20480
	v_mfma_f32_16x16x32_bf16 v[48:51], v[210:213], v[202:205], v[234:237]
	v_mfma_f32_16x16x32_bf16 v[24:27], v[214:217], v[202:205], v[24:27]
	v_mfma_f32_16x16x32_bf16 v[20:23], v[218:221], v[202:205], v[20:23]
	v_mfma_f32_16x16x32_bf16 v[16:19], v[222:225], v[202:205], v[16:19]
	global_load_dwordx4 v[56:59], v[56:57], off offset:384
	s_waitcnt vmcnt(8)
	ds_write_b128 v121, v[154:157] offset:24576
	v_mfma_f32_16x16x32_bf16 v[12:15], v[210:213], v[206:209], v[12:15]
	v_mfma_f32_16x16x32_bf16 v[8:11], v[214:217], v[206:209], v[8:11]
	v_mfma_f32_16x16x32_bf16 v[4:7], v[218:221], v[206:209], v[4:7]
	v_mfma_f32_16x16x32_bf16 v[0:3], v[222:225], v[206:209], v[0:3]
	global_load_dwordx4 v[60:63], v[60:61], off offset:384
	s_waitcnt vmcnt(8)
	ds_write_b128 v121, v[158:161] offset:28672
	s_cmp_gt_u32 s2, 13
	s_mov_b32 s3, s2
	s_waitcnt lgkmcnt(0)
	s_barrier
	s_cbranch_scc0 .LBB0_666
	s_movk_i32 s2, 0x80
	v_cmp_gt_i32_e64 s[36:37], s2, v109
	s_add_i32 s2, 0, 0x10000
	v_lshl_add_u32 v126, v109, 2, s2
	s_and_saveexec_b64 s[2:3], s[36:37]
	v_readlane_b32 s16, v251, 44
	v_readlane_b32 s17, v251, 45
	s_cbranch_execz .LBB0_669
	s_waitcnt vmcnt(7)
	v_add_f32_e32 v28, 0, v112
	v_add_f32_e32 v28, v28, v113
	v_add_f32_e32 v28, v28, v114
	v_add_f32_e32 v28, v28, v115
	v_add_f32_e32 v28, v28, v116
	v_add_f32_e32 v28, v28, v117
	v_add_f32_e32 v28, v28, v118
	v_add_f32_e32 v28, v28, v119
	v_add_f32_e32 v28, v28, v127
	v_add_f32_e32 v28, v28, v128
	v_add_f32_e32 v28, v28, v130
	v_add_f32_e32 v28, v28, v132
	v_add_f32_e32 v28, v28, v133
	v_add_f32_e32 v28, v28, v134
	v_add_f32_e32 v28, v28, v135
	v_add_f32_e32 v28, v28, v136
	v_fmamk_f32 v28, v28, 0x3a800000, v167
	s_mov_b32 s21, 0x800000
	v_mul_f32_e32 v29, 0x4b800000, v28
	v_cmp_gt_f32_e32 vcc, s21, v28
	s_nop 1
	v_cndmask_b32_e32 v28, v28, v29, vcc
	v_rsq_f32_e32 v28, v28
	s_nop 0
	v_mul_f32_e32 v29, 0x45800000, v28
	v_cndmask_b32_e32 v28, v28, v29, vcc
	ds_write_b32 v126, v28
